# GEMM K loops: first MFMA of every MMA phase pinned to a 64-byte boundary with s_nop pads in front of the load phase's closing waits (64 sites)
# baseline (speedup 1.0000x reference)
.LBB0_298:
	s_lshl_b64 s[4:5], s[20:21], 17
	s_add_u32 s24, s2, s4
	s_addc_u32 s25, s19, s5
	s_and_b64 s[4:5], s[36:37], exec
	s_cselect_b32 s37, s25, s31
	s_cselect_b32 s36, s24, s30
	s_add_u32 s56, s30, 0x100
	s_addc_u32 s57, s31, 0
	s_add_u32 s80, s34, 0x100
	s_addc_u32 s81, s35, 0
	s_add_u32 s38, s30, 0x180
	s_addc_u32 s39, s31, 0
	s_add_i32 s4, 0, 0x10000
	s_add_i32 s17, 0, 0x14000
	v_add_u32_e32 v128, s4, v134
	v_add_u32_e32 v129, s17, v134
	ds_read_b128 v[0:3], v128
	ds_read_b128 v[4:7], v128 offset:1024
	ds_read_b128 v[8:11], v128 offset:2048
	ds_read_b128 v[12:15], v128 offset:3072
	ds_read_b128 v[16:19], v129
	ds_read_b128 v[20:23], v129 offset:1024
	ds_read_b128 v[24:27], v129 offset:2048
	ds_read_b128 v[28:31], v129 offset:3072
	s_add_u32 s70, s30, 0x10080
	s_addc_u32 s71, s31, 0
	s_add_i32 s5, s13, 0xc000
	s_mov_b32 m0, s5
	s_add_i32 s15, s13, 0xe000
	ds_read_b128 v[32:35], v135
	ds_read_b128 v[36:39], v135 offset:1024
	ds_read_b128 v[40:43], v135 offset:2048
	ds_read_b128 v[44:47], v135 offset:3072
	ds_read_b128 v[48:51], v135 offset:4096
	ds_read_b128 v[52:55], v135 offset:5120
	ds_read_b128 v[56:59], v135 offset:6144
	ds_read_b128 v[60:63], v135 offset:7168
	s_nop 0
	global_load_lds_dwordx4 v130, s[70:71]
	s_mov_b32 m0, s15
	s_nop 0
	global_load_lds_dwordx4 v132, s[70:71]
	s_nop 0
	s_nop 0
	s_nop 0
	s_nop 0
	s_nop 0
	s_nop 0
	s_nop 0
	s_nop 0
	s_nop 0
	s_nop 0
	s_nop 0
	s_nop 0
	s_waitcnt vmcnt(8)
	s_waitcnt lgkmcnt(0)
	s_setprio 1
	s_barrier
	v_mfma_f32_16x16x32_bf16 v[64:67], v[0:3], v[32:35], 0
	v_mfma_f32_16x16x32_bf16 v[68:71], v[8:11], v[32:35], 0
	v_mfma_f32_16x16x32_bf16 v[72:75], v[0:3], v[40:43], 0
	v_mfma_f32_16x16x32_bf16 v[76:79], v[8:11], v[40:43], 0
	v_mfma_f32_16x16x32_bf16 v[80:83], v[0:3], v[48:51], 0
	v_mfma_f32_16x16x32_bf16 v[84:87], v[8:11], v[48:51], 0
	v_mfma_f32_16x16x32_bf16 v[88:91], v[0:3], v[56:59], 0
	v_mfma_f32_16x16x32_bf16 v[92:95], v[8:11], v[56:59], 0
	v_mfma_f32_16x16x32_bf16 v[64:67], v[4:7], v[36:39], v[64:67]
	v_mfma_f32_16x16x32_bf16 v[68:71], v[12:15], v[36:39], v[68:71]
	v_mfma_f32_16x16x32_bf16 v[72:75], v[4:7], v[44:47], v[72:75]
	v_mfma_f32_16x16x32_bf16 v[76:79], v[12:15], v[44:47], v[76:79]
	v_mfma_f32_16x16x32_bf16 v[80:83], v[4:7], v[52:55], v[80:83]
	v_mfma_f32_16x16x32_bf16 v[84:87], v[12:15], v[52:55], v[84:87]
	v_mfma_f32_16x16x32_bf16 v[88:91], v[4:7], v[60:63], v[88:91]
	v_mfma_f32_16x16x32_bf16 v[92:95], v[12:15], v[60:63], v[92:95]
	v_mfma_f32_16x16x32_bf16 v[96:99], v[16:19], v[32:35], 0
	v_mfma_f32_16x16x32_bf16 v[32:35], v[24:27], v[32:35], 0
	v_mfma_f32_16x16x32_bf16 v[96:99], v[20:23], v[36:39], v[96:99]
	v_mfma_f32_16x16x32_bf16 v[32:35], v[28:31], v[36:39], v[32:35]
	v_mfma_f32_16x16x32_bf16 v[36:39], v[16:19], v[40:43], 0
	v_mfma_f32_16x16x32_bf16 v[40:43], v[24:27], v[40:43], 0
	v_mfma_f32_16x16x32_bf16 v[36:39], v[20:23], v[44:47], v[36:39]
	v_mfma_f32_16x16x32_bf16 v[40:43], v[28:31], v[44:47], v[40:43]
	v_mfma_f32_16x16x32_bf16 v[44:47], v[16:19], v[48:51], 0
	v_mfma_f32_16x16x32_bf16 v[48:51], v[24:27], v[48:51], 0
	v_mfma_f32_16x16x32_bf16 v[44:47], v[20:23], v[52:55], v[44:47]
	v_mfma_f32_16x16x32_bf16 v[48:51], v[28:31], v[52:55], v[48:51]
	v_mfma_f32_16x16x32_bf16 v[52:55], v[16:19], v[56:59], 0
	v_mfma_f32_16x16x32_bf16 v[56:59], v[24:27], v[56:59], 0
	v_mfma_f32_16x16x32_bf16 v[52:55], v[20:23], v[60:63], v[52:55]
	v_mfma_f32_16x16x32_bf16 v[56:59], v[28:31], v[60:63], v[56:59]
	s_barrier
	s_setprio 0
	s_add_i32 s70, s4, s97
	s_add_i32 s4, s70, 0x2000
	s_mov_b32 m0, s70
	s_add_u32 s74, s34, 0x80100
	ds_read_b128 v[60:63], v135 offset:16384
	ds_read_b128 v[100:103], v135 offset:17408
	ds_read_b128 v[104:107], v135 offset:18432
	ds_read_b128 v[108:111], v135 offset:19456
	ds_read_b128 v[112:115], v135 offset:20480
	ds_read_b128 v[116:119], v135 offset:21504
	ds_read_b128 v[120:123], v135 offset:22528
	ds_read_b128 v[124:127], v135 offset:23552
	s_addc_u32 s75, s35, 0
	global_load_lds_dwordx4 v131, s[80:81]
	s_mov_b32 m0, s4
	s_add_i32 s17, s17, s97
	s_add_i32 s21, s17, 0x2000
	global_load_lds_dwordx4 v133, s[80:81]
	s_mov_b32 m0, s17
	s_nop 0
	global_load_lds_dwordx4 v131, s[74:75]
	s_mov_b32 m0, s21
	s_nop 0
	global_load_lds_dwordx4 v133, s[74:75]
	s_mov_b32 m0, s13
	s_nop 0
	global_load_lds_dwordx4 v130, s[56:57]
	s_mov_b32 m0, s27
	s_nop 0
	global_load_lds_dwordx4 v132, s[56:57]
	s_nop 0
	s_nop 0
	s_nop 0
	s_nop 0
	s_nop 0
	s_nop 0
	s_nop 0
	s_nop 0
	s_nop 0
	s_nop 0
	s_nop 0
	s_waitcnt vmcnt(8)
	s_waitcnt lgkmcnt(0)
	s_setprio 1
	s_barrier
	v_mfma_f32_16x16x32_bf16 v[136:139], v[0:3], v[60:63], 0
	v_mfma_f32_16x16x32_bf16 v[144:147], v[0:3], v[104:107], 0
	v_mfma_f32_16x16x32_bf16 v[152:155], v[0:3], v[112:115], 0
	v_mfma_f32_16x16x32_bf16 v[0:3], v[0:3], v[120:123], 0
	v_mfma_f32_16x16x32_bf16 v[136:139], v[4:7], v[100:103], v[136:139]
	v_mfma_f32_16x16x32_bf16 v[144:147], v[4:7], v[108:111], v[144:147]
	v_mfma_f32_16x16x32_bf16 v[152:155], v[4:7], v[116:119], v[152:155]
	v_mfma_f32_16x16x32_bf16 v[0:3], v[4:7], v[124:127], v[0:3]
	v_mfma_f32_16x16x32_bf16 v[4:7], v[8:11], v[120:123], 0
	v_mfma_f32_16x16x32_bf16 v[140:143], v[8:11], v[60:63], 0
	v_mfma_f32_16x16x32_bf16 v[148:151], v[8:11], v[104:107], 0
	v_mfma_f32_16x16x32_bf16 v[156:159], v[8:11], v[112:115], 0
	v_mfma_f32_16x16x32_bf16 v[4:7], v[12:15], v[124:127], v[4:7]
	v_mfma_f32_16x16x32_bf16 v[140:143], v[12:15], v[100:103], v[140:143]
	v_mfma_f32_16x16x32_bf16 v[148:151], v[12:15], v[108:111], v[148:151]
	v_mfma_f32_16x16x32_bf16 v[156:159], v[12:15], v[116:119], v[156:159]
	v_mfma_f32_16x16x32_bf16 v[8:11], v[16:19], v[60:63], 0
	v_mfma_f32_16x16x32_bf16 v[12:15], v[24:27], v[60:63], 0
	v_mfma_f32_16x16x32_bf16 v[8:11], v[20:23], v[100:103], v[8:11]
	v_mfma_f32_16x16x32_bf16 v[12:15], v[28:31], v[100:103], v[12:15]
	v_mfma_f32_16x16x32_bf16 v[60:63], v[16:19], v[104:107], 0
	v_mfma_f32_16x16x32_bf16 v[100:103], v[24:27], v[104:107], 0
	v_mfma_f32_16x16x32_bf16 v[104:107], v[16:19], v[112:115], 0
	v_mfma_f32_16x16x32_bf16 v[16:19], v[16:19], v[120:123], 0
	v_mfma_f32_16x16x32_bf16 v[60:63], v[20:23], v[108:111], v[60:63]
	v_mfma_f32_16x16x32_bf16 v[100:103], v[28:31], v[108:111], v[100:103]
	v_mfma_f32_16x16x32_bf16 v[104:107], v[20:23], v[116:119], v[104:107]
	v_mfma_f32_16x16x32_bf16 v[108:111], v[24:27], v[112:115], 0
	v_mfma_f32_16x16x32_bf16 v[16:19], v[20:23], v[124:127], v[16:19]
	v_mfma_f32_16x16x32_bf16 v[20:23], v[24:27], v[120:123], 0
	v_mfma_f32_16x16x32_bf16 v[108:111], v[28:31], v[116:119], v[108:111]
	v_mfma_f32_16x16x32_bf16 v[20:23], v[28:31], v[124:127], v[20:23]
	s_barrier
	s_setprio 0
	s_add_i32 s71, 0, 0x18000
	s_add_i32 s69, 0, 0x1c000
	v_add_u32_e32 v196, s71, v134
	v_add_u32_e32 v198, s69, v134
	ds_read_b128 v[24:27], v196
	ds_read_b128 v[28:31], v196 offset:1024
	ds_read_b128 v[112:115], v196 offset:2048
	ds_read_b128 v[116:119], v196 offset:3072
	ds_read_b128 v[120:123], v198
	ds_read_b128 v[124:127], v198 offset:1024
	ds_read_b128 v[160:163], v198 offset:2048
	ds_read_b128 v[164:167], v198 offset:3072
	s_add_u32 s56, s30, 0x10100
	s_addc_u32 s57, s31, 0
	s_mov_b32 m0, s29
	ds_read_b128 v[168:171], v135 offset:32768
	ds_read_b128 v[172:175], v135 offset:33792
	ds_read_b128 v[176:179], v135 offset:34816
	ds_read_b128 v[180:183], v135 offset:35840
	ds_read_b128 v[184:187], v135 offset:36864
	ds_read_b128 v[188:191], v135 offset:37888
	ds_read_b128 v[192:195], v135 offset:38912
	ds_read_b128 v[200:203], v135 offset:39936
	s_nop 0
	global_load_lds_dwordx4 v130, s[56:57]
	s_mov_b32 m0, s47
	s_nop 0
	global_load_lds_dwordx4 v132, s[56:57]
	s_nop 0
	s_nop 0
	s_nop 0
	s_nop 0
	s_nop 0
	s_nop 0
	s_nop 0
	s_nop 0
	s_nop 0
	s_waitcnt vmcnt(8)
	s_waitcnt lgkmcnt(0)
	s_setprio 1
	s_barrier
	v_mfma_f32_16x16x32_bf16 v[64:67], v[24:27], v[168:171], v[64:67]
	v_mfma_f32_16x16x32_bf16 v[64:67], v[28:31], v[172:175], v[64:67]
	v_mfma_f32_16x16x32_bf16 v[68:71], v[112:115], v[168:171], v[68:71]
	v_mfma_f32_16x16x32_bf16 v[68:71], v[116:119], v[172:175], v[68:71]
	v_mfma_f32_16x16x32_bf16 v[72:75], v[24:27], v[176:179], v[72:75]
	v_mfma_f32_16x16x32_bf16 v[72:75], v[28:31], v[180:183], v[72:75]
	v_mfma_f32_16x16x32_bf16 v[76:79], v[112:115], v[176:179], v[76:79]
	v_mfma_f32_16x16x32_bf16 v[76:79], v[116:119], v[180:183], v[76:79]
	v_mfma_f32_16x16x32_bf16 v[80:83], v[24:27], v[184:187], v[80:83]
	v_mfma_f32_16x16x32_bf16 v[80:83], v[28:31], v[188:191], v[80:83]
	v_mfma_f32_16x16x32_bf16 v[84:87], v[112:115], v[184:187], v[84:87]
	v_mfma_f32_16x16x32_bf16 v[84:87], v[116:119], v[188:191], v[84:87]
	v_mfma_f32_16x16x32_bf16 v[88:91], v[24:27], v[192:195], v[88:91]
	v_mfma_f32_16x16x32_bf16 v[88:91], v[28:31], v[200:203], v[88:91]
	v_mfma_f32_16x16x32_bf16 v[92:95], v[112:115], v[192:195], v[92:95]
	v_mfma_f32_16x16x32_bf16 v[92:95], v[116:119], v[200:203], v[92:95]
	v_mfma_f32_16x16x32_bf16 v[96:99], v[120:123], v[168:171], v[96:99]
	v_mfma_f32_16x16x32_bf16 v[96:99], v[124:127], v[172:175], v[96:99]
	v_mfma_f32_16x16x32_bf16 v[32:35], v[160:163], v[168:171], v[32:35]
	v_mfma_f32_16x16x32_bf16 v[32:35], v[164:167], v[172:175], v[32:35]
	v_mfma_f32_16x16x32_bf16 v[36:39], v[120:123], v[176:179], v[36:39]
	v_mfma_f32_16x16x32_bf16 v[36:39], v[124:127], v[180:183], v[36:39]
	v_mfma_f32_16x16x32_bf16 v[40:43], v[160:163], v[176:179], v[40:43]
	v_mfma_f32_16x16x32_bf16 v[40:43], v[164:167], v[180:183], v[40:43]
	v_mfma_f32_16x16x32_bf16 v[44:47], v[120:123], v[184:187], v[44:47]
	v_mfma_f32_16x16x32_bf16 v[44:47], v[124:127], v[188:191], v[44:47]
	v_mfma_f32_16x16x32_bf16 v[48:51], v[160:163], v[184:187], v[48:51]
	v_mfma_f32_16x16x32_bf16 v[48:51], v[164:167], v[188:191], v[48:51]
	v_mfma_f32_16x16x32_bf16 v[52:55], v[120:123], v[192:195], v[52:55]
	v_mfma_f32_16x16x32_bf16 v[52:55], v[124:127], v[200:203], v[52:55]
	v_mfma_f32_16x16x32_bf16 v[56:59], v[160:163], v[192:195], v[56:59]
	v_mfma_f32_16x16x32_bf16 v[56:59], v[164:167], v[200:203], v[56:59]
	s_barrier
	s_setprio 0
	s_add_u32 s74, s34, 0x180
	s_addc_u32 s75, s35, 0
	s_add_i32 s71, s71, s97
	s_add_i32 s56, s71, 0x2000
	s_mov_b32 m0, s71
	s_add_u32 s34, s34, 0x80180
	ds_read_b128 v[168:171], v135 offset:49152
	ds_read_b128 v[172:175], v135 offset:50176
	ds_read_b128 v[176:179], v135 offset:51200
	ds_read_b128 v[180:183], v135 offset:52224
	ds_read_b128 v[184:187], v135 offset:53248
	ds_read_b128 v[188:191], v135 offset:54272
	ds_read_b128 v[192:195], v135 offset:55296
	ds_read_b128 v[200:203], v135 offset:56320
	s_addc_u32 s35, s35, 0
	global_load_lds_dwordx4 v131, s[74:75]
	s_mov_b32 m0, s56
	s_add_i32 s57, s69, s97
	s_add_i32 s69, s57, 0x2000
	global_load_lds_dwordx4 v133, s[74:75]
	s_mov_b32 m0, s57
	s_nop 0
	global_load_lds_dwordx4 v131, s[34:35]
	s_mov_b32 m0, s69
	s_nop 0
	global_load_lds_dwordx4 v133, s[34:35]
	s_mov_b32 m0, s48
	s_nop 0
	global_load_lds_dwordx4 v130, s[38:39]
	s_mov_b32 m0, s49
	s_nop 0
	global_load_lds_dwordx4 v132, s[38:39]
	s_nop 0
	s_nop 0
	s_nop 0
	s_nop 0
	s_nop 0
	s_nop 0
	s_nop 0
	s_nop 0
	s_waitcnt vmcnt(8)
	s_waitcnt lgkmcnt(0)
	s_setprio 1
	s_barrier
	v_mfma_f32_16x16x32_bf16 v[0:3], v[24:27], v[192:195], v[0:3]
	v_mfma_f32_16x16x32_bf16 v[0:3], v[28:31], v[200:203], v[0:3]
	v_mfma_f32_16x16x32_bf16 v[4:7], v[112:115], v[192:195], v[4:7]
	v_mfma_f32_16x16x32_bf16 v[4:7], v[116:119], v[200:203], v[4:7]
	v_mfma_f32_16x16x32_bf16 v[136:139], v[24:27], v[168:171], v[136:139]
	v_mfma_f32_16x16x32_bf16 v[136:139], v[28:31], v[172:175], v[136:139]
	v_mfma_f32_16x16x32_bf16 v[140:143], v[112:115], v[168:171], v[140:143]
	v_mfma_f32_16x16x32_bf16 v[140:143], v[116:119], v[172:175], v[140:143]
	v_mfma_f32_16x16x32_bf16 v[144:147], v[24:27], v[176:179], v[144:147]
	v_mfma_f32_16x16x32_bf16 v[144:147], v[28:31], v[180:183], v[144:147]
	v_mfma_f32_16x16x32_bf16 v[148:151], v[112:115], v[176:179], v[148:151]
	v_mfma_f32_16x16x32_bf16 v[148:151], v[116:119], v[180:183], v[148:151]
	v_mfma_f32_16x16x32_bf16 v[152:155], v[24:27], v[184:187], v[152:155]
	v_mfma_f32_16x16x32_bf16 v[152:155], v[28:31], v[188:191], v[152:155]
	v_mfma_f32_16x16x32_bf16 v[156:159], v[112:115], v[184:187], v[156:159]
	v_mfma_f32_16x16x32_bf16 v[156:159], v[116:119], v[188:191], v[156:159]
	v_mfma_f32_16x16x32_bf16 v[8:11], v[120:123], v[168:171], v[8:11]
	v_mfma_f32_16x16x32_bf16 v[12:15], v[160:163], v[168:171], v[12:15]
	v_mfma_f32_16x16x32_bf16 v[24:27], v[120:123], v[176:179], v[60:63]
	v_mfma_f32_16x16x32_bf16 v[28:31], v[160:163], v[176:179], v[100:103]
	v_mfma_f32_16x16x32_bf16 v[60:63], v[120:123], v[184:187], v[104:107]
	v_mfma_f32_16x16x32_bf16 v[100:103], v[160:163], v[184:187], v[108:111]
	v_mfma_f32_16x16x32_bf16 v[16:19], v[120:123], v[192:195], v[16:19]
	v_mfma_f32_16x16x32_bf16 v[20:23], v[160:163], v[192:195], v[20:23]
	v_mfma_f32_16x16x32_bf16 v[8:11], v[124:127], v[172:175], v[8:11]
	v_mfma_f32_16x16x32_bf16 v[12:15], v[164:167], v[172:175], v[12:15]
	v_mfma_f32_16x16x32_bf16 v[24:27], v[124:127], v[180:183], v[24:27]
	v_mfma_f32_16x16x32_bf16 v[28:31], v[164:167], v[180:183], v[28:31]
	v_mfma_f32_16x16x32_bf16 v[60:63], v[124:127], v[188:191], v[60:63]
	v_mfma_f32_16x16x32_bf16 v[100:103], v[164:167], v[188:191], v[100:103]
	v_mfma_f32_16x16x32_bf16 v[16:19], v[124:127], v[200:203], v[16:19]
	v_mfma_f32_16x16x32_bf16 v[20:23], v[164:167], v[200:203], v[20:23]
	s_barrier
	s_setprio 0
	ds_read_b128 v[104:107], v128
	ds_read_b128 v[108:111], v128 offset:1024
	ds_read_b128 v[112:115], v128 offset:2048
	ds_read_b128 v[116:119], v128 offset:3072
	ds_read_b128 v[120:123], v129
	ds_read_b128 v[124:127], v129 offset:1024
	ds_read_b128 v[160:163], v129 offset:2048
	ds_read_b128 v[164:167], v129 offset:3072
	s_add_u32 s34, s36, 0x80
	s_addc_u32 s35, s37, 0
	s_add_u32 s30, s30, 0x10180
	s_addc_u32 s31, s31, 0
	s_mov_b32 m0, s5
	ds_read_b128 v[168:171], v135
	ds_read_b128 v[172:175], v135 offset:1024
	ds_read_b128 v[176:179], v135 offset:2048
	ds_read_b128 v[180:183], v135 offset:3072
	ds_read_b128 v[184:187], v135 offset:4096
	ds_read_b128 v[188:191], v135 offset:5120
	ds_read_b128 v[192:195], v135 offset:6144
	ds_read_b128 v[200:203], v135 offset:7168
	s_nop 0
	global_load_lds_dwordx4 v130, s[30:31]
	s_mov_b32 m0, s15
	s_nop 0
	global_load_lds_dwordx4 v132, s[30:31]
	s_nop 0
	s_nop 0
	s_nop 0
	s_nop 0
	s_nop 0
	s_nop 0
	s_nop 0
	s_nop 0
	s_nop 0
	s_nop 0
	s_nop 0
	s_nop 0
	s_waitcnt vmcnt(8)
	s_waitcnt lgkmcnt(0)
	s_setprio 1
	s_barrier
	v_mfma_f32_16x16x32_bf16 v[64:67], v[104:107], v[168:171], v[64:67]
	v_mfma_f32_16x16x32_bf16 v[64:67], v[108:111], v[172:175], v[64:67]
	v_mfma_f32_16x16x32_bf16 v[68:71], v[112:115], v[168:171], v[68:71]
	v_mfma_f32_16x16x32_bf16 v[68:71], v[116:119], v[172:175], v[68:71]
	v_mfma_f32_16x16x32_bf16 v[72:75], v[104:107], v[176:179], v[72:75]
	v_mfma_f32_16x16x32_bf16 v[72:75], v[108:111], v[180:183], v[72:75]
	v_mfma_f32_16x16x32_bf16 v[76:79], v[112:115], v[176:179], v[76:79]
	v_mfma_f32_16x16x32_bf16 v[76:79], v[116:119], v[180:183], v[76:79]
	v_mfma_f32_16x16x32_bf16 v[80:83], v[104:107], v[184:187], v[80:83]
	v_mfma_f32_16x16x32_bf16 v[80:83], v[108:111], v[188:191], v[80:83]
	v_mfma_f32_16x16x32_bf16 v[84:87], v[112:115], v[184:187], v[84:87]
	v_mfma_f32_16x16x32_bf16 v[84:87], v[116:119], v[188:191], v[84:87]
	v_mfma_f32_16x16x32_bf16 v[88:91], v[104:107], v[192:195], v[88:91]
	v_mfma_f32_16x16x32_bf16 v[88:91], v[108:111], v[200:203], v[88:91]
	v_mfma_f32_16x16x32_bf16 v[92:95], v[112:115], v[192:195], v[92:95]
	v_mfma_f32_16x16x32_bf16 v[92:95], v[116:119], v[200:203], v[92:95]
	v_mfma_f32_16x16x32_bf16 v[32:35], v[160:163], v[168:171], v[32:35]
	v_mfma_f32_16x16x32_bf16 v[96:99], v[120:123], v[168:171], v[96:99]
	v_mfma_f32_16x16x32_bf16 v[168:171], v[164:167], v[172:175], v[32:35]
	v_mfma_f32_16x16x32_bf16 v[32:35], v[120:123], v[176:179], v[36:39]
	v_mfma_f32_16x16x32_bf16 v[36:39], v[124:127], v[180:183], v[32:35]
	v_mfma_f32_16x16x32_bf16 v[32:35], v[160:163], v[176:179], v[40:43]
	v_mfma_f32_16x16x32_bf16 v[204:207], v[124:127], v[172:175], v[96:99]
	v_mfma_f32_16x16x32_bf16 v[172:175], v[164:167], v[180:183], v[32:35]
	v_mfma_f32_16x16x32_bf16 v[32:35], v[120:123], v[184:187], v[44:47]
	v_mfma_f32_16x16x32_bf16 v[44:47], v[124:127], v[188:191], v[32:35]
	v_mfma_f32_16x16x32_bf16 v[32:35], v[160:163], v[184:187], v[48:51]
	v_mfma_f32_16x16x32_bf16 v[48:51], v[164:167], v[188:191], v[32:35]
	v_mfma_f32_16x16x32_bf16 v[32:35], v[120:123], v[192:195], v[52:55]
	v_mfma_f32_16x16x32_bf16 v[52:55], v[124:127], v[200:203], v[32:35]
	v_mfma_f32_16x16x32_bf16 v[32:35], v[160:163], v[192:195], v[56:59]
	v_mfma_f32_16x16x32_bf16 v[56:59], v[164:167], v[200:203], v[32:35]
	s_barrier
	s_setprio 0
	s_mov_b32 m0, s70
	s_mov_b64 s[30:31], s[22:23]
	s_nop 2
	ds_read_b128 v[32:35], v135 offset:16384
	ds_read_b128 v[40:43], v135 offset:17408
	ds_read_b128 v[96:99], v135 offset:18432
	ds_read_b128 v[176:179], v135 offset:19456
	ds_read_b128 v[180:183], v135 offset:20480
	ds_read_b128 v[184:187], v135 offset:21504
	ds_read_b128 v[188:191], v135 offset:22528
	ds_read_b128 v[192:195], v135 offset:23552
	s_nop 0
	global_load_lds_dwordx4 v131, s[30:31]
	s_mov_b32 m0, s4
	s_add_u32 s4, s22, 0x80000
	s_addc_u32 s5, s23, 0
	global_load_lds_dwordx4 v133, s[30:31]
	s_mov_b32 m0, s17
	s_nop 0
	global_load_lds_dwordx4 v131, s[4:5]
	s_mov_b32 m0, s21
	s_nop 0
	global_load_lds_dwordx4 v133, s[4:5]
	s_mov_b64 s[4:5], s[36:37]
	s_mov_b32 m0, s13
	s_nop 0
	global_load_lds_dwordx4 v130, s[4:5]
	s_mov_b32 m0, s27
	s_nop 0
	global_load_lds_dwordx4 v132, s[4:5]
	s_nop 0
	s_nop 0
	s_nop 0
	s_nop 0
	s_nop 0
	s_nop 0
	s_nop 0
	s_nop 0
	s_nop 0
	s_nop 0
	s_nop 0
	s_nop 0
	s_nop 0
	s_waitcnt vmcnt(8)
	s_waitcnt lgkmcnt(0)
	s_setprio 1
	s_barrier
	v_mfma_f32_16x16x32_bf16 v[0:3], v[104:107], v[188:191], v[0:3]
	v_mfma_f32_16x16x32_bf16 v[0:3], v[108:111], v[192:195], v[0:3]
	v_mfma_f32_16x16x32_bf16 v[4:7], v[112:115], v[188:191], v[4:7]
	v_mfma_f32_16x16x32_bf16 v[4:7], v[116:119], v[192:195], v[4:7]
	v_mfma_f32_16x16x32_bf16 v[136:139], v[104:107], v[32:35], v[136:139]
	v_mfma_f32_16x16x32_bf16 v[136:139], v[108:111], v[40:43], v[136:139]
	v_mfma_f32_16x16x32_bf16 v[140:143], v[112:115], v[32:35], v[140:143]
	v_mfma_f32_16x16x32_bf16 v[140:143], v[116:119], v[40:43], v[140:143]
	v_mfma_f32_16x16x32_bf16 v[144:147], v[104:107], v[96:99], v[144:147]
	v_mfma_f32_16x16x32_bf16 v[144:147], v[108:111], v[176:179], v[144:147]
	v_mfma_f32_16x16x32_bf16 v[148:151], v[112:115], v[96:99], v[148:151]
	v_mfma_f32_16x16x32_bf16 v[148:151], v[116:119], v[176:179], v[148:151]
	v_mfma_f32_16x16x32_bf16 v[152:155], v[104:107], v[180:183], v[152:155]
	v_mfma_f32_16x16x32_bf16 v[152:155], v[108:111], v[184:187], v[152:155]
	v_mfma_f32_16x16x32_bf16 v[156:159], v[112:115], v[180:183], v[156:159]
	v_mfma_f32_16x16x32_bf16 v[156:159], v[116:119], v[184:187], v[156:159]
	v_mfma_f32_16x16x32_bf16 v[12:15], v[160:163], v[32:35], v[12:15]
	v_mfma_f32_16x16x32_bf16 v[200:203], v[164:167], v[40:43], v[12:15]
	v_mfma_f32_16x16x32_bf16 v[12:15], v[120:123], v[96:99], v[24:27]
	v_mfma_f32_16x16x32_bf16 v[24:27], v[124:127], v[176:179], v[12:15]
	v_mfma_f32_16x16x32_bf16 v[12:15], v[160:163], v[96:99], v[28:31]
	v_mfma_f32_16x16x32_bf16 v[176:179], v[164:167], v[176:179], v[12:15]
	v_mfma_f32_16x16x32_bf16 v[12:15], v[120:123], v[180:183], v[60:63]
	v_mfma_f32_16x16x32_bf16 v[208:211], v[124:127], v[184:187], v[12:15]
	v_mfma_f32_16x16x32_bf16 v[12:15], v[160:163], v[180:183], v[100:103]
	v_mfma_f32_16x16x32_bf16 v[8:11], v[120:123], v[32:35], v[8:11]
	v_mfma_f32_16x16x32_bf16 v[180:183], v[164:167], v[184:187], v[12:15]
	v_mfma_f32_16x16x32_bf16 v[12:15], v[120:123], v[188:191], v[16:19]
	v_mfma_f32_16x16x32_bf16 v[8:11], v[124:127], v[40:43], v[8:11]
	v_mfma_f32_16x16x32_bf16 v[184:187], v[124:127], v[192:195], v[12:15]
	v_mfma_f32_16x16x32_bf16 v[12:15], v[160:163], v[188:191], v[20:23]
	v_mfma_f32_16x16x32_bf16 v[160:163], v[164:167], v[192:195], v[12:15]
	s_barrier
	s_setprio 0
	s_nop 4
	ds_read_b128 v[12:15], v196
	ds_read_b128 v[16:19], v196 offset:1024
	ds_read_b128 v[164:167], v196 offset:2048
	ds_read_b128 v[188:191], v196 offset:3072
	ds_read_b128 v[192:195], v198
	ds_read_b128 v[220:223], v198 offset:1024
	ds_read_b128 v[224:227], v198 offset:2048
	ds_read_b128 v[228:231], v198 offset:3072
	s_add_u32 s4, s36, 0x10000
	s_addc_u32 s5, s37, 0
	s_mov_b32 m0, s29
	ds_read_b128 v[20:23], v135 offset:32768
	ds_read_b128 v[28:31], v135 offset:33792
	ds_read_b128 v[60:63], v135 offset:34816
	ds_read_b128 v[100:103], v135 offset:35840
	ds_read_b128 v[232:235], v135 offset:36864
	ds_read_b128 v[236:239], v135 offset:37888
	ds_read_b128 v[240:243], v135 offset:38912
	ds_read_b128 v[244:247], v135 offset:39936
	s_nop 0
	global_load_lds_dwordx4 v130, s[4:5]
	s_mov_b32 m0, s47
	s_nop 0
	global_load_lds_dwordx4 v132, s[4:5]
	s_nop 0
	s_nop 0
	s_nop 0
	s_nop 0
	s_nop 0
	s_nop 0
	s_nop 0
	s_nop 0
	s_nop 0
	s_nop 0
	s_nop 0
	s_nop 0
	s_nop 0
	s_nop 0
	s_waitcnt vmcnt(8)
	s_waitcnt lgkmcnt(0)
	s_setprio 1
	s_barrier
	v_mfma_f32_16x16x32_bf16 v[32:35], v[12:15], v[20:23], v[64:67]
	v_mfma_f32_16x16x32_bf16 v[120:123], v[16:19], v[28:31], v[32:35]
	v_mfma_f32_16x16x32_bf16 v[32:35], v[164:167], v[20:23], v[68:71]
	v_mfma_f32_16x16x32_bf16 v[112:115], v[188:191], v[28:31], v[32:35]
	v_mfma_f32_16x16x32_bf16 v[32:35], v[12:15], v[60:63], v[72:75]
	v_mfma_f32_16x16x32_bf16 v[104:107], v[16:19], v[100:103], v[32:35]
	v_mfma_f32_16x16x32_bf16 v[32:35], v[164:167], v[60:63], v[76:79]
	v_mfma_f32_16x16x32_bf16 v[96:99], v[188:191], v[100:103], v[32:35]
	v_mfma_f32_16x16x32_bf16 v[32:35], v[12:15], v[232:235], v[80:83]
	v_mfma_f32_16x16x32_bf16 v[72:75], v[16:19], v[236:239], v[32:35]
	v_mfma_f32_16x16x32_bf16 v[32:35], v[164:167], v[232:235], v[84:87]
	v_mfma_f32_16x16x32_bf16 v[64:67], v[188:191], v[236:239], v[32:35]
	v_mfma_f32_16x16x32_bf16 v[32:35], v[12:15], v[240:243], v[88:91]
	v_mfma_f32_16x16x32_bf16 v[40:43], v[16:19], v[244:247], v[32:35]
	v_mfma_f32_16x16x32_bf16 v[32:35], v[164:167], v[240:243], v[92:95]
	v_mfma_f32_16x16x32_bf16 v[32:35], v[188:191], v[244:247], v[32:35]
	v_mfma_f32_16x16x32_bf16 v[68:71], v[192:195], v[20:23], v[204:207]
	v_mfma_f32_16x16x32_bf16 v[20:23], v[224:227], v[20:23], v[168:171]
	v_mfma_f32_16x16x32_bf16 v[116:119], v[228:231], v[28:31], v[20:23]
	v_mfma_f32_16x16x32_bf16 v[20:23], v[192:195], v[60:63], v[36:39]
	v_mfma_f32_16x16x32_bf16 v[108:111], v[220:223], v[100:103], v[20:23]
	v_mfma_f32_16x16x32_bf16 v[20:23], v[224:227], v[60:63], v[172:175]
	v_mfma_f32_16x16x32_bf16 v[100:103], v[228:231], v[100:103], v[20:23]
	v_mfma_f32_16x16x32_bf16 v[20:23], v[192:195], v[232:235], v[44:47]
	v_mfma_f32_16x16x32_bf16 v[76:79], v[220:223], v[236:239], v[20:23]
	v_mfma_f32_16x16x32_bf16 v[20:23], v[224:227], v[232:235], v[48:51]
	v_mfma_f32_16x16x32_bf16 v[124:127], v[220:223], v[28:31], v[68:71]
	v_mfma_f32_16x16x32_bf16 v[68:71], v[228:231], v[236:239], v[20:23]
	v_mfma_f32_16x16x32_bf16 v[20:23], v[192:195], v[240:243], v[52:55]
	v_mfma_f32_16x16x32_bf16 v[44:47], v[220:223], v[244:247], v[20:23]
	v_mfma_f32_16x16x32_bf16 v[20:23], v[224:227], v[240:243], v[56:59]
	v_mfma_f32_16x16x32_bf16 v[36:39], v[228:231], v[244:247], v[20:23]
	s_barrier
	s_setprio 0
	s_add_u32 s4, s22, 0x80
	s_mov_b32 m0, s71
	s_addc_u32 s5, s23, 0
	ds_read_b128 v[48:51], v135 offset:49152
	ds_read_b128 v[56:59], v135 offset:50176
	ds_read_b128 v[168:171], v135 offset:51200
	ds_read_b128 v[172:175], v135 offset:52224
	ds_read_b128 v[204:207], v135 offset:53248
	ds_read_b128 v[232:235], v135 offset:54272
	ds_read_b128 v[236:239], v135 offset:55296
	ds_read_b128 v[240:243], v135 offset:56320
	s_nop 0
	global_load_lds_dwordx4 v131, s[4:5]
	s_mov_b32 m0, s56
	s_nop 0
	global_load_lds_dwordx4 v133, s[4:5]
	s_add_u32 s4, s22, 0x80080
	s_addc_u32 s5, s23, 0
	s_mov_b32 m0, s57
	s_nop 0
	global_load_lds_dwordx4 v131, s[4:5]
	s_mov_b32 m0, s69
	s_nop 0
	global_load_lds_dwordx4 v133, s[4:5]
	s_mov_b32 m0, s48
	s_nop 0
	global_load_lds_dwordx4 v130, s[34:35]
	s_mov_b32 m0, s49
	s_nop 0
	global_load_lds_dwordx4 v132, s[34:35]
	s_nop 0
	s_nop 0
	s_nop 0
	s_nop 0
	s_nop 0
	s_nop 0
	s_nop 0
	s_nop 0
	s_nop 0
	s_nop 0
	s_nop 0
	s_nop 0
	s_waitcnt vmcnt(8)
	s_waitcnt lgkmcnt(0)
	s_setprio 1
	s_barrier
	v_mfma_f32_16x16x32_bf16 v[20:23], v[12:15], v[48:51], v[136:139]
	v_mfma_f32_16x16x32_bf16 v[92:95], v[16:19], v[56:59], v[20:23]
	v_mfma_f32_16x16x32_bf16 v[20:23], v[164:167], v[48:51], v[140:143]
	v_mfma_f32_16x16x32_bf16 v[84:87], v[188:191], v[56:59], v[20:23]
	v_mfma_f32_16x16x32_bf16 v[20:23], v[12:15], v[168:171], v[144:147]
	v_mfma_f32_16x16x32_bf16 v[60:63], v[16:19], v[172:175], v[20:23]
	v_mfma_f32_16x16x32_bf16 v[20:23], v[164:167], v[168:171], v[148:151]
	v_mfma_f32_16x16x32_bf16 v[52:55], v[188:191], v[172:175], v[20:23]
	v_mfma_f32_16x16x32_bf16 v[20:23], v[12:15], v[204:207], v[152:155]
	v_mfma_f32_16x16x32_bf16 v[0:3], v[12:15], v[236:239], v[0:3]
	v_mfma_f32_16x16x32_bf16 v[28:31], v[16:19], v[232:235], v[20:23]
	v_mfma_f32_16x16x32_bf16 v[20:23], v[164:167], v[204:207], v[156:159]
	v_mfma_f32_16x16x32_bf16 v[12:15], v[16:19], v[240:243], v[0:3]
	v_mfma_f32_16x16x32_bf16 v[0:3], v[164:167], v[236:239], v[4:7]
	v_mfma_f32_16x16x32_bf16 v[20:23], v[188:191], v[232:235], v[20:23]
	v_mfma_f32_16x16x32_bf16 v[4:7], v[188:191], v[240:243], v[0:3]
	v_mfma_f32_16x16x32_bf16 v[0:3], v[192:195], v[48:51], v[8:11]
	v_mfma_f32_16x16x32_bf16 v[88:91], v[220:223], v[56:59], v[0:3]
	v_mfma_f32_16x16x32_bf16 v[0:3], v[224:227], v[48:51], v[200:203]
	v_mfma_f32_16x16x32_bf16 v[80:83], v[228:231], v[56:59], v[0:3]
	v_mfma_f32_16x16x32_bf16 v[0:3], v[192:195], v[168:171], v[24:27]
	v_mfma_f32_16x16x32_bf16 v[56:59], v[220:223], v[172:175], v[0:3]
	v_mfma_f32_16x16x32_bf16 v[0:3], v[224:227], v[168:171], v[176:179]
	v_mfma_f32_16x16x32_bf16 v[48:51], v[228:231], v[172:175], v[0:3]
	v_mfma_f32_16x16x32_bf16 v[0:3], v[192:195], v[204:207], v[208:211]
	v_mfma_f32_16x16x32_bf16 v[24:27], v[220:223], v[232:235], v[0:3]
	v_mfma_f32_16x16x32_bf16 v[0:3], v[224:227], v[204:207], v[180:183]
	v_mfma_f32_16x16x32_bf16 v[16:19], v[228:231], v[232:235], v[0:3]
	v_mfma_f32_16x16x32_bf16 v[0:3], v[192:195], v[236:239], v[184:187]
	v_mfma_f32_16x16x32_bf16 v[8:11], v[220:223], v[240:243], v[0:3]
	v_mfma_f32_16x16x32_bf16 v[0:3], v[224:227], v[236:239], v[160:163]
	v_mfma_f32_16x16x32_bf16 v[0:3], v[228:231], v[240:243], v[0:3]
	s_barrier
	s_setprio 0
	s_andn2_b64 vcc, exec, s[60:61]
	s_cbranch_vccnz .LBB0_300
	s_barrier

.LBB0_313:
	s_ashr_i32 s15, s14, 31
	s_lshl_b64 s[4:5], s[14:15], 17
	s_add_u32 s20, s2, s4
	s_addc_u32 s21, s19, s5
	s_and_b64 s[4:5], s[16:17], exec
	s_cselect_b32 s39, s21, s31
	s_cselect_b32 s38, s20, s30
	s_ashr_i32 s11, s10, 31
	s_lshl_b64 s[4:5], s[10:11], 9
	s_add_u32 s11, s44, s4
	s_addc_u32 s15, s46, s5
	s_ashr_i32 s13, s12, 31
	s_lshl_b64 s[4:5], s[12:13], 20
	s_add_u32 s22, s11, s4
	s_addc_u32 s23, s15, s5
	s_and_b64 s[4:5], s[16:17], exec
	s_cselect_b32 s35, s23, s37
	s_cselect_b32 s34, s22, s36
	s_add_u32 s56, s30, 0x100
	s_addc_u32 s57, s31, 0
	s_add_u32 s82, s36, 0x100
	s_addc_u32 s83, s37, 0
	s_add_u32 s80, s30, 0x180
	s_addc_u32 s81, s31, 0
	s_add_i32 s4, 0, 0x10000
	s_add_i32 s13, 0, 0x14000
	v_add_u32_e32 v128, s4, v134
	v_add_u32_e32 v129, s13, v134
	ds_read_b128 v[0:3], v128
	ds_read_b128 v[4:7], v128 offset:1024
	ds_read_b128 v[8:11], v128 offset:2048
	ds_read_b128 v[12:15], v128 offset:3072
	ds_read_b128 v[16:19], v129
	ds_read_b128 v[20:23], v129 offset:1024
	ds_read_b128 v[24:27], v129 offset:2048
	ds_read_b128 v[28:31], v129 offset:3072
	s_add_u32 s70, s30, 0x10080
	s_addc_u32 s71, s31, 0
	s_add_i32 s5, s25, 0xc000
	s_mov_b32 m0, s5
	s_add_i32 s11, s25, 0xe000
	ds_read_b128 v[32:35], v135
	ds_read_b128 v[36:39], v135 offset:1024
	ds_read_b128 v[40:43], v135 offset:2048
	ds_read_b128 v[44:47], v135 offset:3072
	ds_read_b128 v[48:51], v135 offset:4096
	ds_read_b128 v[52:55], v135 offset:5120
	ds_read_b128 v[56:59], v135 offset:6144
	ds_read_b128 v[60:63], v135 offset:7168
	s_nop 0
	global_load_lds_dwordx4 v133, s[70:71]
	s_mov_b32 m0, s11
	s_nop 0
	global_load_lds_dwordx4 v131, s[70:71]
	s_nop 0
	s_nop 0
	s_nop 0
	s_nop 0
	s_nop 0
	s_waitcnt vmcnt(8)
	s_waitcnt lgkmcnt(0)
	s_setprio 1
	s_barrier
	v_mfma_f32_16x16x32_bf16 v[64:67], v[0:3], v[32:35], 0
	v_mfma_f32_16x16x32_bf16 v[68:71], v[8:11], v[32:35], 0
	v_mfma_f32_16x16x32_bf16 v[72:75], v[0:3], v[40:43], 0
	v_mfma_f32_16x16x32_bf16 v[76:79], v[8:11], v[40:43], 0
	v_mfma_f32_16x16x32_bf16 v[80:83], v[0:3], v[48:51], 0
	v_mfma_f32_16x16x32_bf16 v[84:87], v[8:11], v[48:51], 0
	v_mfma_f32_16x16x32_bf16 v[88:91], v[0:3], v[56:59], 0
	v_mfma_f32_16x16x32_bf16 v[92:95], v[8:11], v[56:59], 0
	v_mfma_f32_16x16x32_bf16 v[64:67], v[4:7], v[36:39], v[64:67]
	v_mfma_f32_16x16x32_bf16 v[68:71], v[12:15], v[36:39], v[68:71]
	v_mfma_f32_16x16x32_bf16 v[72:75], v[4:7], v[44:47], v[72:75]
	v_mfma_f32_16x16x32_bf16 v[76:79], v[12:15], v[44:47], v[76:79]
	v_mfma_f32_16x16x32_bf16 v[80:83], v[4:7], v[52:55], v[80:83]
	v_mfma_f32_16x16x32_bf16 v[84:87], v[12:15], v[52:55], v[84:87]
	v_mfma_f32_16x16x32_bf16 v[88:91], v[4:7], v[60:63], v[88:91]
	v_mfma_f32_16x16x32_bf16 v[92:95], v[12:15], v[60:63], v[92:95]
	v_mfma_f32_16x16x32_bf16 v[96:99], v[16:19], v[32:35], 0
	v_mfma_f32_16x16x32_bf16 v[32:35], v[24:27], v[32:35], 0
	v_mfma_f32_16x16x32_bf16 v[96:99], v[20:23], v[36:39], v[96:99]
	v_mfma_f32_16x16x32_bf16 v[32:35], v[28:31], v[36:39], v[32:35]
	v_mfma_f32_16x16x32_bf16 v[36:39], v[16:19], v[40:43], 0
	v_mfma_f32_16x16x32_bf16 v[40:43], v[24:27], v[40:43], 0
	v_mfma_f32_16x16x32_bf16 v[36:39], v[20:23], v[44:47], v[36:39]
	v_mfma_f32_16x16x32_bf16 v[40:43], v[28:31], v[44:47], v[40:43]
	v_mfma_f32_16x16x32_bf16 v[44:47], v[16:19], v[48:51], 0
	v_mfma_f32_16x16x32_bf16 v[48:51], v[24:27], v[48:51], 0
	v_mfma_f32_16x16x32_bf16 v[44:47], v[20:23], v[52:55], v[44:47]
	v_mfma_f32_16x16x32_bf16 v[48:51], v[28:31], v[52:55], v[48:51]
	v_mfma_f32_16x16x32_bf16 v[52:55], v[16:19], v[56:59], 0
	v_mfma_f32_16x16x32_bf16 v[56:59], v[24:27], v[56:59], 0
	v_mfma_f32_16x16x32_bf16 v[52:55], v[20:23], v[60:63], v[52:55]
	v_mfma_f32_16x16x32_bf16 v[56:59], v[28:31], v[60:63], v[56:59]
	s_barrier
	s_setprio 0
	s_add_i32 s70, s4, s97
	s_add_i32 s4, s70, 0x2000
	s_mov_b32 m0, s70
	s_add_u32 s74, s36, 0x80100
	ds_read_b128 v[60:63], v135 offset:16384
	ds_read_b128 v[100:103], v135 offset:17408
	ds_read_b128 v[104:107], v135 offset:18432
	ds_read_b128 v[108:111], v135 offset:19456
	ds_read_b128 v[112:115], v135 offset:20480
	ds_read_b128 v[116:119], v135 offset:21504
	ds_read_b128 v[120:123], v135 offset:22528
	ds_read_b128 v[124:127], v135 offset:23552
	s_addc_u32 s75, s37, 0
	global_load_lds_dwordx4 v132, s[82:83]
	s_mov_b32 m0, s4
	s_add_i32 s13, s13, s97
	s_add_i32 s15, s13, 0x2000
	global_load_lds_dwordx4 v130, s[82:83]
	s_mov_b32 m0, s13
	s_nop 0
	global_load_lds_dwordx4 v132, s[74:75]
	s_mov_b32 m0, s15
	s_nop 0
	global_load_lds_dwordx4 v130, s[74:75]
	s_mov_b32 m0, s25
	s_nop 0
	global_load_lds_dwordx4 v133, s[56:57]
	s_mov_b32 m0, s27
	s_nop 0
	global_load_lds_dwordx4 v131, s[56:57]
	s_nop 0
	s_nop 0
	s_nop 0
	s_nop 0
	s_nop 0
	s_nop 0
	s_nop 0
	s_nop 0
	s_nop 0
	s_nop 0
	s_nop 0
	s_waitcnt vmcnt(8)
	s_waitcnt lgkmcnt(0)
	s_setprio 1
	s_barrier
	v_mfma_f32_16x16x32_bf16 v[136:139], v[0:3], v[60:63], 0
	v_mfma_f32_16x16x32_bf16 v[144:147], v[0:3], v[104:107], 0
	v_mfma_f32_16x16x32_bf16 v[152:155], v[0:3], v[112:115], 0
	v_mfma_f32_16x16x32_bf16 v[0:3], v[0:3], v[120:123], 0
	v_mfma_f32_16x16x32_bf16 v[136:139], v[4:7], v[100:103], v[136:139]
	v_mfma_f32_16x16x32_bf16 v[144:147], v[4:7], v[108:111], v[144:147]
	v_mfma_f32_16x16x32_bf16 v[152:155], v[4:7], v[116:119], v[152:155]
	v_mfma_f32_16x16x32_bf16 v[0:3], v[4:7], v[124:127], v[0:3]
	v_mfma_f32_16x16x32_bf16 v[4:7], v[8:11], v[120:123], 0
	v_mfma_f32_16x16x32_bf16 v[140:143], v[8:11], v[60:63], 0
	v_mfma_f32_16x16x32_bf16 v[148:151], v[8:11], v[104:107], 0
	v_mfma_f32_16x16x32_bf16 v[156:159], v[8:11], v[112:115], 0
	v_mfma_f32_16x16x32_bf16 v[4:7], v[12:15], v[124:127], v[4:7]
	v_mfma_f32_16x16x32_bf16 v[140:143], v[12:15], v[100:103], v[140:143]
	v_mfma_f32_16x16x32_bf16 v[148:151], v[12:15], v[108:111], v[148:151]
	v_mfma_f32_16x16x32_bf16 v[156:159], v[12:15], v[116:119], v[156:159]
	v_mfma_f32_16x16x32_bf16 v[8:11], v[16:19], v[60:63], 0
	v_mfma_f32_16x16x32_bf16 v[12:15], v[24:27], v[60:63], 0
	v_mfma_f32_16x16x32_bf16 v[8:11], v[20:23], v[100:103], v[8:11]
	v_mfma_f32_16x16x32_bf16 v[12:15], v[28:31], v[100:103], v[12:15]
	v_mfma_f32_16x16x32_bf16 v[60:63], v[16:19], v[104:107], 0
	v_mfma_f32_16x16x32_bf16 v[100:103], v[24:27], v[104:107], 0
	v_mfma_f32_16x16x32_bf16 v[104:107], v[16:19], v[112:115], 0
	v_mfma_f32_16x16x32_bf16 v[16:19], v[16:19], v[120:123], 0
	v_mfma_f32_16x16x32_bf16 v[60:63], v[20:23], v[108:111], v[60:63]
	v_mfma_f32_16x16x32_bf16 v[100:103], v[28:31], v[108:111], v[100:103]
	v_mfma_f32_16x16x32_bf16 v[104:107], v[20:23], v[116:119], v[104:107]
	v_mfma_f32_16x16x32_bf16 v[108:111], v[24:27], v[112:115], 0
	v_mfma_f32_16x16x32_bf16 v[16:19], v[20:23], v[124:127], v[16:19]
	v_mfma_f32_16x16x32_bf16 v[20:23], v[24:27], v[120:123], 0
	v_mfma_f32_16x16x32_bf16 v[108:111], v[28:31], v[116:119], v[108:111]
	v_mfma_f32_16x16x32_bf16 v[20:23], v[28:31], v[124:127], v[20:23]
	s_barrier
	s_setprio 0
	s_add_i32 s71, 0, 0x18000
	s_add_i32 s69, 0, 0x1c000
	v_add_u32_e32 v196, s71, v134
	v_add_u32_e32 v198, s69, v134
	ds_read_b128 v[24:27], v196
	ds_read_b128 v[28:31], v196 offset:1024
	ds_read_b128 v[112:115], v196 offset:2048
	ds_read_b128 v[116:119], v196 offset:3072
	ds_read_b128 v[120:123], v198
	ds_read_b128 v[124:127], v198 offset:1024
	ds_read_b128 v[160:163], v198 offset:2048
	ds_read_b128 v[164:167], v198 offset:3072
	s_add_u32 s56, s30, 0x10100
	s_addc_u32 s57, s31, 0
	s_mov_b32 m0, s29
	ds_read_b128 v[168:171], v135 offset:32768
	ds_read_b128 v[172:175], v135 offset:33792
	ds_read_b128 v[176:179], v135 offset:34816
	ds_read_b128 v[180:183], v135 offset:35840
	ds_read_b128 v[184:187], v135 offset:36864
	ds_read_b128 v[188:191], v135 offset:37888
	ds_read_b128 v[192:195], v135 offset:38912
	ds_read_b128 v[200:203], v135 offset:39936
	s_nop 0
	global_load_lds_dwordx4 v133, s[56:57]
	s_mov_b32 m0, s47
	s_nop 0
	global_load_lds_dwordx4 v131, s[56:57]
	s_nop 0
	s_nop 0
	s_nop 0
	s_nop 0
	s_nop 0
	s_nop 0
	s_nop 0
	s_nop 0
	s_nop 0
	s_waitcnt vmcnt(8)
	s_waitcnt lgkmcnt(0)
	s_setprio 1
	s_barrier
	v_mfma_f32_16x16x32_bf16 v[64:67], v[24:27], v[168:171], v[64:67]
	v_mfma_f32_16x16x32_bf16 v[64:67], v[28:31], v[172:175], v[64:67]
	v_mfma_f32_16x16x32_bf16 v[68:71], v[112:115], v[168:171], v[68:71]
	v_mfma_f32_16x16x32_bf16 v[68:71], v[116:119], v[172:175], v[68:71]
	v_mfma_f32_16x16x32_bf16 v[72:75], v[24:27], v[176:179], v[72:75]
	v_mfma_f32_16x16x32_bf16 v[72:75], v[28:31], v[180:183], v[72:75]
	v_mfma_f32_16x16x32_bf16 v[76:79], v[112:115], v[176:179], v[76:79]
	v_mfma_f32_16x16x32_bf16 v[76:79], v[116:119], v[180:183], v[76:79]
	v_mfma_f32_16x16x32_bf16 v[80:83], v[24:27], v[184:187], v[80:83]
	v_mfma_f32_16x16x32_bf16 v[80:83], v[28:31], v[188:191], v[80:83]
	v_mfma_f32_16x16x32_bf16 v[84:87], v[112:115], v[184:187], v[84:87]
	v_mfma_f32_16x16x32_bf16 v[84:87], v[116:119], v[188:191], v[84:87]
	v_mfma_f32_16x16x32_bf16 v[88:91], v[24:27], v[192:195], v[88:91]
	v_mfma_f32_16x16x32_bf16 v[88:91], v[28:31], v[200:203], v[88:91]
	v_mfma_f32_16x16x32_bf16 v[92:95], v[112:115], v[192:195], v[92:95]
	v_mfma_f32_16x16x32_bf16 v[92:95], v[116:119], v[200:203], v[92:95]
	v_mfma_f32_16x16x32_bf16 v[96:99], v[120:123], v[168:171], v[96:99]
	v_mfma_f32_16x16x32_bf16 v[96:99], v[124:127], v[172:175], v[96:99]
	v_mfma_f32_16x16x32_bf16 v[32:35], v[160:163], v[168:171], v[32:35]
	v_mfma_f32_16x16x32_bf16 v[32:35], v[164:167], v[172:175], v[32:35]
	v_mfma_f32_16x16x32_bf16 v[36:39], v[120:123], v[176:179], v[36:39]
	v_mfma_f32_16x16x32_bf16 v[36:39], v[124:127], v[180:183], v[36:39]
	v_mfma_f32_16x16x32_bf16 v[40:43], v[160:163], v[176:179], v[40:43]
	v_mfma_f32_16x16x32_bf16 v[40:43], v[164:167], v[180:183], v[40:43]
	v_mfma_f32_16x16x32_bf16 v[44:47], v[120:123], v[184:187], v[44:47]
	v_mfma_f32_16x16x32_bf16 v[44:47], v[124:127], v[188:191], v[44:47]
	v_mfma_f32_16x16x32_bf16 v[48:51], v[160:163], v[184:187], v[48:51]
	v_mfma_f32_16x16x32_bf16 v[48:51], v[164:167], v[188:191], v[48:51]
	v_mfma_f32_16x16x32_bf16 v[52:55], v[120:123], v[192:195], v[52:55]
	v_mfma_f32_16x16x32_bf16 v[52:55], v[124:127], v[200:203], v[52:55]
	v_mfma_f32_16x16x32_bf16 v[56:59], v[160:163], v[192:195], v[56:59]
	v_mfma_f32_16x16x32_bf16 v[56:59], v[164:167], v[200:203], v[56:59]
	s_barrier
	s_setprio 0
	s_add_u32 s74, s36, 0x180
	s_addc_u32 s75, s37, 0
	s_add_i32 s71, s71, s97
	s_add_i32 s56, s71, 0x2000
	s_mov_b32 m0, s71
	s_add_u32 s36, s36, 0x80180
	ds_read_b128 v[168:171], v135 offset:49152
	ds_read_b128 v[172:175], v135 offset:50176
	ds_read_b128 v[176:179], v135 offset:51200
	ds_read_b128 v[180:183], v135 offset:52224
	ds_read_b128 v[184:187], v135 offset:53248
	ds_read_b128 v[188:191], v135 offset:54272
	ds_read_b128 v[192:195], v135 offset:55296
	ds_read_b128 v[200:203], v135 offset:56320
	s_addc_u32 s37, s37, 0
	global_load_lds_dwordx4 v132, s[74:75]
	s_mov_b32 m0, s56
	s_add_i32 s57, s69, s97
	s_add_i32 s69, s57, 0x2000
	global_load_lds_dwordx4 v130, s[74:75]
	s_mov_b32 m0, s57
	s_nop 0
	global_load_lds_dwordx4 v132, s[36:37]
	s_mov_b32 m0, s69
	s_nop 0
	global_load_lds_dwordx4 v130, s[36:37]
	s_mov_b32 m0, s48
	s_nop 0
	global_load_lds_dwordx4 v133, s[80:81]
	s_mov_b32 m0, s49
	s_nop 0
	global_load_lds_dwordx4 v131, s[80:81]
	s_nop 0
	s_nop 0
	s_nop 0
	s_nop 0
	s_nop 0
	s_nop 0
	s_nop 0
	s_nop 0
	s_waitcnt vmcnt(8)
	s_waitcnt lgkmcnt(0)
	s_setprio 1
	s_barrier
	v_mfma_f32_16x16x32_bf16 v[0:3], v[24:27], v[192:195], v[0:3]
	v_mfma_f32_16x16x32_bf16 v[0:3], v[28:31], v[200:203], v[0:3]
	v_mfma_f32_16x16x32_bf16 v[4:7], v[112:115], v[192:195], v[4:7]
	v_mfma_f32_16x16x32_bf16 v[4:7], v[116:119], v[200:203], v[4:7]
	v_mfma_f32_16x16x32_bf16 v[136:139], v[24:27], v[168:171], v[136:139]
	v_mfma_f32_16x16x32_bf16 v[136:139], v[28:31], v[172:175], v[136:139]
	v_mfma_f32_16x16x32_bf16 v[140:143], v[112:115], v[168:171], v[140:143]
	v_mfma_f32_16x16x32_bf16 v[140:143], v[116:119], v[172:175], v[140:143]
	v_mfma_f32_16x16x32_bf16 v[144:147], v[24:27], v[176:179], v[144:147]
	v_mfma_f32_16x16x32_bf16 v[144:147], v[28:31], v[180:183], v[144:147]
	v_mfma_f32_16x16x32_bf16 v[148:151], v[112:115], v[176:179], v[148:151]
	v_mfma_f32_16x16x32_bf16 v[148:151], v[116:119], v[180:183], v[148:151]
	v_mfma_f32_16x16x32_bf16 v[152:155], v[24:27], v[184:187], v[152:155]
	v_mfma_f32_16x16x32_bf16 v[152:155], v[28:31], v[188:191], v[152:155]
	v_mfma_f32_16x16x32_bf16 v[156:159], v[112:115], v[184:187], v[156:159]
	v_mfma_f32_16x16x32_bf16 v[156:159], v[116:119], v[188:191], v[156:159]
	v_mfma_f32_16x16x32_bf16 v[8:11], v[120:123], v[168:171], v[8:11]
	v_mfma_f32_16x16x32_bf16 v[12:15], v[160:163], v[168:171], v[12:15]
	v_mfma_f32_16x16x32_bf16 v[24:27], v[120:123], v[176:179], v[60:63]
	v_mfma_f32_16x16x32_bf16 v[28:31], v[160:163], v[176:179], v[100:103]
	v_mfma_f32_16x16x32_bf16 v[60:63], v[120:123], v[184:187], v[104:107]
	v_mfma_f32_16x16x32_bf16 v[100:103], v[160:163], v[184:187], v[108:111]
	v_mfma_f32_16x16x32_bf16 v[16:19], v[120:123], v[192:195], v[16:19]
	v_mfma_f32_16x16x32_bf16 v[20:23], v[160:163], v[192:195], v[20:23]
	v_mfma_f32_16x16x32_bf16 v[8:11], v[124:127], v[172:175], v[8:11]
	v_mfma_f32_16x16x32_bf16 v[12:15], v[164:167], v[172:175], v[12:15]
	v_mfma_f32_16x16x32_bf16 v[24:27], v[124:127], v[180:183], v[24:27]
	v_mfma_f32_16x16x32_bf16 v[28:31], v[164:167], v[180:183], v[28:31]
	v_mfma_f32_16x16x32_bf16 v[60:63], v[124:127], v[188:191], v[60:63]
	v_mfma_f32_16x16x32_bf16 v[100:103], v[164:167], v[188:191], v[100:103]
	v_mfma_f32_16x16x32_bf16 v[16:19], v[124:127], v[200:203], v[16:19]
	v_mfma_f32_16x16x32_bf16 v[20:23], v[164:167], v[200:203], v[20:23]
	s_barrier
	s_setprio 0
	ds_read_b128 v[104:107], v128
	ds_read_b128 v[108:111], v128 offset:1024
	ds_read_b128 v[112:115], v128 offset:2048
	ds_read_b128 v[116:119], v128 offset:3072
	ds_read_b128 v[120:123], v129
	ds_read_b128 v[124:127], v129 offset:1024
	ds_read_b128 v[160:163], v129 offset:2048
	ds_read_b128 v[164:167], v129 offset:3072
	s_add_u32 s36, s38, 0x80
	s_addc_u32 s37, s39, 0
	s_add_u32 s30, s30, 0x10180
	s_addc_u32 s31, s31, 0
	s_mov_b32 m0, s5
	ds_read_b128 v[168:171], v135
	ds_read_b128 v[172:175], v135 offset:1024
	ds_read_b128 v[176:179], v135 offset:2048
	ds_read_b128 v[180:183], v135 offset:3072
	ds_read_b128 v[184:187], v135 offset:4096
	ds_read_b128 v[188:191], v135 offset:5120
	ds_read_b128 v[192:195], v135 offset:6144
	ds_read_b128 v[200:203], v135 offset:7168
	s_nop 0
	global_load_lds_dwordx4 v133, s[30:31]
	s_mov_b32 m0, s11
	s_nop 0
	global_load_lds_dwordx4 v131, s[30:31]
	s_nop 0
	s_nop 0
	s_nop 0
	s_nop 0
	s_nop 0
	s_nop 0
	s_nop 0
	s_nop 0
	s_nop 0
	s_nop 0
	s_nop 0
	s_nop 0
	s_waitcnt vmcnt(8)
	s_waitcnt lgkmcnt(0)
	s_setprio 1
	s_barrier
	v_mfma_f32_16x16x32_bf16 v[64:67], v[104:107], v[168:171], v[64:67]
	v_mfma_f32_16x16x32_bf16 v[64:67], v[108:111], v[172:175], v[64:67]
	v_mfma_f32_16x16x32_bf16 v[68:71], v[112:115], v[168:171], v[68:71]
	v_mfma_f32_16x16x32_bf16 v[68:71], v[116:119], v[172:175], v[68:71]
	v_mfma_f32_16x16x32_bf16 v[72:75], v[104:107], v[176:179], v[72:75]
	v_mfma_f32_16x16x32_bf16 v[72:75], v[108:111], v[180:183], v[72:75]
	v_mfma_f32_16x16x32_bf16 v[76:79], v[112:115], v[176:179], v[76:79]
	v_mfma_f32_16x16x32_bf16 v[76:79], v[116:119], v[180:183], v[76:79]
	v_mfma_f32_16x16x32_bf16 v[80:83], v[104:107], v[184:187], v[80:83]
	v_mfma_f32_16x16x32_bf16 v[80:83], v[108:111], v[188:191], v[80:83]
	v_mfma_f32_16x16x32_bf16 v[84:87], v[112:115], v[184:187], v[84:87]
	v_mfma_f32_16x16x32_bf16 v[84:87], v[116:119], v[188:191], v[84:87]
	v_mfma_f32_16x16x32_bf16 v[88:91], v[104:107], v[192:195], v[88:91]
	v_mfma_f32_16x16x32_bf16 v[88:91], v[108:111], v[200:203], v[88:91]
	v_mfma_f32_16x16x32_bf16 v[92:95], v[112:115], v[192:195], v[92:95]
	v_mfma_f32_16x16x32_bf16 v[92:95], v[116:119], v[200:203], v[92:95]
	v_mfma_f32_16x16x32_bf16 v[32:35], v[160:163], v[168:171], v[32:35]
	v_mfma_f32_16x16x32_bf16 v[96:99], v[120:123], v[168:171], v[96:99]
	v_mfma_f32_16x16x32_bf16 v[168:171], v[164:167], v[172:175], v[32:35]
	v_mfma_f32_16x16x32_bf16 v[32:35], v[120:123], v[176:179], v[36:39]
	v_mfma_f32_16x16x32_bf16 v[36:39], v[124:127], v[180:183], v[32:35]
	v_mfma_f32_16x16x32_bf16 v[32:35], v[160:163], v[176:179], v[40:43]
	v_mfma_f32_16x16x32_bf16 v[204:207], v[124:127], v[172:175], v[96:99]
	v_mfma_f32_16x16x32_bf16 v[172:175], v[164:167], v[180:183], v[32:35]
	v_mfma_f32_16x16x32_bf16 v[32:35], v[120:123], v[184:187], v[44:47]
	v_mfma_f32_16x16x32_bf16 v[44:47], v[124:127], v[188:191], v[32:35]
	v_mfma_f32_16x16x32_bf16 v[32:35], v[160:163], v[184:187], v[48:51]
	v_mfma_f32_16x16x32_bf16 v[48:51], v[164:167], v[188:191], v[32:35]
	v_mfma_f32_16x16x32_bf16 v[32:35], v[120:123], v[192:195], v[52:55]
	v_mfma_f32_16x16x32_bf16 v[52:55], v[124:127], v[200:203], v[32:35]
	v_mfma_f32_16x16x32_bf16 v[32:35], v[160:163], v[192:195], v[56:59]
	v_mfma_f32_16x16x32_bf16 v[56:59], v[164:167], v[200:203], v[32:35]
	s_barrier
	s_setprio 0
	s_mov_b32 m0, s70
	s_mov_b64 s[30:31], s[34:35]
	s_nop 2
	ds_read_b128 v[32:35], v135 offset:16384
	ds_read_b128 v[40:43], v135 offset:17408
	ds_read_b128 v[96:99], v135 offset:18432
	ds_read_b128 v[176:179], v135 offset:19456
	ds_read_b128 v[180:183], v135 offset:20480
	ds_read_b128 v[184:187], v135 offset:21504
	ds_read_b128 v[188:191], v135 offset:22528
	ds_read_b128 v[192:195], v135 offset:23552
	s_nop 0
	global_load_lds_dwordx4 v132, s[30:31]
	s_mov_b32 m0, s4
	s_add_u32 s4, s34, 0x80000
	s_addc_u32 s5, s35, 0
	global_load_lds_dwordx4 v130, s[30:31]
	s_mov_b32 m0, s13
	s_nop 0
	global_load_lds_dwordx4 v132, s[4:5]
	s_mov_b32 m0, s15
	s_nop 0
	global_load_lds_dwordx4 v130, s[4:5]
	s_mov_b64 s[4:5], s[38:39]
	s_mov_b32 m0, s25
	s_nop 0
	global_load_lds_dwordx4 v133, s[4:5]
	s_mov_b32 m0, s27
	s_nop 0
	global_load_lds_dwordx4 v131, s[4:5]
	s_nop 0
	s_nop 0
	s_nop 0
	s_nop 0
	s_nop 0
	s_nop 0
	s_nop 0
	s_nop 0
	s_nop 0
	s_nop 0
	s_nop 0
	s_nop 0
	s_nop 0
	s_waitcnt vmcnt(8)
	s_waitcnt lgkmcnt(0)
	s_setprio 1
	s_barrier
	v_mfma_f32_16x16x32_bf16 v[0:3], v[104:107], v[188:191], v[0:3]
	v_mfma_f32_16x16x32_bf16 v[0:3], v[108:111], v[192:195], v[0:3]
	v_mfma_f32_16x16x32_bf16 v[4:7], v[112:115], v[188:191], v[4:7]
	v_mfma_f32_16x16x32_bf16 v[4:7], v[116:119], v[192:195], v[4:7]
	v_mfma_f32_16x16x32_bf16 v[136:139], v[104:107], v[32:35], v[136:139]
	v_mfma_f32_16x16x32_bf16 v[136:139], v[108:111], v[40:43], v[136:139]
	v_mfma_f32_16x16x32_bf16 v[140:143], v[112:115], v[32:35], v[140:143]
	v_mfma_f32_16x16x32_bf16 v[140:143], v[116:119], v[40:43], v[140:143]
	v_mfma_f32_16x16x32_bf16 v[144:147], v[104:107], v[96:99], v[144:147]
	v_mfma_f32_16x16x32_bf16 v[144:147], v[108:111], v[176:179], v[144:147]
	v_mfma_f32_16x16x32_bf16 v[148:151], v[112:115], v[96:99], v[148:151]
	v_mfma_f32_16x16x32_bf16 v[148:151], v[116:119], v[176:179], v[148:151]
	v_mfma_f32_16x16x32_bf16 v[152:155], v[104:107], v[180:183], v[152:155]
	v_mfma_f32_16x16x32_bf16 v[152:155], v[108:111], v[184:187], v[152:155]
	v_mfma_f32_16x16x32_bf16 v[156:159], v[112:115], v[180:183], v[156:159]
	v_mfma_f32_16x16x32_bf16 v[156:159], v[116:119], v[184:187], v[156:159]
	v_mfma_f32_16x16x32_bf16 v[12:15], v[160:163], v[32:35], v[12:15]
	v_mfma_f32_16x16x32_bf16 v[200:203], v[164:167], v[40:43], v[12:15]
	v_mfma_f32_16x16x32_bf16 v[12:15], v[120:123], v[96:99], v[24:27]
	v_mfma_f32_16x16x32_bf16 v[24:27], v[124:127], v[176:179], v[12:15]
	v_mfma_f32_16x16x32_bf16 v[12:15], v[160:163], v[96:99], v[28:31]
	v_mfma_f32_16x16x32_bf16 v[176:179], v[164:167], v[176:179], v[12:15]
	v_mfma_f32_16x16x32_bf16 v[12:15], v[120:123], v[180:183], v[60:63]
	v_mfma_f32_16x16x32_bf16 v[208:211], v[124:127], v[184:187], v[12:15]
	v_mfma_f32_16x16x32_bf16 v[12:15], v[160:163], v[180:183], v[100:103]
	v_mfma_f32_16x16x32_bf16 v[8:11], v[120:123], v[32:35], v[8:11]
	v_mfma_f32_16x16x32_bf16 v[180:183], v[164:167], v[184:187], v[12:15]
	v_mfma_f32_16x16x32_bf16 v[12:15], v[120:123], v[188:191], v[16:19]
	v_mfma_f32_16x16x32_bf16 v[8:11], v[124:127], v[40:43], v[8:11]
	v_mfma_f32_16x16x32_bf16 v[184:187], v[124:127], v[192:195], v[12:15]
	v_mfma_f32_16x16x32_bf16 v[12:15], v[160:163], v[188:191], v[20:23]
	v_mfma_f32_16x16x32_bf16 v[160:163], v[164:167], v[192:195], v[12:15]
	s_barrier
	s_setprio 0
	s_nop 4
	ds_read_b128 v[12:15], v196
	ds_read_b128 v[16:19], v196 offset:1024
	ds_read_b128 v[164:167], v196 offset:2048
	ds_read_b128 v[188:191], v196 offset:3072
	ds_read_b128 v[192:195], v198
	ds_read_b128 v[220:223], v198 offset:1024
	ds_read_b128 v[224:227], v198 offset:2048
	ds_read_b128 v[228:231], v198 offset:3072
	s_add_u32 s4, s38, 0x10000
	s_addc_u32 s5, s39, 0
	s_mov_b32 m0, s29
	ds_read_b128 v[20:23], v135 offset:32768
	ds_read_b128 v[28:31], v135 offset:33792
	ds_read_b128 v[60:63], v135 offset:34816
	ds_read_b128 v[100:103], v135 offset:35840
	ds_read_b128 v[232:235], v135 offset:36864
	ds_read_b128 v[236:239], v135 offset:37888
	ds_read_b128 v[240:243], v135 offset:38912
	ds_read_b128 v[244:247], v135 offset:39936
	s_nop 0
	global_load_lds_dwordx4 v133, s[4:5]
	s_mov_b32 m0, s47
	s_nop 0
	global_load_lds_dwordx4 v131, s[4:5]
	s_nop 0
	s_nop 0
	s_nop 0
	s_nop 0
	s_nop 0
	s_nop 0
	s_nop 0
	s_nop 0
	s_nop 0
	s_nop 0
	s_nop 0
	s_nop 0
	s_nop 0
	s_nop 0
	s_waitcnt vmcnt(8)
	s_waitcnt lgkmcnt(0)
	s_setprio 1
	s_barrier
	v_mfma_f32_16x16x32_bf16 v[32:35], v[12:15], v[20:23], v[64:67]
	v_mfma_f32_16x16x32_bf16 v[120:123], v[16:19], v[28:31], v[32:35]
	v_mfma_f32_16x16x32_bf16 v[32:35], v[164:167], v[20:23], v[68:71]
	v_mfma_f32_16x16x32_bf16 v[112:115], v[188:191], v[28:31], v[32:35]
	v_mfma_f32_16x16x32_bf16 v[32:35], v[12:15], v[60:63], v[72:75]
	v_mfma_f32_16x16x32_bf16 v[104:107], v[16:19], v[100:103], v[32:35]
	v_mfma_f32_16x16x32_bf16 v[32:35], v[164:167], v[60:63], v[76:79]
	v_mfma_f32_16x16x32_bf16 v[96:99], v[188:191], v[100:103], v[32:35]
	v_mfma_f32_16x16x32_bf16 v[32:35], v[12:15], v[232:235], v[80:83]
	v_mfma_f32_16x16x32_bf16 v[72:75], v[16:19], v[236:239], v[32:35]
	v_mfma_f32_16x16x32_bf16 v[32:35], v[164:167], v[232:235], v[84:87]
	v_mfma_f32_16x16x32_bf16 v[64:67], v[188:191], v[236:239], v[32:35]
	v_mfma_f32_16x16x32_bf16 v[32:35], v[12:15], v[240:243], v[88:91]
	v_mfma_f32_16x16x32_bf16 v[40:43], v[16:19], v[244:247], v[32:35]
	v_mfma_f32_16x16x32_bf16 v[32:35], v[164:167], v[240:243], v[92:95]
	v_mfma_f32_16x16x32_bf16 v[32:35], v[188:191], v[244:247], v[32:35]
	v_mfma_f32_16x16x32_bf16 v[68:71], v[192:195], v[20:23], v[204:207]
	v_mfma_f32_16x16x32_bf16 v[20:23], v[224:227], v[20:23], v[168:171]
	v_mfma_f32_16x16x32_bf16 v[116:119], v[228:231], v[28:31], v[20:23]
	v_mfma_f32_16x16x32_bf16 v[20:23], v[192:195], v[60:63], v[36:39]
	v_mfma_f32_16x16x32_bf16 v[108:111], v[220:223], v[100:103], v[20:23]
	v_mfma_f32_16x16x32_bf16 v[20:23], v[224:227], v[60:63], v[172:175]
	v_mfma_f32_16x16x32_bf16 v[100:103], v[228:231], v[100:103], v[20:23]
	v_mfma_f32_16x16x32_bf16 v[20:23], v[192:195], v[232:235], v[44:47]
	v_mfma_f32_16x16x32_bf16 v[76:79], v[220:223], v[236:239], v[20:23]
	v_mfma_f32_16x16x32_bf16 v[20:23], v[224:227], v[232:235], v[48:51]
	v_mfma_f32_16x16x32_bf16 v[124:127], v[220:223], v[28:31], v[68:71]
	v_mfma_f32_16x16x32_bf16 v[68:71], v[228:231], v[236:239], v[20:23]
	v_mfma_f32_16x16x32_bf16 v[20:23], v[192:195], v[240:243], v[52:55]
	v_mfma_f32_16x16x32_bf16 v[44:47], v[220:223], v[244:247], v[20:23]
	v_mfma_f32_16x16x32_bf16 v[20:23], v[224:227], v[240:243], v[56:59]
	v_mfma_f32_16x16x32_bf16 v[36:39], v[228:231], v[244:247], v[20:23]
	s_barrier
	s_setprio 0
	s_add_u32 s4, s34, 0x80
	s_mov_b32 m0, s71
	s_addc_u32 s5, s35, 0
	ds_read_b128 v[48:51], v135 offset:49152
	ds_read_b128 v[56:59], v135 offset:50176
	ds_read_b128 v[168:171], v135 offset:51200
	ds_read_b128 v[172:175], v135 offset:52224
	ds_read_b128 v[204:207], v135 offset:53248
	ds_read_b128 v[232:235], v135 offset:54272
	ds_read_b128 v[236:239], v135 offset:55296
	ds_read_b128 v[240:243], v135 offset:56320
	s_nop 0
	global_load_lds_dwordx4 v132, s[4:5]
	s_mov_b32 m0, s56
	s_nop 0
	global_load_lds_dwordx4 v130, s[4:5]
	s_add_u32 s4, s34, 0x80080
	s_addc_u32 s5, s35, 0
	s_mov_b32 m0, s57
	s_nop 0
	global_load_lds_dwordx4 v132, s[4:5]
	s_mov_b32 m0, s69
	s_nop 0
	global_load_lds_dwordx4 v130, s[4:5]
	s_mov_b32 m0, s48
	s_nop 0
	global_load_lds_dwordx4 v133, s[36:37]
	s_mov_b32 m0, s49
	s_nop 0
	global_load_lds_dwordx4 v131, s[36:37]
	s_nop 0
	s_nop 0
	s_nop 0
	s_nop 0
	s_nop 0
	s_nop 0
	s_nop 0
	s_nop 0
	s_nop 0
	s_nop 0
	s_nop 0
	s_nop 0
	s_waitcnt vmcnt(8)
	s_waitcnt lgkmcnt(0)
	s_setprio 1
	s_barrier
	v_mfma_f32_16x16x32_bf16 v[20:23], v[12:15], v[48:51], v[136:139]
	v_mfma_f32_16x16x32_bf16 v[92:95], v[16:19], v[56:59], v[20:23]
	v_mfma_f32_16x16x32_bf16 v[20:23], v[164:167], v[48:51], v[140:143]
	v_mfma_f32_16x16x32_bf16 v[84:87], v[188:191], v[56:59], v[20:23]
	v_mfma_f32_16x16x32_bf16 v[20:23], v[12:15], v[168:171], v[144:147]
	v_mfma_f32_16x16x32_bf16 v[60:63], v[16:19], v[172:175], v[20:23]
	v_mfma_f32_16x16x32_bf16 v[20:23], v[164:167], v[168:171], v[148:151]
	v_mfma_f32_16x16x32_bf16 v[52:55], v[188:191], v[172:175], v[20:23]
	v_mfma_f32_16x16x32_bf16 v[20:23], v[12:15], v[204:207], v[152:155]
	v_mfma_f32_16x16x32_bf16 v[0:3], v[12:15], v[236:239], v[0:3]
	v_mfma_f32_16x16x32_bf16 v[28:31], v[16:19], v[232:235], v[20:23]
	v_mfma_f32_16x16x32_bf16 v[20:23], v[164:167], v[204:207], v[156:159]
	v_mfma_f32_16x16x32_bf16 v[12:15], v[16:19], v[240:243], v[0:3]
	v_mfma_f32_16x16x32_bf16 v[0:3], v[164:167], v[236:239], v[4:7]
	v_mfma_f32_16x16x32_bf16 v[20:23], v[188:191], v[232:235], v[20:23]
	v_mfma_f32_16x16x32_bf16 v[4:7], v[188:191], v[240:243], v[0:3]
	v_mfma_f32_16x16x32_bf16 v[0:3], v[192:195], v[48:51], v[8:11]
	v_mfma_f32_16x16x32_bf16 v[88:91], v[220:223], v[56:59], v[0:3]
	v_mfma_f32_16x16x32_bf16 v[0:3], v[224:227], v[48:51], v[200:203]
	v_mfma_f32_16x16x32_bf16 v[80:83], v[228:231], v[56:59], v[0:3]
	v_mfma_f32_16x16x32_bf16 v[0:3], v[192:195], v[168:171], v[24:27]
	v_mfma_f32_16x16x32_bf16 v[56:59], v[220:223], v[172:175], v[0:3]
	v_mfma_f32_16x16x32_bf16 v[0:3], v[224:227], v[168:171], v[176:179]
	v_mfma_f32_16x16x32_bf16 v[48:51], v[228:231], v[172:175], v[0:3]
	v_mfma_f32_16x16x32_bf16 v[0:3], v[192:195], v[204:207], v[208:211]
	v_mfma_f32_16x16x32_bf16 v[24:27], v[220:223], v[232:235], v[0:3]
	v_mfma_f32_16x16x32_bf16 v[0:3], v[224:227], v[204:207], v[180:183]
	v_mfma_f32_16x16x32_bf16 v[16:19], v[228:231], v[232:235], v[0:3]
	v_mfma_f32_16x16x32_bf16 v[0:3], v[192:195], v[236:239], v[184:187]
	v_mfma_f32_16x16x32_bf16 v[8:11], v[220:223], v[240:243], v[0:3]
	v_mfma_f32_16x16x32_bf16 v[0:3], v[224:227], v[236:239], v[160:163]
	v_mfma_f32_16x16x32_bf16 v[0:3], v[228:231], v[240:243], v[0:3]
	s_barrier
	s_setprio 0
	s_andn2_b64 vcc, exec, s[60:61]
	s_cbranch_vccnz .LBB0_315
	s_barrier

.LBB0_380:
	s_cmp_eq_u32 s15, 28
	s_cselect_b32 s36, s20, s4
	s_cselect_b32 s37, s21, s5
	s_cselect_b32 s34, s26, s11
	s_cselect_b32 s35, s27, s13
	s_add_u32 s30, s36, 0x80
	s_addc_u32 s31, s37, 0
	s_add_i32 s17, 0, 0x10000
	v_add_u32_e32 v128, s17, v134
	s_add_i32 s69, 0, 0x14000
	ds_read_b128 v[136:139], v128
	ds_read_b128 v[140:143], v128 offset:1024
	ds_read_b128 v[144:147], v128 offset:2048
	ds_read_b128 v[148:151], v128 offset:3072
	v_add_u32_e32 v128, s69, v134
	ds_read_b128 v[152:155], v128
	ds_read_b128 v[156:159], v128 offset:1024
	ds_read_b128 v[160:163], v128 offset:2048
	ds_read_b128 v[164:167], v128 offset:3072
	s_mov_b64 s[70:71], s[28:29]
	s_add_i32 m0, s23, 0xc000
	ds_read_b128 v[168:171], v135
	ds_read_b128 v[172:175], v135 offset:1024
	ds_read_b128 v[176:179], v135 offset:2048
	ds_read_b128 v[180:183], v135 offset:3072
	ds_read_b128 v[184:187], v135 offset:4096
	ds_read_b128 v[188:191], v135 offset:5120
	ds_read_b128 v[192:195], v135 offset:6144
	ds_read_b128 v[200:203], v135 offset:7168
	s_nop 0
	global_load_lds_dwordx4 v133, s[70:71]
	s_add_i32 m0, s23, 0xe000
	s_nop 0
	global_load_lds_dwordx4 v131, s[70:71]
	s_nop 0
	s_nop 0
	s_nop 0
	s_nop 0
	s_nop 0
	s_nop 0
	s_nop 0
	s_nop 0
	s_nop 0
	s_nop 0
	s_nop 0
	s_waitcnt vmcnt(8)
	s_waitcnt lgkmcnt(0)
	s_setprio 1
	s_barrier
	v_mfma_f32_16x16x32_bf16 v[124:127], v[136:139], v[168:171], v[124:127]
	v_mfma_f32_16x16x32_bf16 v[124:127], v[140:143], v[172:175], v[124:127]
	v_mfma_f32_16x16x32_bf16 v[120:123], v[144:147], v[168:171], v[120:123]
	v_mfma_f32_16x16x32_bf16 v[120:123], v[148:151], v[172:175], v[120:123]
	v_mfma_f32_16x16x32_bf16 v[116:119], v[136:139], v[176:179], v[116:119]
	v_mfma_f32_16x16x32_bf16 v[116:119], v[140:143], v[180:183], v[116:119]
	v_mfma_f32_16x16x32_bf16 v[108:111], v[144:147], v[176:179], v[108:111]
	v_mfma_f32_16x16x32_bf16 v[108:111], v[148:151], v[180:183], v[108:111]
	v_mfma_f32_16x16x32_bf16 v[100:103], v[136:139], v[184:187], v[100:103]
	v_mfma_f32_16x16x32_bf16 v[100:103], v[140:143], v[188:191], v[100:103]
	v_mfma_f32_16x16x32_bf16 v[92:95], v[144:147], v[184:187], v[92:95]
	v_mfma_f32_16x16x32_bf16 v[92:95], v[148:151], v[188:191], v[92:95]
	v_mfma_f32_16x16x32_bf16 v[84:87], v[136:139], v[192:195], v[84:87]
	v_mfma_f32_16x16x32_bf16 v[84:87], v[140:143], v[200:203], v[84:87]
	v_mfma_f32_16x16x32_bf16 v[76:79], v[144:147], v[192:195], v[76:79]
	v_mfma_f32_16x16x32_bf16 v[76:79], v[148:151], v[200:203], v[76:79]
	v_mfma_f32_16x16x32_bf16 v[112:115], v[152:155], v[168:171], v[112:115]
	v_mfma_f32_16x16x32_bf16 v[112:115], v[156:159], v[172:175], v[112:115]
	v_mfma_f32_16x16x32_bf16 v[104:107], v[160:163], v[168:171], v[104:107]
	v_mfma_f32_16x16x32_bf16 v[104:107], v[164:167], v[172:175], v[104:107]
	v_mfma_f32_16x16x32_bf16 v[96:99], v[152:155], v[176:179], v[96:99]
	v_mfma_f32_16x16x32_bf16 v[96:99], v[156:159], v[180:183], v[96:99]
	v_mfma_f32_16x16x32_bf16 v[88:91], v[160:163], v[176:179], v[88:91]
	v_mfma_f32_16x16x32_bf16 v[88:91], v[164:167], v[180:183], v[88:91]
	v_mfma_f32_16x16x32_bf16 v[80:83], v[152:155], v[184:187], v[80:83]
	v_mfma_f32_16x16x32_bf16 v[80:83], v[156:159], v[188:191], v[80:83]
	v_mfma_f32_16x16x32_bf16 v[72:75], v[160:163], v[184:187], v[72:75]
	v_mfma_f32_16x16x32_bf16 v[72:75], v[164:167], v[188:191], v[72:75]
	v_mfma_f32_16x16x32_bf16 v[68:71], v[152:155], v[192:195], v[68:71]
	v_mfma_f32_16x16x32_bf16 v[68:71], v[156:159], v[200:203], v[68:71]
	v_mfma_f32_16x16x32_bf16 v[64:67], v[160:163], v[192:195], v[64:67]
	v_mfma_f32_16x16x32_bf16 v[64:67], v[164:167], v[200:203], v[64:67]
	s_barrier
	s_setprio 0
	s_add_i32 s17, s17, s97
	s_mov_b64 s[70:71], s[34:35]
	s_mov_b32 m0, s17
	ds_read_b128 v[168:171], v135 offset:16384
	ds_read_b128 v[172:175], v135 offset:17408
	ds_read_b128 v[176:179], v135 offset:18432
	ds_read_b128 v[180:183], v135 offset:19456
	ds_read_b128 v[184:187], v135 offset:20480
	ds_read_b128 v[188:191], v135 offset:21504
	ds_read_b128 v[192:195], v135 offset:22528
	ds_read_b128 v[200:203], v135 offset:23552
	s_nop 0
	global_load_lds_dwordx4 v132, s[70:71]
	s_add_i32 m0, s17, 0x2000
	s_nop 0
	global_load_lds_dwordx4 v130, s[70:71]
	s_add_u32 s70, s34, 0x200000
	s_addc_u32 s71, s35, 0
	s_add_i32 s17, s69, s97
	s_mov_b32 m0, s17
	s_nop 0
	global_load_lds_dwordx4 v132, s[70:71]
	s_add_i32 m0, s17, 0x2000
	s_nop 0
	global_load_lds_dwordx4 v130, s[70:71]
	s_mov_b64 s[70:71], s[36:37]
	s_mov_b32 m0, s23
	s_nop 0
	global_load_lds_dwordx4 v133, s[70:71]
	s_mov_b32 m0, s25
	s_nop 0
	global_load_lds_dwordx4 v131, s[70:71]
	s_nop 0
	s_nop 0
	s_nop 0
	s_nop 0
	s_nop 0
	s_nop 0
	s_nop 0
	s_nop 0
	s_nop 0
	s_waitcnt vmcnt(8)
	s_waitcnt lgkmcnt(0)
	s_setprio 1
	s_barrier
	v_mfma_f32_16x16x32_bf16 v[60:63], v[136:139], v[168:171], v[60:63]
	v_mfma_f32_16x16x32_bf16 v[60:63], v[140:143], v[172:175], v[60:63]
	v_mfma_f32_16x16x32_bf16 v[56:59], v[144:147], v[168:171], v[56:59]
	v_mfma_f32_16x16x32_bf16 v[56:59], v[148:151], v[172:175], v[56:59]
	v_mfma_f32_16x16x32_bf16 v[52:55], v[136:139], v[176:179], v[52:55]
	v_mfma_f32_16x16x32_bf16 v[52:55], v[140:143], v[180:183], v[52:55]
	v_mfma_f32_16x16x32_bf16 v[44:47], v[144:147], v[176:179], v[44:47]
	v_mfma_f32_16x16x32_bf16 v[44:47], v[148:151], v[180:183], v[44:47]
	v_mfma_f32_16x16x32_bf16 v[36:39], v[136:139], v[184:187], v[36:39]
	v_mfma_f32_16x16x32_bf16 v[36:39], v[140:143], v[188:191], v[36:39]
	v_mfma_f32_16x16x32_bf16 v[28:31], v[144:147], v[184:187], v[28:31]
	v_mfma_f32_16x16x32_bf16 v[28:31], v[148:151], v[188:191], v[28:31]
	v_mfma_f32_16x16x32_bf16 v[20:23], v[136:139], v[192:195], v[20:23]
	v_mfma_f32_16x16x32_bf16 v[20:23], v[140:143], v[200:203], v[20:23]
	v_mfma_f32_16x16x32_bf16 v[12:15], v[144:147], v[192:195], v[12:15]
	v_mfma_f32_16x16x32_bf16 v[12:15], v[148:151], v[200:203], v[12:15]
	v_mfma_f32_16x16x32_bf16 v[48:51], v[152:155], v[168:171], v[48:51]
	v_mfma_f32_16x16x32_bf16 v[48:51], v[156:159], v[172:175], v[48:51]
	v_mfma_f32_16x16x32_bf16 v[40:43], v[160:163], v[168:171], v[40:43]
	v_mfma_f32_16x16x32_bf16 v[40:43], v[164:167], v[172:175], v[40:43]
	v_mfma_f32_16x16x32_bf16 v[32:35], v[152:155], v[176:179], v[32:35]
	v_mfma_f32_16x16x32_bf16 v[32:35], v[156:159], v[180:183], v[32:35]
	v_mfma_f32_16x16x32_bf16 v[24:27], v[160:163], v[176:179], v[24:27]
	v_mfma_f32_16x16x32_bf16 v[24:27], v[164:167], v[180:183], v[24:27]
	v_mfma_f32_16x16x32_bf16 v[16:19], v[152:155], v[184:187], v[16:19]
	v_mfma_f32_16x16x32_bf16 v[16:19], v[156:159], v[188:191], v[16:19]
	v_mfma_f32_16x16x32_bf16 v[8:11], v[160:163], v[184:187], v[8:11]
	v_mfma_f32_16x16x32_bf16 v[8:11], v[164:167], v[188:191], v[8:11]
	v_mfma_f32_16x16x32_bf16 v[4:7], v[152:155], v[192:195], v[4:7]
	v_mfma_f32_16x16x32_bf16 v[4:7], v[156:159], v[200:203], v[4:7]
	v_mfma_f32_16x16x32_bf16 v[0:3], v[160:163], v[192:195], v[0:3]
	v_mfma_f32_16x16x32_bf16 v[0:3], v[164:167], v[200:203], v[0:3]
	s_barrier
	s_setprio 0
	s_add_i32 s17, 0, 0x18000
	v_add_u32_e32 v128, s17, v134
	s_add_i32 s69, 0, 0x1c000
	ds_read_b128 v[136:139], v128
	ds_read_b128 v[140:143], v128 offset:1024
	ds_read_b128 v[144:147], v128 offset:2048
	ds_read_b128 v[148:151], v128 offset:3072
	v_add_u32_e32 v128, s69, v134
	ds_read_b128 v[152:155], v128
	ds_read_b128 v[156:159], v128 offset:1024
	ds_read_b128 v[160:163], v128 offset:2048
	ds_read_b128 v[164:167], v128 offset:3072
	s_add_u32 s36, s36, 0x80000
	s_addc_u32 s37, s37, 0
	s_mov_b32 m0, s46
	ds_read_b128 v[168:171], v135 offset:32768
	ds_read_b128 v[172:175], v135 offset:33792
	ds_read_b128 v[176:179], v135 offset:34816
	ds_read_b128 v[180:183], v135 offset:35840
	ds_read_b128 v[184:187], v135 offset:36864
	ds_read_b128 v[188:191], v135 offset:37888
	ds_read_b128 v[192:195], v135 offset:38912
	ds_read_b128 v[200:203], v135 offset:39936
	s_nop 0
	global_load_lds_dwordx4 v133, s[36:37]
	s_mov_b32 m0, s47
	s_nop 0
	global_load_lds_dwordx4 v131, s[36:37]
	s_nop 0
	s_nop 0
	s_nop 0
	s_nop 0
	s_nop 0
	s_nop 0
	s_nop 0
	s_nop 0
	s_nop 0
	s_waitcnt vmcnt(8)
	s_waitcnt lgkmcnt(0)
	s_setprio 1
	s_barrier
	v_mfma_f32_16x16x32_bf16 v[124:127], v[136:139], v[168:171], v[124:127]
	v_mfma_f32_16x16x32_bf16 v[124:127], v[140:143], v[172:175], v[124:127]
	v_mfma_f32_16x16x32_bf16 v[120:123], v[144:147], v[168:171], v[120:123]
	v_mfma_f32_16x16x32_bf16 v[120:123], v[148:151], v[172:175], v[120:123]
	v_mfma_f32_16x16x32_bf16 v[116:119], v[136:139], v[176:179], v[116:119]
	v_mfma_f32_16x16x32_bf16 v[116:119], v[140:143], v[180:183], v[116:119]
	v_mfma_f32_16x16x32_bf16 v[108:111], v[144:147], v[176:179], v[108:111]
	v_mfma_f32_16x16x32_bf16 v[108:111], v[148:151], v[180:183], v[108:111]
	v_mfma_f32_16x16x32_bf16 v[100:103], v[136:139], v[184:187], v[100:103]
	v_mfma_f32_16x16x32_bf16 v[100:103], v[140:143], v[188:191], v[100:103]
	v_mfma_f32_16x16x32_bf16 v[92:95], v[144:147], v[184:187], v[92:95]
	v_mfma_f32_16x16x32_bf16 v[92:95], v[148:151], v[188:191], v[92:95]
	v_mfma_f32_16x16x32_bf16 v[84:87], v[136:139], v[192:195], v[84:87]
	v_mfma_f32_16x16x32_bf16 v[84:87], v[140:143], v[200:203], v[84:87]
	v_mfma_f32_16x16x32_bf16 v[76:79], v[144:147], v[192:195], v[76:79]
	v_mfma_f32_16x16x32_bf16 v[76:79], v[148:151], v[200:203], v[76:79]
	v_mfma_f32_16x16x32_bf16 v[112:115], v[152:155], v[168:171], v[112:115]
	v_mfma_f32_16x16x32_bf16 v[112:115], v[156:159], v[172:175], v[112:115]
	v_mfma_f32_16x16x32_bf16 v[104:107], v[160:163], v[168:171], v[104:107]
	v_mfma_f32_16x16x32_bf16 v[104:107], v[164:167], v[172:175], v[104:107]
	v_mfma_f32_16x16x32_bf16 v[96:99], v[152:155], v[176:179], v[96:99]
	v_mfma_f32_16x16x32_bf16 v[96:99], v[156:159], v[180:183], v[96:99]
	v_mfma_f32_16x16x32_bf16 v[88:91], v[160:163], v[176:179], v[88:91]
	v_mfma_f32_16x16x32_bf16 v[88:91], v[164:167], v[180:183], v[88:91]
	v_mfma_f32_16x16x32_bf16 v[80:83], v[152:155], v[184:187], v[80:83]
	v_mfma_f32_16x16x32_bf16 v[80:83], v[156:159], v[188:191], v[80:83]
	v_mfma_f32_16x16x32_bf16 v[72:75], v[160:163], v[184:187], v[72:75]
	v_mfma_f32_16x16x32_bf16 v[72:75], v[164:167], v[188:191], v[72:75]
	v_mfma_f32_16x16x32_bf16 v[68:71], v[152:155], v[192:195], v[68:71]
	v_mfma_f32_16x16x32_bf16 v[68:71], v[156:159], v[200:203], v[68:71]
	v_mfma_f32_16x16x32_bf16 v[64:67], v[160:163], v[192:195], v[64:67]
	v_mfma_f32_16x16x32_bf16 v[64:67], v[164:167], v[200:203], v[64:67]
	s_barrier
	s_setprio 0
	s_add_u32 s36, s34, 0x80
	s_addc_u32 s37, s35, 0
	s_add_i32 s17, s17, s97
	s_mov_b32 m0, s17
	ds_read_b128 v[168:171], v135 offset:49152
	ds_read_b128 v[172:175], v135 offset:50176
	ds_read_b128 v[176:179], v135 offset:51200
	ds_read_b128 v[180:183], v135 offset:52224
	ds_read_b128 v[184:187], v135 offset:53248
	ds_read_b128 v[188:191], v135 offset:54272
	ds_read_b128 v[192:195], v135 offset:55296
	ds_read_b128 v[200:203], v135 offset:56320
	s_nop 0
	global_load_lds_dwordx4 v132, s[36:37]
	s_add_i32 m0, s17, 0x2000
	s_add_u32 s34, s34, 0x200080
	s_addc_u32 s35, s35, 0
	s_add_i32 s17, s69, s97
	s_nop 0
	global_load_lds_dwordx4 v130, s[36:37]
	s_mov_b32 m0, s17
	s_nop 0
	global_load_lds_dwordx4 v132, s[34:35]
	s_add_i32 m0, s17, 0x2000
	s_nop 0
	global_load_lds_dwordx4 v130, s[34:35]
	s_mov_b32 m0, s56
	s_nop 0
	global_load_lds_dwordx4 v133, s[30:31]
	s_mov_b32 m0, s57
	s_nop 0
	global_load_lds_dwordx4 v131, s[30:31]
	s_nop 0
	s_nop 0
	s_nop 0
	s_nop 0
	s_nop 0
	s_nop 0
	s_nop 0
	s_nop 0
	s_waitcnt vmcnt(8)
	s_waitcnt lgkmcnt(0)
	s_setprio 1
	s_barrier
	v_mfma_f32_16x16x32_bf16 v[60:63], v[136:139], v[168:171], v[60:63]
	v_mfma_f32_16x16x32_bf16 v[60:63], v[140:143], v[172:175], v[60:63]
	v_mfma_f32_16x16x32_bf16 v[56:59], v[144:147], v[168:171], v[56:59]
	v_mfma_f32_16x16x32_bf16 v[56:59], v[148:151], v[172:175], v[56:59]
	v_mfma_f32_16x16x32_bf16 v[52:55], v[136:139], v[176:179], v[52:55]
	v_mfma_f32_16x16x32_bf16 v[52:55], v[140:143], v[180:183], v[52:55]
	v_mfma_f32_16x16x32_bf16 v[44:47], v[144:147], v[176:179], v[44:47]
	v_mfma_f32_16x16x32_bf16 v[44:47], v[148:151], v[180:183], v[44:47]
	v_mfma_f32_16x16x32_bf16 v[36:39], v[136:139], v[184:187], v[36:39]
	v_mfma_f32_16x16x32_bf16 v[36:39], v[140:143], v[188:191], v[36:39]
	v_mfma_f32_16x16x32_bf16 v[28:31], v[144:147], v[184:187], v[28:31]
	v_mfma_f32_16x16x32_bf16 v[28:31], v[148:151], v[188:191], v[28:31]
	v_mfma_f32_16x16x32_bf16 v[20:23], v[136:139], v[192:195], v[20:23]
	v_mfma_f32_16x16x32_bf16 v[20:23], v[140:143], v[200:203], v[20:23]
	v_mfma_f32_16x16x32_bf16 v[12:15], v[144:147], v[192:195], v[12:15]
	v_mfma_f32_16x16x32_bf16 v[12:15], v[148:151], v[200:203], v[12:15]
	v_mfma_f32_16x16x32_bf16 v[48:51], v[152:155], v[168:171], v[48:51]
	v_mfma_f32_16x16x32_bf16 v[48:51], v[156:159], v[172:175], v[48:51]
	v_mfma_f32_16x16x32_bf16 v[40:43], v[160:163], v[168:171], v[40:43]
	v_mfma_f32_16x16x32_bf16 v[40:43], v[164:167], v[172:175], v[40:43]
	v_mfma_f32_16x16x32_bf16 v[32:35], v[152:155], v[176:179], v[32:35]
	v_mfma_f32_16x16x32_bf16 v[32:35], v[156:159], v[180:183], v[32:35]
	v_mfma_f32_16x16x32_bf16 v[24:27], v[160:163], v[176:179], v[24:27]
	v_mfma_f32_16x16x32_bf16 v[24:27], v[164:167], v[180:183], v[24:27]
	v_mfma_f32_16x16x32_bf16 v[16:19], v[152:155], v[184:187], v[16:19]
	v_mfma_f32_16x16x32_bf16 v[16:19], v[156:159], v[188:191], v[16:19]
	v_mfma_f32_16x16x32_bf16 v[8:11], v[160:163], v[184:187], v[8:11]
	v_mfma_f32_16x16x32_bf16 v[8:11], v[164:167], v[188:191], v[8:11]
	v_mfma_f32_16x16x32_bf16 v[4:7], v[152:155], v[192:195], v[4:7]
	v_mfma_f32_16x16x32_bf16 v[4:7], v[156:159], v[200:203], v[4:7]
	v_mfma_f32_16x16x32_bf16 v[0:3], v[160:163], v[192:195], v[0:3]
	v_mfma_f32_16x16x32_bf16 v[0:3], v[164:167], v[200:203], v[0:3]
	s_barrier
	s_setprio 0
	s_add_i32 s15, s15, 2
	s_add_u32 s4, s4, 0x100
	s_addc_u32 s5, s5, 0
	s_add_u32 s11, s11, 0x100
	s_addc_u32 s13, s13, 0
	s_add_u32 s28, s28, 0x100
	s_addc_u32 s29, s29, 0
	s_cmp_gt_u32 s15, 29
	s_cbranch_scc0 .LBB0_380
	s_and_b64 vcc, exec, s[60:61]
	s_cbranch_vccz .LBB0_383
	s_barrier

.LBB0_397:
	s_cmp_eq_u32 s69, 4
	s_cselect_b32 s34, s15, s49
	s_cselect_b32 s35, s5, s56
	s_cselect_b32 s30, s48, s57
	s_cselect_b32 s31, s13, s65
	s_add_u32 s28, s34, 0x80
	s_addc_u32 s29, s35, 0
	s_add_i32 s72, 0, 0x10000
	v_add_u32_e32 v128, s72, v134
	s_add_i32 s74, 0, 0x14000
	ds_read_b128 v[136:139], v128
	ds_read_b128 v[140:143], v128 offset:1024
	ds_read_b128 v[144:147], v128 offset:2048
	ds_read_b128 v[148:151], v128 offset:3072
	v_add_u32_e32 v128, s74, v134
	ds_read_b128 v[152:155], v128
	ds_read_b128 v[156:159], v128 offset:1024
	ds_read_b128 v[160:163], v128 offset:2048
	ds_read_b128 v[164:167], v128 offset:3072
	s_mov_b64 s[70:71], s[26:27]
	s_add_i32 m0, s25, 0xc000
	ds_read_b128 v[168:171], v135
	ds_read_b128 v[172:175], v135 offset:1024
	ds_read_b128 v[176:179], v135 offset:2048
	ds_read_b128 v[180:183], v135 offset:3072
	ds_read_b128 v[184:187], v135 offset:4096
	ds_read_b128 v[188:191], v135 offset:5120
	ds_read_b128 v[192:195], v135 offset:6144
	ds_read_b128 v[200:203], v135 offset:7168
	s_nop 0
	global_load_lds_dwordx4 v133, s[70:71]
	s_add_i32 m0, s25, 0xe000
	s_nop 0
	global_load_lds_dwordx4 v131, s[70:71]
	s_nop 0
	s_nop 0
	s_nop 0
	s_waitcnt vmcnt(8)
	s_waitcnt lgkmcnt(0)
	s_setprio 1
	s_barrier
	v_mfma_f32_16x16x32_bf16 v[124:127], v[136:139], v[168:171], v[124:127]
	v_mfma_f32_16x16x32_bf16 v[124:127], v[140:143], v[172:175], v[124:127]
	v_mfma_f32_16x16x32_bf16 v[120:123], v[144:147], v[168:171], v[120:123]
	v_mfma_f32_16x16x32_bf16 v[120:123], v[148:151], v[172:175], v[120:123]
	v_mfma_f32_16x16x32_bf16 v[116:119], v[136:139], v[176:179], v[116:119]
	v_mfma_f32_16x16x32_bf16 v[116:119], v[140:143], v[180:183], v[116:119]
	v_mfma_f32_16x16x32_bf16 v[108:111], v[144:147], v[176:179], v[108:111]
	v_mfma_f32_16x16x32_bf16 v[108:111], v[148:151], v[180:183], v[108:111]
	v_mfma_f32_16x16x32_bf16 v[100:103], v[136:139], v[184:187], v[100:103]
	v_mfma_f32_16x16x32_bf16 v[100:103], v[140:143], v[188:191], v[100:103]
	v_mfma_f32_16x16x32_bf16 v[92:95], v[144:147], v[184:187], v[92:95]
	v_mfma_f32_16x16x32_bf16 v[92:95], v[148:151], v[188:191], v[92:95]
	v_mfma_f32_16x16x32_bf16 v[84:87], v[136:139], v[192:195], v[84:87]
	v_mfma_f32_16x16x32_bf16 v[84:87], v[140:143], v[200:203], v[84:87]
	v_mfma_f32_16x16x32_bf16 v[76:79], v[144:147], v[192:195], v[76:79]
	v_mfma_f32_16x16x32_bf16 v[76:79], v[148:151], v[200:203], v[76:79]
	v_mfma_f32_16x16x32_bf16 v[112:115], v[152:155], v[168:171], v[112:115]
	v_mfma_f32_16x16x32_bf16 v[112:115], v[156:159], v[172:175], v[112:115]
	v_mfma_f32_16x16x32_bf16 v[104:107], v[160:163], v[168:171], v[104:107]
	v_mfma_f32_16x16x32_bf16 v[104:107], v[164:167], v[172:175], v[104:107]
	v_mfma_f32_16x16x32_bf16 v[96:99], v[152:155], v[176:179], v[96:99]
	v_mfma_f32_16x16x32_bf16 v[96:99], v[156:159], v[180:183], v[96:99]
	v_mfma_f32_16x16x32_bf16 v[88:91], v[160:163], v[176:179], v[88:91]
	v_mfma_f32_16x16x32_bf16 v[88:91], v[164:167], v[180:183], v[88:91]
	v_mfma_f32_16x16x32_bf16 v[80:83], v[152:155], v[184:187], v[80:83]
	v_mfma_f32_16x16x32_bf16 v[80:83], v[156:159], v[188:191], v[80:83]
	v_mfma_f32_16x16x32_bf16 v[72:75], v[160:163], v[184:187], v[72:75]
	v_mfma_f32_16x16x32_bf16 v[72:75], v[164:167], v[188:191], v[72:75]
	v_mfma_f32_16x16x32_bf16 v[68:71], v[152:155], v[192:195], v[68:71]
	v_mfma_f32_16x16x32_bf16 v[68:71], v[156:159], v[200:203], v[68:71]
	v_mfma_f32_16x16x32_bf16 v[64:67], v[160:163], v[192:195], v[64:67]
	v_mfma_f32_16x16x32_bf16 v[64:67], v[164:167], v[200:203], v[64:67]
	s_barrier
	s_setprio 0
	s_add_i32 s72, s72, s97
	s_mov_b64 s[70:71], s[30:31]
	s_mov_b32 m0, s72
	ds_read_b128 v[168:171], v135 offset:16384
	ds_read_b128 v[172:175], v135 offset:17408
	ds_read_b128 v[176:179], v135 offset:18432
	ds_read_b128 v[180:183], v135 offset:19456
	ds_read_b128 v[184:187], v135 offset:20480
	ds_read_b128 v[188:191], v135 offset:21504
	ds_read_b128 v[192:195], v135 offset:22528
	ds_read_b128 v[200:203], v135 offset:23552
	s_nop 0
	global_load_lds_dwordx4 v132, s[70:71]
	s_add_i32 m0, s72, 0x2000
	s_nop 0
	global_load_lds_dwordx4 v130, s[70:71]
	s_add_u32 s70, s30, 0x20000
	s_addc_u32 s71, s31, 0
	s_add_i32 s72, s74, s97
	s_mov_b32 m0, s72
	s_nop 0
	global_load_lds_dwordx4 v132, s[70:71]
	s_add_i32 m0, s72, 0x2000
	s_nop 0
	global_load_lds_dwordx4 v130, s[70:71]
	s_mov_b64 s[70:71], s[34:35]
	s_mov_b32 m0, s25
	s_nop 0
	global_load_lds_dwordx4 v133, s[70:71]
	s_mov_b32 m0, s37
	s_nop 0
	global_load_lds_dwordx4 v131, s[70:71]
	s_nop 0
	s_nop 0
	s_nop 0
	s_nop 0
	s_nop 0
	s_nop 0
	s_nop 0
	s_nop 0
	s_nop 0
	s_waitcnt vmcnt(8)
	s_waitcnt lgkmcnt(0)
	s_setprio 1
	s_barrier
	v_mfma_f32_16x16x32_bf16 v[60:63], v[136:139], v[168:171], v[60:63]
	v_mfma_f32_16x16x32_bf16 v[60:63], v[140:143], v[172:175], v[60:63]
	v_mfma_f32_16x16x32_bf16 v[56:59], v[144:147], v[168:171], v[56:59]
	v_mfma_f32_16x16x32_bf16 v[56:59], v[148:151], v[172:175], v[56:59]
	v_mfma_f32_16x16x32_bf16 v[52:55], v[136:139], v[176:179], v[52:55]
	v_mfma_f32_16x16x32_bf16 v[52:55], v[140:143], v[180:183], v[52:55]
	v_mfma_f32_16x16x32_bf16 v[44:47], v[144:147], v[176:179], v[44:47]
	v_mfma_f32_16x16x32_bf16 v[44:47], v[148:151], v[180:183], v[44:47]
	v_mfma_f32_16x16x32_bf16 v[36:39], v[136:139], v[184:187], v[36:39]
	v_mfma_f32_16x16x32_bf16 v[36:39], v[140:143], v[188:191], v[36:39]
	v_mfma_f32_16x16x32_bf16 v[28:31], v[144:147], v[184:187], v[28:31]
	v_mfma_f32_16x16x32_bf16 v[28:31], v[148:151], v[188:191], v[28:31]
	v_mfma_f32_16x16x32_bf16 v[20:23], v[136:139], v[192:195], v[20:23]
	v_mfma_f32_16x16x32_bf16 v[20:23], v[140:143], v[200:203], v[20:23]
	v_mfma_f32_16x16x32_bf16 v[12:15], v[144:147], v[192:195], v[12:15]
	v_mfma_f32_16x16x32_bf16 v[12:15], v[148:151], v[200:203], v[12:15]
	v_mfma_f32_16x16x32_bf16 v[48:51], v[152:155], v[168:171], v[48:51]
	v_mfma_f32_16x16x32_bf16 v[48:51], v[156:159], v[172:175], v[48:51]
	v_mfma_f32_16x16x32_bf16 v[40:43], v[160:163], v[168:171], v[40:43]
	v_mfma_f32_16x16x32_bf16 v[40:43], v[164:167], v[172:175], v[40:43]
	v_mfma_f32_16x16x32_bf16 v[32:35], v[152:155], v[176:179], v[32:35]
	v_mfma_f32_16x16x32_bf16 v[32:35], v[156:159], v[180:183], v[32:35]
	v_mfma_f32_16x16x32_bf16 v[24:27], v[160:163], v[176:179], v[24:27]
	v_mfma_f32_16x16x32_bf16 v[24:27], v[164:167], v[180:183], v[24:27]
	v_mfma_f32_16x16x32_bf16 v[16:19], v[152:155], v[184:187], v[16:19]
	v_mfma_f32_16x16x32_bf16 v[16:19], v[156:159], v[188:191], v[16:19]
	v_mfma_f32_16x16x32_bf16 v[8:11], v[160:163], v[184:187], v[8:11]
	v_mfma_f32_16x16x32_bf16 v[8:11], v[164:167], v[188:191], v[8:11]
	v_mfma_f32_16x16x32_bf16 v[4:7], v[152:155], v[192:195], v[4:7]
	v_mfma_f32_16x16x32_bf16 v[4:7], v[156:159], v[200:203], v[4:7]
	v_mfma_f32_16x16x32_bf16 v[0:3], v[160:163], v[192:195], v[0:3]
	v_mfma_f32_16x16x32_bf16 v[0:3], v[164:167], v[200:203], v[0:3]
	s_barrier
	s_setprio 0
	s_add_i32 s70, 0, 0x18000
	v_add_u32_e32 v128, s70, v134
	s_add_i32 s71, 0, 0x1c000
	ds_read_b128 v[136:139], v128
	ds_read_b128 v[140:143], v128 offset:1024
	ds_read_b128 v[144:147], v128 offset:2048
	ds_read_b128 v[148:151], v128 offset:3072
	v_add_u32_e32 v128, s71, v134
	ds_read_b128 v[152:155], v128
	ds_read_b128 v[156:159], v128 offset:1024
	ds_read_b128 v[160:163], v128 offset:2048
	ds_read_b128 v[164:167], v128 offset:3072
	s_add_u32 s34, s34, 0x20000
	s_addc_u32 s35, s35, 0
	s_mov_b32 m0, s38
	ds_read_b128 v[168:171], v135 offset:32768
	ds_read_b128 v[172:175], v135 offset:33792
	ds_read_b128 v[176:179], v135 offset:34816
	ds_read_b128 v[180:183], v135 offset:35840
	ds_read_b128 v[184:187], v135 offset:36864
	ds_read_b128 v[188:191], v135 offset:37888
	ds_read_b128 v[192:195], v135 offset:38912
	ds_read_b128 v[200:203], v135 offset:39936
	s_nop 0
	global_load_lds_dwordx4 v133, s[34:35]
	s_mov_b32 m0, s39
	s_nop 0
	global_load_lds_dwordx4 v131, s[34:35]
	s_nop 0
	s_nop 0
	s_nop 0
	s_nop 0
	s_nop 0
	s_nop 0
	s_nop 0
	s_nop 0
	s_nop 0
	s_waitcnt vmcnt(8)
	s_waitcnt lgkmcnt(0)
	s_setprio 1
	s_barrier
	v_mfma_f32_16x16x32_bf16 v[124:127], v[136:139], v[168:171], v[124:127]
	v_mfma_f32_16x16x32_bf16 v[124:127], v[140:143], v[172:175], v[124:127]
	v_mfma_f32_16x16x32_bf16 v[120:123], v[144:147], v[168:171], v[120:123]
	v_mfma_f32_16x16x32_bf16 v[120:123], v[148:151], v[172:175], v[120:123]
	v_mfma_f32_16x16x32_bf16 v[116:119], v[136:139], v[176:179], v[116:119]
	v_mfma_f32_16x16x32_bf16 v[116:119], v[140:143], v[180:183], v[116:119]
	v_mfma_f32_16x16x32_bf16 v[108:111], v[144:147], v[176:179], v[108:111]
	v_mfma_f32_16x16x32_bf16 v[108:111], v[148:151], v[180:183], v[108:111]
	v_mfma_f32_16x16x32_bf16 v[100:103], v[136:139], v[184:187], v[100:103]
	v_mfma_f32_16x16x32_bf16 v[100:103], v[140:143], v[188:191], v[100:103]
	v_mfma_f32_16x16x32_bf16 v[92:95], v[144:147], v[184:187], v[92:95]
	v_mfma_f32_16x16x32_bf16 v[92:95], v[148:151], v[188:191], v[92:95]
	v_mfma_f32_16x16x32_bf16 v[84:87], v[136:139], v[192:195], v[84:87]
	v_mfma_f32_16x16x32_bf16 v[84:87], v[140:143], v[200:203], v[84:87]
	v_mfma_f32_16x16x32_bf16 v[76:79], v[144:147], v[192:195], v[76:79]
	v_mfma_f32_16x16x32_bf16 v[76:79], v[148:151], v[200:203], v[76:79]
	v_mfma_f32_16x16x32_bf16 v[112:115], v[152:155], v[168:171], v[112:115]
	v_mfma_f32_16x16x32_bf16 v[112:115], v[156:159], v[172:175], v[112:115]
	v_mfma_f32_16x16x32_bf16 v[104:107], v[160:163], v[168:171], v[104:107]
	v_mfma_f32_16x16x32_bf16 v[104:107], v[164:167], v[172:175], v[104:107]
	v_mfma_f32_16x16x32_bf16 v[96:99], v[152:155], v[176:179], v[96:99]
	v_mfma_f32_16x16x32_bf16 v[96:99], v[156:159], v[180:183], v[96:99]
	v_mfma_f32_16x16x32_bf16 v[88:91], v[160:163], v[176:179], v[88:91]
	v_mfma_f32_16x16x32_bf16 v[88:91], v[164:167], v[180:183], v[88:91]
	v_mfma_f32_16x16x32_bf16 v[80:83], v[152:155], v[184:187], v[80:83]
	v_mfma_f32_16x16x32_bf16 v[80:83], v[156:159], v[188:191], v[80:83]
	v_mfma_f32_16x16x32_bf16 v[72:75], v[160:163], v[184:187], v[72:75]
	v_mfma_f32_16x16x32_bf16 v[72:75], v[164:167], v[188:191], v[72:75]
	v_mfma_f32_16x16x32_bf16 v[68:71], v[152:155], v[192:195], v[68:71]
	v_mfma_f32_16x16x32_bf16 v[68:71], v[156:159], v[200:203], v[68:71]
	v_mfma_f32_16x16x32_bf16 v[64:67], v[160:163], v[192:195], v[64:67]
	v_mfma_f32_16x16x32_bf16 v[64:67], v[164:167], v[200:203], v[64:67]
	s_barrier
	s_setprio 0
	s_add_u32 s34, s30, 0x80
	s_addc_u32 s35, s31, 0
	s_add_i32 s70, s70, s97
	s_mov_b32 m0, s70
	ds_read_b128 v[168:171], v135 offset:49152
	ds_read_b128 v[172:175], v135 offset:50176
	ds_read_b128 v[176:179], v135 offset:51200
	ds_read_b128 v[180:183], v135 offset:52224
	ds_read_b128 v[184:187], v135 offset:53248
	ds_read_b128 v[188:191], v135 offset:54272
	ds_read_b128 v[192:195], v135 offset:55296
	ds_read_b128 v[200:203], v135 offset:56320
	s_nop 0
	global_load_lds_dwordx4 v132, s[34:35]
	s_add_i32 m0, s70, 0x2000
	s_add_u32 s30, s30, 0x20080
	s_addc_u32 s31, s31, 0
	global_load_lds_dwordx4 v130, s[34:35]
	s_add_i32 s34, s71, s97
	s_mov_b32 m0, s34
	s_nop 0
	global_load_lds_dwordx4 v132, s[30:31]
	s_add_i32 m0, s34, 0x2000
	s_nop 0
	global_load_lds_dwordx4 v130, s[30:31]
	s_mov_b32 m0, s44
	s_nop 0
	global_load_lds_dwordx4 v133, s[28:29]
	s_mov_b32 m0, s46
	s_nop 0
	global_load_lds_dwordx4 v131, s[28:29]
	s_nop 0
	s_nop 0
	s_nop 0
	s_nop 0
	s_nop 0
	s_nop 0
	s_nop 0
	s_nop 0
	s_nop 0
	s_waitcnt vmcnt(8)
	s_waitcnt lgkmcnt(0)
	s_setprio 1
	s_barrier
	v_mfma_f32_16x16x32_bf16 v[60:63], v[136:139], v[168:171], v[60:63]
	v_mfma_f32_16x16x32_bf16 v[60:63], v[140:143], v[172:175], v[60:63]
	v_mfma_f32_16x16x32_bf16 v[56:59], v[144:147], v[168:171], v[56:59]
	v_mfma_f32_16x16x32_bf16 v[56:59], v[148:151], v[172:175], v[56:59]
	v_mfma_f32_16x16x32_bf16 v[52:55], v[136:139], v[176:179], v[52:55]
	v_mfma_f32_16x16x32_bf16 v[52:55], v[140:143], v[180:183], v[52:55]
	v_mfma_f32_16x16x32_bf16 v[44:47], v[144:147], v[176:179], v[44:47]
	v_mfma_f32_16x16x32_bf16 v[44:47], v[148:151], v[180:183], v[44:47]
	v_mfma_f32_16x16x32_bf16 v[36:39], v[136:139], v[184:187], v[36:39]
	v_mfma_f32_16x16x32_bf16 v[36:39], v[140:143], v[188:191], v[36:39]
	v_mfma_f32_16x16x32_bf16 v[28:31], v[144:147], v[184:187], v[28:31]
	v_mfma_f32_16x16x32_bf16 v[28:31], v[148:151], v[188:191], v[28:31]
	v_mfma_f32_16x16x32_bf16 v[20:23], v[136:139], v[192:195], v[20:23]
	v_mfma_f32_16x16x32_bf16 v[20:23], v[140:143], v[200:203], v[20:23]
	v_mfma_f32_16x16x32_bf16 v[12:15], v[144:147], v[192:195], v[12:15]
	v_mfma_f32_16x16x32_bf16 v[12:15], v[148:151], v[200:203], v[12:15]
	v_mfma_f32_16x16x32_bf16 v[48:51], v[152:155], v[168:171], v[48:51]
	v_mfma_f32_16x16x32_bf16 v[48:51], v[156:159], v[172:175], v[48:51]
	v_mfma_f32_16x16x32_bf16 v[40:43], v[160:163], v[168:171], v[40:43]
	v_mfma_f32_16x16x32_bf16 v[40:43], v[164:167], v[172:175], v[40:43]
	v_mfma_f32_16x16x32_bf16 v[32:35], v[152:155], v[176:179], v[32:35]
	v_mfma_f32_16x16x32_bf16 v[32:35], v[156:159], v[180:183], v[32:35]
	v_mfma_f32_16x16x32_bf16 v[24:27], v[160:163], v[176:179], v[24:27]
	v_mfma_f32_16x16x32_bf16 v[24:27], v[164:167], v[180:183], v[24:27]
	v_mfma_f32_16x16x32_bf16 v[16:19], v[152:155], v[184:187], v[16:19]
	v_mfma_f32_16x16x32_bf16 v[16:19], v[156:159], v[188:191], v[16:19]
	v_mfma_f32_16x16x32_bf16 v[8:11], v[160:163], v[184:187], v[8:11]
	v_mfma_f32_16x16x32_bf16 v[8:11], v[164:167], v[188:191], v[8:11]
	v_mfma_f32_16x16x32_bf16 v[4:7], v[152:155], v[192:195], v[4:7]
	v_mfma_f32_16x16x32_bf16 v[4:7], v[156:159], v[200:203], v[4:7]
	v_mfma_f32_16x16x32_bf16 v[0:3], v[160:163], v[192:195], v[0:3]
	v_mfma_f32_16x16x32_bf16 v[0:3], v[164:167], v[200:203], v[0:3]
	s_barrier
	s_setprio 0
	s_add_i32 s69, s69, 2
	s_add_u32 s49, s49, 0x100
	s_addc_u32 s56, s56, 0
	s_add_u32 s57, s57, 0x100
	s_addc_u32 s65, s65, 0
	s_add_u32 s26, s26, 0x100
	s_addc_u32 s27, s27, 0
	s_cmp_gt_u32 s69, 5
	s_cbranch_scc0 .LBB0_397
	s_and_b64 vcc, exec, s[60:61]
	s_cbranch_vccz .LBB0_400
	s_barrier

.LBB0_527:
	s_cmp_eq_u32 s85, 28
	s_cselect_b32 s56, s5, s39
	s_cselect_b32 s57, s4, s69
	s_cselect_b32 s86, s37, s72
	s_cselect_b32 s87, s11, s74
	s_add_u32 s12, s56, 0x80
	s_addc_u32 s13, s57, 0
	s_add_i32 vcc_lo, 0, 0x10000
	s_add_i32 vcc_hi, 0, 0x14000
	v_add_u32_e32 v136, vcc_lo, v184
	v_add_u32_e32 v156, vcc_hi, v184
	ds_read_b128 v[104:107], v136
	ds_read_b128 v[108:111], v136 offset:1024
	ds_read_b128 v[132:135], v136 offset:2048
	ds_read_b128 v[136:139], v136 offset:3072
	ds_read_b128 v[144:147], v156
	ds_read_b128 v[148:151], v156 offset:1024
	ds_read_b128 v[152:155], v156 offset:2048
	ds_read_b128 v[156:159], v156 offset:3072
	s_mov_b64 s[8:9], s[16:17]
	s_add_i32 m0, s89, 0xc000
	ds_read_b128 v[160:163], v185
	ds_read_b128 v[164:167], v185 offset:1024
	ds_read_b128 v[168:171], v185 offset:2048
	ds_read_b128 v[172:175], v185 offset:3072
	ds_read_b128 v[186:189], v185 offset:4096
	ds_read_b128 v[190:193], v185 offset:5120
	ds_read_b128 v[200:203], v185 offset:6144
	ds_read_b128 v[204:207], v185 offset:7168
	s_nop 0
	global_load_lds_dwordx4 v179, s[8:9]
	s_add_i32 m0, s89, 0xe000
	s_nop 0
	global_load_lds_dwordx4 v182, s[8:9]
	s_nop 0
	s_nop 0
	s_nop 0
	s_nop 0
	s_nop 0
	s_nop 0
	s_nop 0
	s_nop 0
	s_nop 0
	s_nop 0
	s_nop 0
	s_waitcnt vmcnt(8)
	s_waitcnt lgkmcnt(0)
	s_setprio 1
	s_barrier
	v_mfma_f32_16x16x32_bf16 v[140:143], v[104:107], v[160:163], v[140:143]
	v_mfma_f32_16x16x32_bf16 v[140:143], v[108:111], v[164:167], v[140:143]
	v_mfma_f32_16x16x32_bf16 v[128:131], v[132:135], v[160:163], v[128:131]
	v_mfma_f32_16x16x32_bf16 v[128:131], v[136:139], v[164:167], v[128:131]
	v_mfma_f32_16x16x32_bf16 v[124:127], v[104:107], v[168:171], v[124:127]
	v_mfma_f32_16x16x32_bf16 v[124:127], v[108:111], v[172:175], v[124:127]
	v_mfma_f32_16x16x32_bf16 v[112:115], v[132:135], v[168:171], v[112:115]
	v_mfma_f32_16x16x32_bf16 v[112:115], v[136:139], v[172:175], v[112:115]
	v_mfma_f32_16x16x32_bf16 v[96:99], v[104:107], v[186:189], v[96:99]
	v_mfma_f32_16x16x32_bf16 v[96:99], v[108:111], v[190:193], v[96:99]
	v_mfma_f32_16x16x32_bf16 v[88:91], v[132:135], v[186:189], v[88:91]
	v_mfma_f32_16x16x32_bf16 v[88:91], v[136:139], v[190:193], v[88:91]
	v_mfma_f32_16x16x32_bf16 v[84:87], v[104:107], v[200:203], v[84:87]
	v_mfma_f32_16x16x32_bf16 v[84:87], v[108:111], v[204:207], v[84:87]
	v_mfma_f32_16x16x32_bf16 v[72:75], v[132:135], v[200:203], v[72:75]
	v_mfma_f32_16x16x32_bf16 v[72:75], v[136:139], v[204:207], v[72:75]
	v_mfma_f32_16x16x32_bf16 v[120:123], v[144:147], v[160:163], v[120:123]
	v_mfma_f32_16x16x32_bf16 v[120:123], v[148:151], v[164:167], v[120:123]
	v_mfma_f32_16x16x32_bf16 v[116:119], v[152:155], v[160:163], v[116:119]
	v_mfma_f32_16x16x32_bf16 v[116:119], v[156:159], v[164:167], v[116:119]
	v_mfma_f32_16x16x32_bf16 v[100:103], v[144:147], v[168:171], v[100:103]
	v_mfma_f32_16x16x32_bf16 v[100:103], v[148:151], v[172:175], v[100:103]
	v_mfma_f32_16x16x32_bf16 v[92:95], v[152:155], v[168:171], v[92:95]
	v_mfma_f32_16x16x32_bf16 v[92:95], v[156:159], v[172:175], v[92:95]
	v_mfma_f32_16x16x32_bf16 v[80:83], v[144:147], v[186:189], v[80:83]
	v_mfma_f32_16x16x32_bf16 v[80:83], v[148:151], v[190:193], v[80:83]
	v_mfma_f32_16x16x32_bf16 v[76:79], v[152:155], v[186:189], v[76:79]
	v_mfma_f32_16x16x32_bf16 v[76:79], v[156:159], v[190:193], v[76:79]
	v_mfma_f32_16x16x32_bf16 v[68:71], v[144:147], v[200:203], v[68:71]
	v_mfma_f32_16x16x32_bf16 v[68:71], v[148:151], v[204:207], v[68:71]
	v_mfma_f32_16x16x32_bf16 v[64:67], v[152:155], v[200:203], v[64:67]
	v_mfma_f32_16x16x32_bf16 v[64:67], v[156:159], v[204:207], v[64:67]
	s_barrier
	s_setprio 0
	s_add_i32 vcc_lo, vcc_lo, s97
	s_mov_b64 s[8:9], s[86:87]
	s_mov_b32 m0, vcc_lo
	ds_read_b128 v[160:163], v185 offset:16384
	ds_read_b128 v[164:167], v185 offset:17408
	ds_read_b128 v[168:171], v185 offset:18432
	ds_read_b128 v[172:175], v185 offset:19456
	ds_read_b128 v[186:189], v185 offset:20480
	ds_read_b128 v[190:193], v185 offset:21504
	ds_read_b128 v[200:203], v185 offset:22528
	ds_read_b128 v[204:207], v185 offset:23552
	s_nop 0
	global_load_lds_dwordx4 v181, s[8:9]
	s_add_i32 m0, vcc_lo, 0x2000
	s_nop 0
	global_load_lds_dwordx4 v183, s[8:9]
	s_add_u32 s8, s86, 0x80000
	s_addc_u32 s9, s87, 0
	s_add_i32 vcc_lo, vcc_hi, s97
	s_mov_b32 m0, vcc_lo
	s_nop 0
	global_load_lds_dwordx4 v181, s[8:9]
	s_add_i32 m0, vcc_lo, 0x2000
	s_nop 0
	global_load_lds_dwordx4 v183, s[8:9]
	s_mov_b64 s[8:9], s[56:57]
	s_mov_b32 m0, s89
	s_nop 0
	global_load_lds_dwordx4 v179, s[8:9]
	s_mov_b32 m0, s92
	s_nop 0
	global_load_lds_dwordx4 v182, s[8:9]
	s_nop 0
	s_nop 0
	s_nop 0
	s_nop 0
	s_nop 0
	s_nop 0
	s_nop 0
	s_nop 0
	s_nop 0
	s_waitcnt vmcnt(8)
	s_waitcnt lgkmcnt(0)
	s_setprio 1
	s_barrier
	v_mfma_f32_16x16x32_bf16 v[60:63], v[104:107], v[160:163], v[60:63]
	v_mfma_f32_16x16x32_bf16 v[60:63], v[108:111], v[164:167], v[60:63]
	v_mfma_f32_16x16x32_bf16 v[56:59], v[132:135], v[160:163], v[56:59]
	v_mfma_f32_16x16x32_bf16 v[56:59], v[136:139], v[164:167], v[56:59]
	v_mfma_f32_16x16x32_bf16 v[48:51], v[104:107], v[168:171], v[48:51]
	v_mfma_f32_16x16x32_bf16 v[48:51], v[108:111], v[172:175], v[48:51]
	v_mfma_f32_16x16x32_bf16 v[40:43], v[132:135], v[168:171], v[40:43]
	v_mfma_f32_16x16x32_bf16 v[40:43], v[136:139], v[172:175], v[40:43]
	v_mfma_f32_16x16x32_bf16 v[32:35], v[104:107], v[186:189], v[32:35]
	v_mfma_f32_16x16x32_bf16 v[32:35], v[108:111], v[190:193], v[32:35]
	v_mfma_f32_16x16x32_bf16 v[24:27], v[132:135], v[186:189], v[24:27]
	v_mfma_f32_16x16x32_bf16 v[24:27], v[136:139], v[190:193], v[24:27]
	v_mfma_f32_16x16x32_bf16 v[16:19], v[104:107], v[200:203], v[16:19]
	v_mfma_f32_16x16x32_bf16 v[16:19], v[108:111], v[204:207], v[16:19]
	v_mfma_f32_16x16x32_bf16 v[8:11], v[132:135], v[200:203], v[8:11]
	v_mfma_f32_16x16x32_bf16 v[8:11], v[136:139], v[204:207], v[8:11]
	v_mfma_f32_16x16x32_bf16 v[52:55], v[144:147], v[160:163], v[52:55]
	v_mfma_f32_16x16x32_bf16 v[52:55], v[148:151], v[164:167], v[52:55]
	v_mfma_f32_16x16x32_bf16 v[44:47], v[152:155], v[160:163], v[44:47]
	v_mfma_f32_16x16x32_bf16 v[44:47], v[156:159], v[164:167], v[44:47]
	v_mfma_f32_16x16x32_bf16 v[36:39], v[144:147], v[168:171], v[36:39]
	v_mfma_f32_16x16x32_bf16 v[36:39], v[148:151], v[172:175], v[36:39]
	v_mfma_f32_16x16x32_bf16 v[28:31], v[152:155], v[168:171], v[28:31]
	v_mfma_f32_16x16x32_bf16 v[28:31], v[156:159], v[172:175], v[28:31]
	v_mfma_f32_16x16x32_bf16 v[20:23], v[144:147], v[186:189], v[20:23]
	v_mfma_f32_16x16x32_bf16 v[20:23], v[148:151], v[190:193], v[20:23]
	v_mfma_f32_16x16x32_bf16 v[12:15], v[152:155], v[186:189], v[12:15]
	v_mfma_f32_16x16x32_bf16 v[12:15], v[156:159], v[190:193], v[12:15]
	v_mfma_f32_16x16x32_bf16 v[4:7], v[144:147], v[200:203], v[4:7]
	v_mfma_f32_16x16x32_bf16 v[4:7], v[148:151], v[204:207], v[4:7]
	v_mfma_f32_16x16x32_bf16 v[0:3], v[152:155], v[200:203], v[0:3]
	v_mfma_f32_16x16x32_bf16 v[0:3], v[156:159], v[204:207], v[0:3]
	s_barrier
	s_setprio 0
	s_add_i32 vcc_lo, 0, 0x18000
	s_add_i32 vcc_hi, 0, 0x1c000
	v_add_u32_e32 v136, vcc_lo, v184
	v_add_u32_e32 v156, vcc_hi, v184
	ds_read_b128 v[104:107], v136
	ds_read_b128 v[108:111], v136 offset:1024
	ds_read_b128 v[132:135], v136 offset:2048
	ds_read_b128 v[136:139], v136 offset:3072
	ds_read_b128 v[144:147], v156
	ds_read_b128 v[148:151], v156 offset:1024
	ds_read_b128 v[152:155], v156 offset:2048
	ds_read_b128 v[156:159], v156 offset:3072
	s_add_u32 s8, s56, 0x80000
	s_addc_u32 s9, s57, 0
	s_mov_b32 m0, s93
	ds_read_b128 v[160:163], v185 offset:32768
	ds_read_b128 v[164:167], v185 offset:33792
	ds_read_b128 v[168:171], v185 offset:34816
	ds_read_b128 v[172:175], v185 offset:35840
	ds_read_b128 v[186:189], v185 offset:36864
	ds_read_b128 v[190:193], v185 offset:37888
	ds_read_b128 v[200:203], v185 offset:38912
	ds_read_b128 v[204:207], v185 offset:39936
	s_nop 0
	global_load_lds_dwordx4 v179, s[8:9]
	s_mov_b32 m0, s48
	s_nop 0
	global_load_lds_dwordx4 v182, s[8:9]
	s_nop 0
	s_nop 0
	s_nop 0
	s_nop 0
	s_nop 0
	s_nop 0
	s_nop 0
	s_nop 0
	s_nop 0
	s_waitcnt vmcnt(8)
	s_waitcnt lgkmcnt(0)
	s_setprio 1
	s_barrier
	v_mfma_f32_16x16x32_bf16 v[140:143], v[104:107], v[160:163], v[140:143]
	v_mfma_f32_16x16x32_bf16 v[140:143], v[108:111], v[164:167], v[140:143]
	v_mfma_f32_16x16x32_bf16 v[128:131], v[132:135], v[160:163], v[128:131]
	v_mfma_f32_16x16x32_bf16 v[128:131], v[136:139], v[164:167], v[128:131]
	v_mfma_f32_16x16x32_bf16 v[124:127], v[104:107], v[168:171], v[124:127]
	v_mfma_f32_16x16x32_bf16 v[124:127], v[108:111], v[172:175], v[124:127]
	v_mfma_f32_16x16x32_bf16 v[112:115], v[132:135], v[168:171], v[112:115]
	v_mfma_f32_16x16x32_bf16 v[112:115], v[136:139], v[172:175], v[112:115]
	v_mfma_f32_16x16x32_bf16 v[96:99], v[104:107], v[186:189], v[96:99]
	v_mfma_f32_16x16x32_bf16 v[96:99], v[108:111], v[190:193], v[96:99]
	v_mfma_f32_16x16x32_bf16 v[88:91], v[132:135], v[186:189], v[88:91]
	v_mfma_f32_16x16x32_bf16 v[88:91], v[136:139], v[190:193], v[88:91]
	v_mfma_f32_16x16x32_bf16 v[84:87], v[104:107], v[200:203], v[84:87]
	v_mfma_f32_16x16x32_bf16 v[84:87], v[108:111], v[204:207], v[84:87]
	v_mfma_f32_16x16x32_bf16 v[72:75], v[132:135], v[200:203], v[72:75]
	v_mfma_f32_16x16x32_bf16 v[72:75], v[136:139], v[204:207], v[72:75]
	v_mfma_f32_16x16x32_bf16 v[120:123], v[144:147], v[160:163], v[120:123]
	v_mfma_f32_16x16x32_bf16 v[120:123], v[148:151], v[164:167], v[120:123]
	v_mfma_f32_16x16x32_bf16 v[116:119], v[152:155], v[160:163], v[116:119]
	v_mfma_f32_16x16x32_bf16 v[116:119], v[156:159], v[164:167], v[116:119]
	v_mfma_f32_16x16x32_bf16 v[100:103], v[144:147], v[168:171], v[100:103]
	v_mfma_f32_16x16x32_bf16 v[100:103], v[148:151], v[172:175], v[100:103]
	v_mfma_f32_16x16x32_bf16 v[92:95], v[152:155], v[168:171], v[92:95]
	v_mfma_f32_16x16x32_bf16 v[92:95], v[156:159], v[172:175], v[92:95]
	v_mfma_f32_16x16x32_bf16 v[80:83], v[144:147], v[186:189], v[80:83]
	v_mfma_f32_16x16x32_bf16 v[80:83], v[148:151], v[190:193], v[80:83]
	v_mfma_f32_16x16x32_bf16 v[76:79], v[152:155], v[186:189], v[76:79]
	v_mfma_f32_16x16x32_bf16 v[76:79], v[156:159], v[190:193], v[76:79]
	v_mfma_f32_16x16x32_bf16 v[68:71], v[144:147], v[200:203], v[68:71]
	v_mfma_f32_16x16x32_bf16 v[68:71], v[148:151], v[204:207], v[68:71]
	v_mfma_f32_16x16x32_bf16 v[64:67], v[152:155], v[200:203], v[64:67]
	v_mfma_f32_16x16x32_bf16 v[64:67], v[156:159], v[204:207], v[64:67]
	s_barrier
	s_setprio 0
	s_add_u32 s8, s86, 0x80
	s_addc_u32 s9, s87, 0
	s_add_i32 s56, vcc_lo, s97
	s_mov_b32 m0, s56
	ds_read_b128 v[160:163], v185 offset:49152
	ds_read_b128 v[164:167], v185 offset:50176
	ds_read_b128 v[168:171], v185 offset:51200
	ds_read_b128 v[172:175], v185 offset:52224
	ds_read_b128 v[186:189], v185 offset:53248
	ds_read_b128 v[190:193], v185 offset:54272
	ds_read_b128 v[200:203], v185 offset:55296
	ds_read_b128 v[204:207], v185 offset:56320
	s_nop 0
	global_load_lds_dwordx4 v181, s[8:9]
	s_add_i32 m0, s56, 0x2000
	s_nop 0
	global_load_lds_dwordx4 v183, s[8:9]
	s_add_u32 s8, s86, 0x80080
	s_addc_u32 s9, s87, 0
	s_add_i32 s56, vcc_hi, s97
	s_mov_b32 m0, s56
	s_nop 0
	global_load_lds_dwordx4 v181, s[8:9]
	s_add_i32 m0, s56, 0x2000
	s_nop 0
	global_load_lds_dwordx4 v183, s[8:9]
	s_mov_b32 m0, s46
	s_nop 0
	global_load_lds_dwordx4 v179, s[12:13]
	s_mov_b32 m0, s70
	s_nop 0
	global_load_lds_dwordx4 v182, s[12:13]
	s_nop 0
	s_nop 0
	s_nop 0
	s_nop 0
	s_nop 0
	s_nop 0
	s_nop 0
	s_nop 0
	s_waitcnt vmcnt(8)
	s_waitcnt lgkmcnt(0)
	s_setprio 1
	s_barrier
	v_mfma_f32_16x16x32_bf16 v[60:63], v[104:107], v[160:163], v[60:63]
	v_mfma_f32_16x16x32_bf16 v[60:63], v[108:111], v[164:167], v[60:63]
	v_mfma_f32_16x16x32_bf16 v[56:59], v[132:135], v[160:163], v[56:59]
	v_mfma_f32_16x16x32_bf16 v[56:59], v[136:139], v[164:167], v[56:59]
	v_mfma_f32_16x16x32_bf16 v[48:51], v[104:107], v[168:171], v[48:51]
	v_mfma_f32_16x16x32_bf16 v[48:51], v[108:111], v[172:175], v[48:51]
	v_mfma_f32_16x16x32_bf16 v[40:43], v[132:135], v[168:171], v[40:43]
	v_mfma_f32_16x16x32_bf16 v[40:43], v[136:139], v[172:175], v[40:43]
	v_mfma_f32_16x16x32_bf16 v[32:35], v[104:107], v[186:189], v[32:35]
	v_mfma_f32_16x16x32_bf16 v[32:35], v[108:111], v[190:193], v[32:35]
	v_mfma_f32_16x16x32_bf16 v[24:27], v[132:135], v[186:189], v[24:27]
	v_mfma_f32_16x16x32_bf16 v[24:27], v[136:139], v[190:193], v[24:27]
	v_mfma_f32_16x16x32_bf16 v[16:19], v[104:107], v[200:203], v[16:19]
	v_mfma_f32_16x16x32_bf16 v[16:19], v[108:111], v[204:207], v[16:19]
	v_mfma_f32_16x16x32_bf16 v[8:11], v[132:135], v[200:203], v[8:11]
	v_mfma_f32_16x16x32_bf16 v[8:11], v[136:139], v[204:207], v[8:11]
	v_mfma_f32_16x16x32_bf16 v[52:55], v[144:147], v[160:163], v[52:55]
	v_mfma_f32_16x16x32_bf16 v[52:55], v[148:151], v[164:167], v[52:55]
	v_mfma_f32_16x16x32_bf16 v[44:47], v[152:155], v[160:163], v[44:47]
	v_mfma_f32_16x16x32_bf16 v[44:47], v[156:159], v[164:167], v[44:47]
	v_mfma_f32_16x16x32_bf16 v[36:39], v[144:147], v[168:171], v[36:39]
	v_mfma_f32_16x16x32_bf16 v[36:39], v[148:151], v[172:175], v[36:39]
	v_mfma_f32_16x16x32_bf16 v[28:31], v[152:155], v[168:171], v[28:31]
	v_mfma_f32_16x16x32_bf16 v[28:31], v[156:159], v[172:175], v[28:31]
	v_mfma_f32_16x16x32_bf16 v[20:23], v[144:147], v[186:189], v[20:23]
	v_mfma_f32_16x16x32_bf16 v[20:23], v[148:151], v[190:193], v[20:23]
	v_mfma_f32_16x16x32_bf16 v[12:15], v[152:155], v[186:189], v[12:15]
	v_mfma_f32_16x16x32_bf16 v[12:15], v[156:159], v[190:193], v[12:15]
	v_mfma_f32_16x16x32_bf16 v[4:7], v[144:147], v[200:203], v[4:7]
	v_mfma_f32_16x16x32_bf16 v[4:7], v[148:151], v[204:207], v[4:7]
	v_mfma_f32_16x16x32_bf16 v[0:3], v[152:155], v[200:203], v[0:3]
	v_mfma_f32_16x16x32_bf16 v[0:3], v[156:159], v[204:207], v[0:3]
	s_barrier
	s_setprio 0
	s_add_i32 s85, s85, 2
	s_add_u32 s39, s39, 0x100
	s_addc_u32 s69, s69, 0
	s_add_u32 s72, s72, 0x100
	s_addc_u32 s74, s74, 0
	s_add_u32 s16, s16, 0x100
	s_addc_u32 s17, s17, 0
	s_cmp_gt_u32 s85, 29
	s_cbranch_scc0 .LBB0_527
	s_and_b64 vcc, exec, s[60:61]
	s_cbranch_vccz .LBB0_530
	s_barrier

.LBB0_604:
	s_cmp_eq_u32 s21, 4
	s_cselect_b32 s38, s22, s4
	s_cselect_b32 s39, s23, s5
	s_cselect_b32 s36, s24, s15
	s_cselect_b32 s37, s25, s17
	s_add_u32 s34, s38, 0x80
	s_addc_u32 s35, s39, 0
	s_add_i32 s65, 0, 0x10000
	s_add_i32 s69, 0, 0x14000
	v_add_u32_e32 v132, s65, v154
	v_add_u32_e32 v148, s69, v154
	ds_read_b128 v[112:115], v132
	ds_read_b128 v[120:123], v132 offset:1024
	ds_read_b128 v[128:131], v132 offset:2048
	ds_read_b128 v[132:135], v132 offset:3072
	ds_read_b128 v[144:147], v148
	ds_read_b128 v[156:159], v148 offset:1024
	ds_read_b128 v[160:163], v148 offset:2048
	ds_read_b128 v[164:167], v148 offset:3072
	s_add_u32 s70, s4, 0x7ff80
	s_addc_u32 s71, s5, 0
	s_add_i32 m0, s27, 0xc000
	ds_read_b128 v[168:171], v155
	ds_read_b128 v[172:175], v155 offset:1024
	ds_read_b128 v[176:179], v155 offset:2048
	ds_read_b128 v[180:183], v155 offset:3072
	ds_read_b128 v[184:187], v155 offset:4096
	ds_read_b128 v[188:191], v155 offset:5120
	ds_read_b128 v[192:195], v155 offset:6144
	ds_read_b128 v[200:203], v155 offset:7168
	s_nop 0
	global_load_lds_dwordx4 v151, s[70:71]
	s_add_i32 m0, s27, 0xe000
	s_nop 0
	global_load_lds_dwordx4 v150, s[70:71]
	s_nop 0
	s_nop 0
	s_nop 0
	s_nop 0
	s_waitcnt vmcnt(8)
	s_waitcnt lgkmcnt(0)
	s_setprio 1
	s_barrier
	v_mfma_f32_16x16x32_bf16 v[140:143], v[112:115], v[168:171], v[140:143]
	v_mfma_f32_16x16x32_bf16 v[140:143], v[120:123], v[172:175], v[140:143]
	v_mfma_f32_16x16x32_bf16 v[136:139], v[128:131], v[168:171], v[136:139]
	v_mfma_f32_16x16x32_bf16 v[136:139], v[132:135], v[172:175], v[136:139]
	v_mfma_f32_16x16x32_bf16 v[108:111], v[112:115], v[176:179], v[108:111]
	v_mfma_f32_16x16x32_bf16 v[108:111], v[120:123], v[180:183], v[108:111]
	v_mfma_f32_16x16x32_bf16 v[104:107], v[128:131], v[176:179], v[104:107]
	v_mfma_f32_16x16x32_bf16 v[104:107], v[132:135], v[180:183], v[104:107]
	v_mfma_f32_16x16x32_bf16 v[92:95], v[112:115], v[184:187], v[92:95]
	v_mfma_f32_16x16x32_bf16 v[92:95], v[120:123], v[188:191], v[92:95]
	v_mfma_f32_16x16x32_bf16 v[88:91], v[128:131], v[184:187], v[88:91]
	v_mfma_f32_16x16x32_bf16 v[88:91], v[132:135], v[188:191], v[88:91]
	v_mfma_f32_16x16x32_bf16 v[76:79], v[112:115], v[192:195], v[76:79]
	v_mfma_f32_16x16x32_bf16 v[76:79], v[120:123], v[200:203], v[76:79]
	v_mfma_f32_16x16x32_bf16 v[72:75], v[128:131], v[192:195], v[72:75]
	v_mfma_f32_16x16x32_bf16 v[72:75], v[132:135], v[200:203], v[72:75]
	v_mfma_f32_16x16x32_bf16 v[124:127], v[144:147], v[168:171], v[124:127]
	v_mfma_f32_16x16x32_bf16 v[124:127], v[156:159], v[172:175], v[124:127]
	v_mfma_f32_16x16x32_bf16 v[116:119], v[160:163], v[168:171], v[116:119]
	v_mfma_f32_16x16x32_bf16 v[116:119], v[164:167], v[172:175], v[116:119]
	v_mfma_f32_16x16x32_bf16 v[100:103], v[144:147], v[176:179], v[100:103]
	v_mfma_f32_16x16x32_bf16 v[100:103], v[156:159], v[180:183], v[100:103]
	v_mfma_f32_16x16x32_bf16 v[96:99], v[160:163], v[176:179], v[96:99]
	v_mfma_f32_16x16x32_bf16 v[96:99], v[164:167], v[180:183], v[96:99]
	v_mfma_f32_16x16x32_bf16 v[84:87], v[144:147], v[184:187], v[84:87]
	v_mfma_f32_16x16x32_bf16 v[84:87], v[156:159], v[188:191], v[84:87]
	v_mfma_f32_16x16x32_bf16 v[80:83], v[160:163], v[184:187], v[80:83]
	v_mfma_f32_16x16x32_bf16 v[80:83], v[164:167], v[188:191], v[80:83]
	v_mfma_f32_16x16x32_bf16 v[68:71], v[144:147], v[192:195], v[68:71]
	v_mfma_f32_16x16x32_bf16 v[68:71], v[156:159], v[200:203], v[68:71]
	v_mfma_f32_16x16x32_bf16 v[64:67], v[160:163], v[192:195], v[64:67]
	v_mfma_f32_16x16x32_bf16 v[64:67], v[164:167], v[200:203], v[64:67]
	s_barrier
	s_setprio 0
	s_add_i32 s65, s65, s97
	s_mov_b64 s[70:71], s[36:37]
	s_mov_b32 m0, s65
	ds_read_b128 v[168:171], v155 offset:16384
	ds_read_b128 v[172:175], v155 offset:17408
	ds_read_b128 v[176:179], v155 offset:18432
	ds_read_b128 v[180:183], v155 offset:19456
	ds_read_b128 v[184:187], v155 offset:20480
	ds_read_b128 v[188:191], v155 offset:21504
	ds_read_b128 v[192:195], v155 offset:22528
	ds_read_b128 v[200:203], v155 offset:23552
	s_nop 0
	global_load_lds_dwordx4 v152, s[70:71]
	s_add_i32 m0, s65, 0x2000
	s_nop 0
	global_load_lds_dwordx4 v153, s[70:71]
	s_add_u32 s70, s36, 0x80000
	s_addc_u32 s71, s37, 0
	s_add_i32 s65, s69, s97
	s_mov_b32 m0, s65
	s_nop 0
	global_load_lds_dwordx4 v152, s[70:71]
	s_add_i32 m0, s65, 0x2000
	s_nop 0
	global_load_lds_dwordx4 v153, s[70:71]
	s_mov_b64 s[70:71], s[38:39]
	s_mov_b32 m0, s27
	s_nop 0
	global_load_lds_dwordx4 v151, s[70:71]
	s_mov_b32 m0, s29
	s_nop 0
	global_load_lds_dwordx4 v150, s[70:71]
	s_nop 0
	s_nop 0
	s_nop 0
	s_nop 0
	s_nop 0
	s_nop 0
	s_nop 0
	s_nop 0
	s_nop 0
	s_waitcnt vmcnt(8)
	s_waitcnt lgkmcnt(0)
	s_setprio 1
	s_barrier
	v_mfma_f32_16x16x32_bf16 v[60:63], v[112:115], v[168:171], v[60:63]
	v_mfma_f32_16x16x32_bf16 v[60:63], v[120:123], v[172:175], v[60:63]
	v_mfma_f32_16x16x32_bf16 v[56:59], v[128:131], v[168:171], v[56:59]
	v_mfma_f32_16x16x32_bf16 v[56:59], v[132:135], v[172:175], v[56:59]
	v_mfma_f32_16x16x32_bf16 v[52:55], v[112:115], v[176:179], v[52:55]
	v_mfma_f32_16x16x32_bf16 v[52:55], v[120:123], v[180:183], v[52:55]
	v_mfma_f32_16x16x32_bf16 v[44:47], v[128:131], v[176:179], v[44:47]
	v_mfma_f32_16x16x32_bf16 v[44:47], v[132:135], v[180:183], v[44:47]
	v_mfma_f32_16x16x32_bf16 v[36:39], v[112:115], v[184:187], v[36:39]
	v_mfma_f32_16x16x32_bf16 v[36:39], v[120:123], v[188:191], v[36:39]
	v_mfma_f32_16x16x32_bf16 v[28:31], v[128:131], v[184:187], v[28:31]
	v_mfma_f32_16x16x32_bf16 v[28:31], v[132:135], v[188:191], v[28:31]
	v_mfma_f32_16x16x32_bf16 v[20:23], v[112:115], v[192:195], v[20:23]
	v_mfma_f32_16x16x32_bf16 v[20:23], v[120:123], v[200:203], v[20:23]
	v_mfma_f32_16x16x32_bf16 v[8:11], v[128:131], v[192:195], v[8:11]
	v_mfma_f32_16x16x32_bf16 v[8:11], v[132:135], v[200:203], v[8:11]
	v_mfma_f32_16x16x32_bf16 v[48:51], v[144:147], v[168:171], v[48:51]
	v_mfma_f32_16x16x32_bf16 v[48:51], v[156:159], v[172:175], v[48:51]
	v_mfma_f32_16x16x32_bf16 v[40:43], v[160:163], v[168:171], v[40:43]
	v_mfma_f32_16x16x32_bf16 v[40:43], v[164:167], v[172:175], v[40:43]
	v_mfma_f32_16x16x32_bf16 v[32:35], v[144:147], v[176:179], v[32:35]
	v_mfma_f32_16x16x32_bf16 v[32:35], v[156:159], v[180:183], v[32:35]
	v_mfma_f32_16x16x32_bf16 v[24:27], v[160:163], v[176:179], v[24:27]
	v_mfma_f32_16x16x32_bf16 v[24:27], v[164:167], v[180:183], v[24:27]
	v_mfma_f32_16x16x32_bf16 v[16:19], v[144:147], v[184:187], v[16:19]
	v_mfma_f32_16x16x32_bf16 v[16:19], v[156:159], v[188:191], v[16:19]
	v_mfma_f32_16x16x32_bf16 v[12:15], v[160:163], v[184:187], v[12:15]
	v_mfma_f32_16x16x32_bf16 v[12:15], v[164:167], v[188:191], v[12:15]
	v_mfma_f32_16x16x32_bf16 v[4:7], v[144:147], v[192:195], v[4:7]
	v_mfma_f32_16x16x32_bf16 v[4:7], v[156:159], v[200:203], v[4:7]
	v_mfma_f32_16x16x32_bf16 v[0:3], v[160:163], v[192:195], v[0:3]
	v_mfma_f32_16x16x32_bf16 v[0:3], v[164:167], v[200:203], v[0:3]
	s_barrier
	s_setprio 0
	s_add_i32 s65, 0, 0x18000
	s_add_i32 s69, 0, 0x1c000
	v_add_u32_e32 v132, s65, v154
	v_add_u32_e32 v148, s69, v154
	ds_read_b128 v[112:115], v132
	ds_read_b128 v[120:123], v132 offset:1024
	ds_read_b128 v[128:131], v132 offset:2048
	ds_read_b128 v[132:135], v132 offset:3072
	ds_read_b128 v[144:147], v148
	ds_read_b128 v[156:159], v148 offset:1024
	ds_read_b128 v[160:163], v148 offset:2048
	ds_read_b128 v[164:167], v148 offset:3072
	s_add_u32 s38, s38, 0x80000
	s_addc_u32 s39, s39, 0
	s_mov_b32 m0, s31
	ds_read_b128 v[168:171], v155 offset:32768
	ds_read_b128 v[172:175], v155 offset:33792
	ds_read_b128 v[176:179], v155 offset:34816
	ds_read_b128 v[180:183], v155 offset:35840
	ds_read_b128 v[184:187], v155 offset:36864
	ds_read_b128 v[188:191], v155 offset:37888
	ds_read_b128 v[192:195], v155 offset:38912
	ds_read_b128 v[200:203], v155 offset:39936
	s_nop 0
	global_load_lds_dwordx4 v151, s[38:39]
	s_mov_b32 m0, s48
	s_nop 0
	global_load_lds_dwordx4 v150, s[38:39]
	s_nop 0
	s_nop 0
	s_nop 0
	s_nop 0
	s_nop 0
	s_nop 0
	s_nop 0
	s_nop 0
	s_nop 0
	s_waitcnt vmcnt(8)
	s_waitcnt lgkmcnt(0)
	s_setprio 1
	s_barrier
	v_mfma_f32_16x16x32_bf16 v[140:143], v[112:115], v[168:171], v[140:143]
	v_mfma_f32_16x16x32_bf16 v[140:143], v[120:123], v[172:175], v[140:143]
	v_mfma_f32_16x16x32_bf16 v[136:139], v[128:131], v[168:171], v[136:139]
	v_mfma_f32_16x16x32_bf16 v[136:139], v[132:135], v[172:175], v[136:139]
	v_mfma_f32_16x16x32_bf16 v[108:111], v[112:115], v[176:179], v[108:111]
	v_mfma_f32_16x16x32_bf16 v[108:111], v[120:123], v[180:183], v[108:111]
	v_mfma_f32_16x16x32_bf16 v[104:107], v[128:131], v[176:179], v[104:107]
	v_mfma_f32_16x16x32_bf16 v[104:107], v[132:135], v[180:183], v[104:107]
	v_mfma_f32_16x16x32_bf16 v[92:95], v[112:115], v[184:187], v[92:95]
	v_mfma_f32_16x16x32_bf16 v[92:95], v[120:123], v[188:191], v[92:95]
	v_mfma_f32_16x16x32_bf16 v[88:91], v[128:131], v[184:187], v[88:91]
	v_mfma_f32_16x16x32_bf16 v[88:91], v[132:135], v[188:191], v[88:91]
	v_mfma_f32_16x16x32_bf16 v[76:79], v[112:115], v[192:195], v[76:79]
	v_mfma_f32_16x16x32_bf16 v[76:79], v[120:123], v[200:203], v[76:79]
	v_mfma_f32_16x16x32_bf16 v[72:75], v[128:131], v[192:195], v[72:75]
	v_mfma_f32_16x16x32_bf16 v[72:75], v[132:135], v[200:203], v[72:75]
	v_mfma_f32_16x16x32_bf16 v[124:127], v[144:147], v[168:171], v[124:127]
	v_mfma_f32_16x16x32_bf16 v[124:127], v[156:159], v[172:175], v[124:127]
	v_mfma_f32_16x16x32_bf16 v[116:119], v[160:163], v[168:171], v[116:119]
	v_mfma_f32_16x16x32_bf16 v[116:119], v[164:167], v[172:175], v[116:119]
	v_mfma_f32_16x16x32_bf16 v[100:103], v[144:147], v[176:179], v[100:103]
	v_mfma_f32_16x16x32_bf16 v[100:103], v[156:159], v[180:183], v[100:103]
	v_mfma_f32_16x16x32_bf16 v[96:99], v[160:163], v[176:179], v[96:99]
	v_mfma_f32_16x16x32_bf16 v[96:99], v[164:167], v[180:183], v[96:99]
	v_mfma_f32_16x16x32_bf16 v[84:87], v[144:147], v[184:187], v[84:87]
	v_mfma_f32_16x16x32_bf16 v[84:87], v[156:159], v[188:191], v[84:87]
	v_mfma_f32_16x16x32_bf16 v[80:83], v[160:163], v[184:187], v[80:83]
	v_mfma_f32_16x16x32_bf16 v[80:83], v[164:167], v[188:191], v[80:83]
	v_mfma_f32_16x16x32_bf16 v[68:71], v[144:147], v[192:195], v[68:71]
	v_mfma_f32_16x16x32_bf16 v[68:71], v[156:159], v[200:203], v[68:71]
	v_mfma_f32_16x16x32_bf16 v[64:67], v[160:163], v[192:195], v[64:67]
	v_mfma_f32_16x16x32_bf16 v[64:67], v[164:167], v[200:203], v[64:67]
	s_barrier
	s_setprio 0
	s_add_u32 s38, s36, 0x80
	s_addc_u32 s39, s37, 0
	s_add_i32 s65, s65, s97
	s_mov_b32 m0, s65
	ds_read_b128 v[168:171], v155 offset:49152
	ds_read_b128 v[172:175], v155 offset:50176
	ds_read_b128 v[176:179], v155 offset:51200
	ds_read_b128 v[180:183], v155 offset:52224
	ds_read_b128 v[184:187], v155 offset:53248
	ds_read_b128 v[188:191], v155 offset:54272
	ds_read_b128 v[192:195], v155 offset:55296
	ds_read_b128 v[200:203], v155 offset:56320
	s_nop 0
	global_load_lds_dwordx4 v152, s[38:39]
	s_add_i32 m0, s65, 0x2000
	s_add_u32 s36, s36, 0x80080
	s_addc_u32 s37, s37, 0
	global_load_lds_dwordx4 v153, s[38:39]
	s_add_i32 s38, s69, s97
	s_mov_b32 m0, s38
	s_nop 0
	global_load_lds_dwordx4 v152, s[36:37]
	s_add_i32 m0, s38, 0x2000
	s_nop 0
	global_load_lds_dwordx4 v153, s[36:37]
	s_mov_b32 m0, s49
	s_nop 0
	global_load_lds_dwordx4 v151, s[34:35]
	s_mov_b32 m0, s56
	s_nop 0
	global_load_lds_dwordx4 v150, s[34:35]
	s_nop 0
	s_nop 0
	s_nop 0
	s_nop 0
	s_nop 0
	s_nop 0
	s_nop 0
	s_nop 0
	s_nop 0
	s_waitcnt vmcnt(8)
	s_waitcnt lgkmcnt(0)
	s_setprio 1
	s_barrier
	v_mfma_f32_16x16x32_bf16 v[60:63], v[112:115], v[168:171], v[60:63]
	v_mfma_f32_16x16x32_bf16 v[60:63], v[120:123], v[172:175], v[60:63]
	v_mfma_f32_16x16x32_bf16 v[56:59], v[128:131], v[168:171], v[56:59]
	v_mfma_f32_16x16x32_bf16 v[56:59], v[132:135], v[172:175], v[56:59]
	v_mfma_f32_16x16x32_bf16 v[52:55], v[112:115], v[176:179], v[52:55]
	v_mfma_f32_16x16x32_bf16 v[52:55], v[120:123], v[180:183], v[52:55]
	v_mfma_f32_16x16x32_bf16 v[44:47], v[128:131], v[176:179], v[44:47]
	v_mfma_f32_16x16x32_bf16 v[44:47], v[132:135], v[180:183], v[44:47]
	v_mfma_f32_16x16x32_bf16 v[36:39], v[112:115], v[184:187], v[36:39]
	v_mfma_f32_16x16x32_bf16 v[36:39], v[120:123], v[188:191], v[36:39]
	v_mfma_f32_16x16x32_bf16 v[28:31], v[128:131], v[184:187], v[28:31]
	v_mfma_f32_16x16x32_bf16 v[28:31], v[132:135], v[188:191], v[28:31]
	v_mfma_f32_16x16x32_bf16 v[20:23], v[112:115], v[192:195], v[20:23]
	v_mfma_f32_16x16x32_bf16 v[20:23], v[120:123], v[200:203], v[20:23]
	v_mfma_f32_16x16x32_bf16 v[8:11], v[128:131], v[192:195], v[8:11]
	v_mfma_f32_16x16x32_bf16 v[8:11], v[132:135], v[200:203], v[8:11]
	v_mfma_f32_16x16x32_bf16 v[48:51], v[144:147], v[168:171], v[48:51]
	v_mfma_f32_16x16x32_bf16 v[48:51], v[156:159], v[172:175], v[48:51]
	v_mfma_f32_16x16x32_bf16 v[40:43], v[160:163], v[168:171], v[40:43]
	v_mfma_f32_16x16x32_bf16 v[40:43], v[164:167], v[172:175], v[40:43]
	v_mfma_f32_16x16x32_bf16 v[32:35], v[144:147], v[176:179], v[32:35]
	v_mfma_f32_16x16x32_bf16 v[32:35], v[156:159], v[180:183], v[32:35]
	v_mfma_f32_16x16x32_bf16 v[24:27], v[160:163], v[176:179], v[24:27]
	v_mfma_f32_16x16x32_bf16 v[24:27], v[164:167], v[180:183], v[24:27]
	v_mfma_f32_16x16x32_bf16 v[16:19], v[144:147], v[184:187], v[16:19]
	v_mfma_f32_16x16x32_bf16 v[16:19], v[156:159], v[188:191], v[16:19]
	v_mfma_f32_16x16x32_bf16 v[12:15], v[160:163], v[184:187], v[12:15]
	v_mfma_f32_16x16x32_bf16 v[12:15], v[164:167], v[188:191], v[12:15]
	v_mfma_f32_16x16x32_bf16 v[4:7], v[144:147], v[192:195], v[4:7]
	v_mfma_f32_16x16x32_bf16 v[4:7], v[156:159], v[200:203], v[4:7]
	v_mfma_f32_16x16x32_bf16 v[0:3], v[160:163], v[192:195], v[0:3]
	v_mfma_f32_16x16x32_bf16 v[0:3], v[164:167], v[200:203], v[0:3]
	s_barrier
	s_setprio 0
	s_add_i32 s21, s21, 2
	s_add_u32 s4, s4, 0x100
	s_addc_u32 s5, s5, 0
	s_add_u32 s15, s15, 0x100
	s_addc_u32 s17, s17, 0
	s_cmp_gt_u32 s21, 5
	s_cbranch_scc0 .LBB0_604
	s_and_b64 vcc, exec, s[60:61]
	s_cbranch_vccz .LBB0_607
	s_barrier

.LBB0_676:
	s_add_u32 s30, s28, 0x100
	s_addc_u32 s31, s29, 0
	s_cmp_eq_u32 s69, 28
	s_cselect_b32 s38, s5, s30
	s_cselect_b32 s39, s4, s31
	s_cselect_b32 s36, s17, s21
	s_cselect_b32 s37, s13, s27
	s_add_u32 s34, s38, 0x80
	s_addc_u32 s35, s39, 0
	s_add_i32 s74, 0, 0x10000
	s_add_i32 s84, 0, 0x14000
	v_add_u32_e32 v140, s74, v150
	v_add_u32_e32 v144, s84, v150
	ds_read_b128 v[128:131], v140
	ds_read_b128 v[132:135], v140 offset:1024
	ds_read_b128 v[136:139], v140 offset:2048
	ds_read_b128 v[140:143], v140 offset:3072
	ds_read_b128 v[152:155], v144
	ds_read_b128 v[156:159], v144 offset:1024
	ds_read_b128 v[160:163], v144 offset:2048
	ds_read_b128 v[164:167], v144 offset:3072
	s_add_u32 s28, s28, 0x80080
	s_addc_u32 s29, s29, 0
	s_add_i32 m0, s48, 0xc000
	ds_read_b128 v[168:171], v151
	ds_read_b128 v[172:175], v151 offset:1024
	ds_read_b128 v[176:179], v151 offset:2048
	ds_read_b128 v[180:183], v151 offset:3072
	ds_read_b128 v[184:187], v151 offset:4096
	ds_read_b128 v[188:191], v151 offset:5120
	ds_read_b128 v[192:195], v151 offset:6144
	ds_read_b128 v[200:203], v151 offset:7168
	s_nop 0
	global_load_lds_dwordx4 v146, s[28:29]
	s_add_i32 m0, s48, 0xe000
	s_nop 0
	global_load_lds_dwordx4 v148, s[28:29]
	s_nop 0
	s_nop 0
	s_nop 0
	s_nop 0
	s_nop 0
	s_nop 0
	s_nop 0
	s_nop 0
	s_nop 0
	s_nop 0
	s_nop 0
	s_nop 0
	s_nop 0
	s_waitcnt vmcnt(8)
	s_waitcnt lgkmcnt(0)
	s_setprio 1
	s_barrier
	v_mfma_f32_16x16x32_bf16 v[124:127], v[128:131], v[168:171], v[124:127]
	v_mfma_f32_16x16x32_bf16 v[124:127], v[132:135], v[172:175], v[124:127]
	v_mfma_f32_16x16x32_bf16 v[120:123], v[136:139], v[168:171], v[120:123]
	v_mfma_f32_16x16x32_bf16 v[120:123], v[140:143], v[172:175], v[120:123]
	v_mfma_f32_16x16x32_bf16 v[108:111], v[128:131], v[176:179], v[108:111]
	v_mfma_f32_16x16x32_bf16 v[108:111], v[132:135], v[180:183], v[108:111]
	v_mfma_f32_16x16x32_bf16 v[104:107], v[136:139], v[176:179], v[104:107]
	v_mfma_f32_16x16x32_bf16 v[104:107], v[140:143], v[180:183], v[104:107]
	v_mfma_f32_16x16x32_bf16 v[96:99], v[128:131], v[184:187], v[96:99]
	v_mfma_f32_16x16x32_bf16 v[96:99], v[132:135], v[188:191], v[96:99]
	v_mfma_f32_16x16x32_bf16 v[88:91], v[136:139], v[184:187], v[88:91]
	v_mfma_f32_16x16x32_bf16 v[88:91], v[140:143], v[188:191], v[88:91]
	v_mfma_f32_16x16x32_bf16 v[80:83], v[128:131], v[192:195], v[80:83]
	v_mfma_f32_16x16x32_bf16 v[80:83], v[132:135], v[200:203], v[80:83]
	v_mfma_f32_16x16x32_bf16 v[72:75], v[136:139], v[192:195], v[72:75]
	v_mfma_f32_16x16x32_bf16 v[72:75], v[140:143], v[200:203], v[72:75]
	v_mfma_f32_16x16x32_bf16 v[116:119], v[152:155], v[168:171], v[116:119]
	v_mfma_f32_16x16x32_bf16 v[116:119], v[156:159], v[172:175], v[116:119]
	v_mfma_f32_16x16x32_bf16 v[112:115], v[160:163], v[168:171], v[112:115]
	v_mfma_f32_16x16x32_bf16 v[112:115], v[164:167], v[172:175], v[112:115]
	v_mfma_f32_16x16x32_bf16 v[100:103], v[152:155], v[176:179], v[100:103]
	v_mfma_f32_16x16x32_bf16 v[100:103], v[156:159], v[180:183], v[100:103]
	v_mfma_f32_16x16x32_bf16 v[92:95], v[160:163], v[176:179], v[92:95]
	v_mfma_f32_16x16x32_bf16 v[92:95], v[164:167], v[180:183], v[92:95]
	v_mfma_f32_16x16x32_bf16 v[84:87], v[152:155], v[184:187], v[84:87]
	v_mfma_f32_16x16x32_bf16 v[84:87], v[156:159], v[188:191], v[84:87]
	v_mfma_f32_16x16x32_bf16 v[76:79], v[160:163], v[184:187], v[76:79]
	v_mfma_f32_16x16x32_bf16 v[76:79], v[164:167], v[188:191], v[76:79]
	v_mfma_f32_16x16x32_bf16 v[68:71], v[152:155], v[192:195], v[68:71]
	v_mfma_f32_16x16x32_bf16 v[68:71], v[156:159], v[200:203], v[68:71]
	v_mfma_f32_16x16x32_bf16 v[64:67], v[160:163], v[192:195], v[64:67]
	v_mfma_f32_16x16x32_bf16 v[64:67], v[164:167], v[200:203], v[64:67]
	s_barrier
	s_setprio 0
	s_add_i32 s74, s74, s97
	s_mov_b64 s[28:29], s[36:37]
	s_mov_b32 m0, s74
	ds_read_b128 v[168:171], v151 offset:16384
	ds_read_b128 v[172:175], v151 offset:17408
	ds_read_b128 v[176:179], v151 offset:18432
	ds_read_b128 v[180:183], v151 offset:19456
	ds_read_b128 v[184:187], v151 offset:20480
	ds_read_b128 v[188:191], v151 offset:21504
	ds_read_b128 v[192:195], v151 offset:22528
	ds_read_b128 v[200:203], v151 offset:23552
	s_nop 0
	global_load_lds_dwordx4 v147, s[28:29]
	s_add_i32 m0, s74, 0x2000
	s_nop 0
	global_load_lds_dwordx4 v149, s[28:29]
	s_add_u32 s28, s36, 0x80000
	s_addc_u32 s29, s37, 0
	s_add_i32 s74, s84, s97
	s_mov_b32 m0, s74
	s_nop 0
	global_load_lds_dwordx4 v147, s[28:29]
	s_add_i32 m0, s74, 0x2000
	s_nop 0
	global_load_lds_dwordx4 v149, s[28:29]
	s_mov_b64 s[28:29], s[38:39]
	s_mov_b32 m0, s48
	s_nop 0
	global_load_lds_dwordx4 v146, s[28:29]
	s_mov_b32 m0, s49
	s_nop 0
	global_load_lds_dwordx4 v148, s[28:29]
	s_nop 0
	s_nop 0
	s_nop 0
	s_nop 0
	s_nop 0
	s_nop 0
	s_nop 0
	s_nop 0
	s_nop 0
	s_waitcnt vmcnt(8)
	s_waitcnt lgkmcnt(0)
	s_setprio 1
	s_barrier
	v_mfma_f32_16x16x32_bf16 v[60:63], v[128:131], v[168:171], v[60:63]
	v_mfma_f32_16x16x32_bf16 v[60:63], v[132:135], v[172:175], v[60:63]
	v_mfma_f32_16x16x32_bf16 v[56:59], v[136:139], v[168:171], v[56:59]
	v_mfma_f32_16x16x32_bf16 v[56:59], v[140:143], v[172:175], v[56:59]
	v_mfma_f32_16x16x32_bf16 v[48:51], v[128:131], v[176:179], v[48:51]
	v_mfma_f32_16x16x32_bf16 v[48:51], v[132:135], v[180:183], v[48:51]
	v_mfma_f32_16x16x32_bf16 v[40:43], v[136:139], v[176:179], v[40:43]
	v_mfma_f32_16x16x32_bf16 v[40:43], v[140:143], v[180:183], v[40:43]
	v_mfma_f32_16x16x32_bf16 v[32:35], v[128:131], v[184:187], v[32:35]
	v_mfma_f32_16x16x32_bf16 v[32:35], v[132:135], v[188:191], v[32:35]
	v_mfma_f32_16x16x32_bf16 v[24:27], v[136:139], v[184:187], v[24:27]
	v_mfma_f32_16x16x32_bf16 v[24:27], v[140:143], v[188:191], v[24:27]
	v_mfma_f32_16x16x32_bf16 v[16:19], v[128:131], v[192:195], v[16:19]
	v_mfma_f32_16x16x32_bf16 v[16:19], v[132:135], v[200:203], v[16:19]
	v_mfma_f32_16x16x32_bf16 v[8:11], v[136:139], v[192:195], v[8:11]
	v_mfma_f32_16x16x32_bf16 v[8:11], v[140:143], v[200:203], v[8:11]
	v_mfma_f32_16x16x32_bf16 v[52:55], v[152:155], v[168:171], v[52:55]
	v_mfma_f32_16x16x32_bf16 v[52:55], v[156:159], v[172:175], v[52:55]
	v_mfma_f32_16x16x32_bf16 v[44:47], v[160:163], v[168:171], v[44:47]
	v_mfma_f32_16x16x32_bf16 v[44:47], v[164:167], v[172:175], v[44:47]
	v_mfma_f32_16x16x32_bf16 v[36:39], v[152:155], v[176:179], v[36:39]
	v_mfma_f32_16x16x32_bf16 v[36:39], v[156:159], v[180:183], v[36:39]
	v_mfma_f32_16x16x32_bf16 v[28:31], v[160:163], v[176:179], v[28:31]
	v_mfma_f32_16x16x32_bf16 v[28:31], v[164:167], v[180:183], v[28:31]
	v_mfma_f32_16x16x32_bf16 v[20:23], v[152:155], v[184:187], v[20:23]
	v_mfma_f32_16x16x32_bf16 v[20:23], v[156:159], v[188:191], v[20:23]
	v_mfma_f32_16x16x32_bf16 v[12:15], v[160:163], v[184:187], v[12:15]
	v_mfma_f32_16x16x32_bf16 v[12:15], v[164:167], v[188:191], v[12:15]
	v_mfma_f32_16x16x32_bf16 v[4:7], v[152:155], v[192:195], v[4:7]
	v_mfma_f32_16x16x32_bf16 v[4:7], v[156:159], v[200:203], v[4:7]
	v_mfma_f32_16x16x32_bf16 v[0:3], v[160:163], v[192:195], v[0:3]
	v_mfma_f32_16x16x32_bf16 v[0:3], v[164:167], v[200:203], v[0:3]
	s_barrier
	s_setprio 0
	s_add_i32 s74, 0, 0x18000
	s_add_i32 s84, 0, 0x1c000
	v_add_u32_e32 v140, s74, v150
	v_add_u32_e32 v144, s84, v150
	ds_read_b128 v[128:131], v140
	ds_read_b128 v[132:135], v140 offset:1024
	ds_read_b128 v[136:139], v140 offset:2048
	ds_read_b128 v[140:143], v140 offset:3072
	ds_read_b128 v[152:155], v144
	ds_read_b128 v[156:159], v144 offset:1024
	ds_read_b128 v[160:163], v144 offset:2048
	ds_read_b128 v[164:167], v144 offset:3072
	s_add_u32 s28, s38, 0x80000
	s_addc_u32 s29, s39, 0
	s_mov_b32 m0, s56
	ds_read_b128 v[168:171], v151 offset:32768
	ds_read_b128 v[172:175], v151 offset:33792
	ds_read_b128 v[176:179], v151 offset:34816
	ds_read_b128 v[180:183], v151 offset:35840
	ds_read_b128 v[184:187], v151 offset:36864
	ds_read_b128 v[188:191], v151 offset:37888
	ds_read_b128 v[192:195], v151 offset:38912
	ds_read_b128 v[200:203], v151 offset:39936
	s_nop 0
	global_load_lds_dwordx4 v146, s[28:29]
	s_mov_b32 m0, s57
	s_nop 0
	global_load_lds_dwordx4 v148, s[28:29]
	s_nop 0
	s_nop 0
	s_nop 0
	s_nop 0
	s_nop 0
	s_nop 0
	s_nop 0
	s_nop 0
	s_nop 0
	s_waitcnt vmcnt(8)
	s_waitcnt lgkmcnt(0)
	s_setprio 1
	s_barrier
	v_mfma_f32_16x16x32_bf16 v[124:127], v[128:131], v[168:171], v[124:127]
	v_mfma_f32_16x16x32_bf16 v[124:127], v[132:135], v[172:175], v[124:127]
	v_mfma_f32_16x16x32_bf16 v[120:123], v[136:139], v[168:171], v[120:123]
	v_mfma_f32_16x16x32_bf16 v[120:123], v[140:143], v[172:175], v[120:123]
	v_mfma_f32_16x16x32_bf16 v[108:111], v[128:131], v[176:179], v[108:111]
	v_mfma_f32_16x16x32_bf16 v[108:111], v[132:135], v[180:183], v[108:111]
	v_mfma_f32_16x16x32_bf16 v[104:107], v[136:139], v[176:179], v[104:107]
	v_mfma_f32_16x16x32_bf16 v[104:107], v[140:143], v[180:183], v[104:107]
	v_mfma_f32_16x16x32_bf16 v[96:99], v[128:131], v[184:187], v[96:99]
	v_mfma_f32_16x16x32_bf16 v[96:99], v[132:135], v[188:191], v[96:99]
	v_mfma_f32_16x16x32_bf16 v[88:91], v[136:139], v[184:187], v[88:91]
	v_mfma_f32_16x16x32_bf16 v[88:91], v[140:143], v[188:191], v[88:91]
	v_mfma_f32_16x16x32_bf16 v[80:83], v[128:131], v[192:195], v[80:83]
	v_mfma_f32_16x16x32_bf16 v[80:83], v[132:135], v[200:203], v[80:83]
	v_mfma_f32_16x16x32_bf16 v[72:75], v[136:139], v[192:195], v[72:75]
	v_mfma_f32_16x16x32_bf16 v[72:75], v[140:143], v[200:203], v[72:75]
	v_mfma_f32_16x16x32_bf16 v[116:119], v[152:155], v[168:171], v[116:119]
	v_mfma_f32_16x16x32_bf16 v[116:119], v[156:159], v[172:175], v[116:119]
	v_mfma_f32_16x16x32_bf16 v[112:115], v[160:163], v[168:171], v[112:115]
	v_mfma_f32_16x16x32_bf16 v[112:115], v[164:167], v[172:175], v[112:115]
	v_mfma_f32_16x16x32_bf16 v[100:103], v[152:155], v[176:179], v[100:103]
	v_mfma_f32_16x16x32_bf16 v[100:103], v[156:159], v[180:183], v[100:103]
	v_mfma_f32_16x16x32_bf16 v[92:95], v[160:163], v[176:179], v[92:95]
	v_mfma_f32_16x16x32_bf16 v[92:95], v[164:167], v[180:183], v[92:95]
	v_mfma_f32_16x16x32_bf16 v[84:87], v[152:155], v[184:187], v[84:87]
	v_mfma_f32_16x16x32_bf16 v[84:87], v[156:159], v[188:191], v[84:87]
	v_mfma_f32_16x16x32_bf16 v[76:79], v[160:163], v[184:187], v[76:79]
	v_mfma_f32_16x16x32_bf16 v[76:79], v[164:167], v[188:191], v[76:79]
	v_mfma_f32_16x16x32_bf16 v[68:71], v[152:155], v[192:195], v[68:71]
	v_mfma_f32_16x16x32_bf16 v[68:71], v[156:159], v[200:203], v[68:71]
	v_mfma_f32_16x16x32_bf16 v[64:67], v[160:163], v[192:195], v[64:67]
	v_mfma_f32_16x16x32_bf16 v[64:67], v[164:167], v[200:203], v[64:67]
	s_barrier
	s_setprio 0
	s_add_u32 s28, s36, 0x80
	s_addc_u32 s29, s37, 0
	s_add_i32 s38, s74, s97
	s_mov_b32 m0, s38
	ds_read_b128 v[168:171], v151 offset:49152
	ds_read_b128 v[172:175], v151 offset:50176
	ds_read_b128 v[176:179], v151 offset:51200
	ds_read_b128 v[180:183], v151 offset:52224
	ds_read_b128 v[184:187], v151 offset:53248
	ds_read_b128 v[188:191], v151 offset:54272
	ds_read_b128 v[192:195], v151 offset:55296
	ds_read_b128 v[200:203], v151 offset:56320
	s_nop 0
	global_load_lds_dwordx4 v147, s[28:29]
	s_add_i32 m0, s38, 0x2000
	s_nop 0
	global_load_lds_dwordx4 v149, s[28:29]
	s_add_u32 s28, s36, 0x80080
	s_addc_u32 s29, s37, 0
	s_add_i32 s36, s84, s97
	s_mov_b32 m0, s36
	s_nop 0
	global_load_lds_dwordx4 v147, s[28:29]
	s_add_i32 m0, s36, 0x2000
	s_nop 0
	global_load_lds_dwordx4 v149, s[28:29]
	s_mov_b32 m0, s82
	s_nop 0
	global_load_lds_dwordx4 v146, s[34:35]
	s_mov_b32 m0, s83
	s_nop 0
	global_load_lds_dwordx4 v148, s[34:35]
	s_nop 0
	s_nop 0
	s_nop 0
	s_nop 0
	s_nop 0
	s_nop 0
	s_nop 0
	s_nop 0
	s_waitcnt vmcnt(8)
	s_waitcnt lgkmcnt(0)
	s_setprio 1
	s_barrier
	v_mfma_f32_16x16x32_bf16 v[60:63], v[128:131], v[168:171], v[60:63]
	v_mfma_f32_16x16x32_bf16 v[60:63], v[132:135], v[172:175], v[60:63]
	v_mfma_f32_16x16x32_bf16 v[56:59], v[136:139], v[168:171], v[56:59]
	v_mfma_f32_16x16x32_bf16 v[56:59], v[140:143], v[172:175], v[56:59]
	v_mfma_f32_16x16x32_bf16 v[48:51], v[128:131], v[176:179], v[48:51]
	v_mfma_f32_16x16x32_bf16 v[48:51], v[132:135], v[180:183], v[48:51]
	v_mfma_f32_16x16x32_bf16 v[40:43], v[136:139], v[176:179], v[40:43]
	v_mfma_f32_16x16x32_bf16 v[40:43], v[140:143], v[180:183], v[40:43]
	v_mfma_f32_16x16x32_bf16 v[32:35], v[128:131], v[184:187], v[32:35]
	v_mfma_f32_16x16x32_bf16 v[32:35], v[132:135], v[188:191], v[32:35]
	v_mfma_f32_16x16x32_bf16 v[24:27], v[136:139], v[184:187], v[24:27]
	v_mfma_f32_16x16x32_bf16 v[24:27], v[140:143], v[188:191], v[24:27]
	v_mfma_f32_16x16x32_bf16 v[16:19], v[128:131], v[192:195], v[16:19]
	v_mfma_f32_16x16x32_bf16 v[16:19], v[132:135], v[200:203], v[16:19]
	v_mfma_f32_16x16x32_bf16 v[8:11], v[136:139], v[192:195], v[8:11]
	v_mfma_f32_16x16x32_bf16 v[8:11], v[140:143], v[200:203], v[8:11]
	v_mfma_f32_16x16x32_bf16 v[52:55], v[152:155], v[168:171], v[52:55]
	v_mfma_f32_16x16x32_bf16 v[52:55], v[156:159], v[172:175], v[52:55]
	v_mfma_f32_16x16x32_bf16 v[44:47], v[160:163], v[168:171], v[44:47]
	v_mfma_f32_16x16x32_bf16 v[44:47], v[164:167], v[172:175], v[44:47]
	v_mfma_f32_16x16x32_bf16 v[36:39], v[152:155], v[176:179], v[36:39]
	v_mfma_f32_16x16x32_bf16 v[36:39], v[156:159], v[180:183], v[36:39]
	v_mfma_f32_16x16x32_bf16 v[28:31], v[160:163], v[176:179], v[28:31]
	v_mfma_f32_16x16x32_bf16 v[28:31], v[164:167], v[180:183], v[28:31]
	v_mfma_f32_16x16x32_bf16 v[20:23], v[152:155], v[184:187], v[20:23]
	v_mfma_f32_16x16x32_bf16 v[20:23], v[156:159], v[188:191], v[20:23]
	v_mfma_f32_16x16x32_bf16 v[12:15], v[160:163], v[184:187], v[12:15]
	v_mfma_f32_16x16x32_bf16 v[12:15], v[164:167], v[188:191], v[12:15]
	v_mfma_f32_16x16x32_bf16 v[4:7], v[152:155], v[192:195], v[4:7]
	v_mfma_f32_16x16x32_bf16 v[4:7], v[156:159], v[200:203], v[4:7]
	v_mfma_f32_16x16x32_bf16 v[0:3], v[160:163], v[192:195], v[0:3]
	v_mfma_f32_16x16x32_bf16 v[0:3], v[164:167], v[200:203], v[0:3]
	s_barrier
	s_setprio 0
	s_add_i32 s69, s69, 2
	s_add_u32 s21, s21, 0x100
	s_addc_u32 s27, s27, 0
	s_cmp_gt_u32 s69, 29
	s_mov_b64 s[28:29], s[30:31]
	s_cbranch_scc0 .LBB0_676
	s_and_b64 vcc, exec, s[60:61]
	s_cbranch_vccz .LBB0_679
	s_barrier

.LBB0_788:
	s_add_u32 s30, s28, 0x100
	s_addc_u32 s31, s29, 0
	s_cmp_eq_u32 s17, 4
	s_cselect_b32 s38, s20, s30
	s_cselect_b32 s39, s21, s31
	s_cselect_b32 s36, s22, s5
	s_cselect_b32 s37, s23, s15
	s_add_u32 s34, s38, 0x80
	s_addc_u32 s35, s39, 0
	s_add_i32 s83, 0, 0x10000
	s_add_i32 s84, 0, 0x14000
	v_add_u32_e32 v146, s83, v136
	v_add_u32_e32 v162, s84, v136
	ds_read_b128 v[128:131], v146
	ds_read_b128 v[138:141], v146 offset:1024
	ds_read_b128 v[142:145], v146 offset:2048
	ds_read_b128 v[146:149], v146 offset:3072
	ds_read_b128 v[150:153], v162
	ds_read_b128 v[154:157], v162 offset:1024
	ds_read_b128 v[158:161], v162 offset:2048
	ds_read_b128 v[162:165], v162 offset:3072
	s_add_u32 s28, s28, 0x20080
	s_addc_u32 s29, s29, 0
	s_add_i32 m0, s27, 0xc000
	ds_read_b128 v[166:169], v137
	ds_read_b128 v[170:173], v137 offset:1024
	ds_read_b128 v[174:177], v137 offset:2048
	ds_read_b128 v[178:181], v137 offset:3072
	ds_read_b128 v[182:185], v137 offset:4096
	ds_read_b128 v[186:189], v137 offset:5120
	ds_read_b128 v[190:193], v137 offset:6144
	ds_read_b128 v[200:203], v137 offset:7168
	s_nop 0
	global_load_lds_dwordx4 v132, s[28:29]
	s_add_i32 m0, s27, 0xe000
	s_nop 0
	global_load_lds_dwordx4 v134, s[28:29]
	s_nop 0
	s_nop 0
	s_nop 0
	s_nop 0
	s_nop 0
	s_nop 0
	s_nop 0
	s_nop 0
	s_nop 0
	s_nop 0
	s_nop 0
	s_nop 0
	s_nop 0
	s_nop 0
	s_waitcnt vmcnt(8)
	s_waitcnt lgkmcnt(0)
	s_setprio 1
	s_barrier
	v_mfma_f32_16x16x32_bf16 v[124:127], v[128:131], v[166:169], v[124:127]
	v_mfma_f32_16x16x32_bf16 v[124:127], v[138:141], v[170:173], v[124:127]
	v_mfma_f32_16x16x32_bf16 v[120:123], v[142:145], v[166:169], v[120:123]
	v_mfma_f32_16x16x32_bf16 v[120:123], v[146:149], v[170:173], v[120:123]
	v_mfma_f32_16x16x32_bf16 v[108:111], v[128:131], v[174:177], v[108:111]
	v_mfma_f32_16x16x32_bf16 v[108:111], v[138:141], v[178:181], v[108:111]
	v_mfma_f32_16x16x32_bf16 v[104:107], v[142:145], v[174:177], v[104:107]
	v_mfma_f32_16x16x32_bf16 v[104:107], v[146:149], v[178:181], v[104:107]
	v_mfma_f32_16x16x32_bf16 v[92:95], v[128:131], v[182:185], v[92:95]
	v_mfma_f32_16x16x32_bf16 v[92:95], v[138:141], v[186:189], v[92:95]
	v_mfma_f32_16x16x32_bf16 v[88:91], v[142:145], v[182:185], v[88:91]
	v_mfma_f32_16x16x32_bf16 v[88:91], v[146:149], v[186:189], v[88:91]
	v_mfma_f32_16x16x32_bf16 v[76:79], v[128:131], v[190:193], v[76:79]
	v_mfma_f32_16x16x32_bf16 v[76:79], v[138:141], v[200:203], v[76:79]
	v_mfma_f32_16x16x32_bf16 v[72:75], v[142:145], v[190:193], v[72:75]
	v_mfma_f32_16x16x32_bf16 v[72:75], v[146:149], v[200:203], v[72:75]
	v_mfma_f32_16x16x32_bf16 v[116:119], v[150:153], v[166:169], v[116:119]
	v_mfma_f32_16x16x32_bf16 v[116:119], v[154:157], v[170:173], v[116:119]
	v_mfma_f32_16x16x32_bf16 v[112:115], v[158:161], v[166:169], v[112:115]
	v_mfma_f32_16x16x32_bf16 v[112:115], v[162:165], v[170:173], v[112:115]
	v_mfma_f32_16x16x32_bf16 v[100:103], v[150:153], v[174:177], v[100:103]
	v_mfma_f32_16x16x32_bf16 v[100:103], v[154:157], v[178:181], v[100:103]
	v_mfma_f32_16x16x32_bf16 v[96:99], v[158:161], v[174:177], v[96:99]
	v_mfma_f32_16x16x32_bf16 v[96:99], v[162:165], v[178:181], v[96:99]
	v_mfma_f32_16x16x32_bf16 v[84:87], v[150:153], v[182:185], v[84:87]
	v_mfma_f32_16x16x32_bf16 v[84:87], v[154:157], v[186:189], v[84:87]
	v_mfma_f32_16x16x32_bf16 v[80:83], v[158:161], v[182:185], v[80:83]
	v_mfma_f32_16x16x32_bf16 v[80:83], v[162:165], v[186:189], v[80:83]
	v_mfma_f32_16x16x32_bf16 v[68:71], v[150:153], v[190:193], v[68:71]
	v_mfma_f32_16x16x32_bf16 v[68:71], v[154:157], v[200:203], v[68:71]
	v_mfma_f32_16x16x32_bf16 v[64:67], v[158:161], v[190:193], v[64:67]
	v_mfma_f32_16x16x32_bf16 v[64:67], v[162:165], v[200:203], v[64:67]
	s_barrier
	s_setprio 0
	s_add_i32 s83, s83, s97
	s_mov_b64 s[28:29], s[36:37]
	s_mov_b32 m0, s83
	ds_read_b128 v[166:169], v137 offset:16384
	ds_read_b128 v[170:173], v137 offset:17408
	ds_read_b128 v[174:177], v137 offset:18432
	ds_read_b128 v[178:181], v137 offset:19456
	ds_read_b128 v[182:185], v137 offset:20480
	ds_read_b128 v[186:189], v137 offset:21504
	ds_read_b128 v[190:193], v137 offset:22528
	ds_read_b128 v[200:203], v137 offset:23552
	s_nop 0
	global_load_lds_dwordx4 v133, s[28:29]
	s_add_i32 m0, s83, 0x2000
	s_nop 0
	global_load_lds_dwordx4 v135, s[28:29]
	s_add_u32 s28, s36, 0x20000
	s_addc_u32 s29, s37, 0
	s_add_i32 s83, s84, s97
	s_mov_b32 m0, s83
	s_nop 0
	global_load_lds_dwordx4 v133, s[28:29]
	s_add_i32 m0, s83, 0x2000
	s_nop 0
	global_load_lds_dwordx4 v135, s[28:29]
	s_mov_b64 s[28:29], s[38:39]
	s_mov_b32 m0, s27
	s_nop 0
	global_load_lds_dwordx4 v132, s[28:29]
	s_mov_b32 m0, s69
	s_nop 0
	global_load_lds_dwordx4 v134, s[28:29]
	s_nop 0
	s_nop 0
	s_nop 0
	s_nop 0
	s_nop 0
	s_nop 0
	s_nop 0
	s_nop 0
	s_nop 0
	s_waitcnt vmcnt(8)
	s_waitcnt lgkmcnt(0)
	s_setprio 1
	s_barrier
	v_mfma_f32_16x16x32_bf16 v[60:63], v[128:131], v[166:169], v[60:63]
	v_mfma_f32_16x16x32_bf16 v[60:63], v[138:141], v[170:173], v[60:63]
	v_mfma_f32_16x16x32_bf16 v[56:59], v[142:145], v[166:169], v[56:59]
	v_mfma_f32_16x16x32_bf16 v[56:59], v[146:149], v[170:173], v[56:59]
	v_mfma_f32_16x16x32_bf16 v[44:47], v[128:131], v[174:177], v[44:47]
	v_mfma_f32_16x16x32_bf16 v[44:47], v[138:141], v[178:181], v[44:47]
	v_mfma_f32_16x16x32_bf16 v[40:43], v[142:145], v[174:177], v[40:43]
	v_mfma_f32_16x16x32_bf16 v[40:43], v[146:149], v[178:181], v[40:43]
	v_mfma_f32_16x16x32_bf16 v[28:31], v[128:131], v[182:185], v[28:31]
	v_mfma_f32_16x16x32_bf16 v[28:31], v[138:141], v[186:189], v[28:31]
	v_mfma_f32_16x16x32_bf16 v[24:27], v[142:145], v[182:185], v[24:27]
	v_mfma_f32_16x16x32_bf16 v[24:27], v[146:149], v[186:189], v[24:27]
	v_mfma_f32_16x16x32_bf16 v[12:15], v[128:131], v[190:193], v[12:15]
	v_mfma_f32_16x16x32_bf16 v[12:15], v[138:141], v[200:203], v[12:15]
	v_mfma_f32_16x16x32_bf16 v[8:11], v[142:145], v[190:193], v[8:11]
	v_mfma_f32_16x16x32_bf16 v[8:11], v[146:149], v[200:203], v[8:11]
	v_mfma_f32_16x16x32_bf16 v[52:55], v[150:153], v[166:169], v[52:55]
	v_mfma_f32_16x16x32_bf16 v[52:55], v[154:157], v[170:173], v[52:55]
	v_mfma_f32_16x16x32_bf16 v[48:51], v[158:161], v[166:169], v[48:51]
	v_mfma_f32_16x16x32_bf16 v[48:51], v[162:165], v[170:173], v[48:51]
	v_mfma_f32_16x16x32_bf16 v[36:39], v[150:153], v[174:177], v[36:39]
	v_mfma_f32_16x16x32_bf16 v[36:39], v[154:157], v[178:181], v[36:39]
	v_mfma_f32_16x16x32_bf16 v[32:35], v[158:161], v[174:177], v[32:35]
	v_mfma_f32_16x16x32_bf16 v[32:35], v[162:165], v[178:181], v[32:35]
	v_mfma_f32_16x16x32_bf16 v[20:23], v[150:153], v[182:185], v[20:23]
	v_mfma_f32_16x16x32_bf16 v[20:23], v[154:157], v[186:189], v[20:23]
	v_mfma_f32_16x16x32_bf16 v[16:19], v[158:161], v[182:185], v[16:19]
	v_mfma_f32_16x16x32_bf16 v[16:19], v[162:165], v[186:189], v[16:19]
	v_mfma_f32_16x16x32_bf16 v[4:7], v[150:153], v[190:193], v[4:7]
	v_mfma_f32_16x16x32_bf16 v[4:7], v[154:157], v[200:203], v[4:7]
	v_mfma_f32_16x16x32_bf16 v[0:3], v[158:161], v[190:193], v[0:3]
	v_mfma_f32_16x16x32_bf16 v[0:3], v[162:165], v[200:203], v[0:3]
	s_barrier
	s_setprio 0
	s_add_i32 s83, 0, 0x18000
	s_add_i32 s84, 0, 0x1c000
	v_add_u32_e32 v146, s83, v136
	v_add_u32_e32 v162, s84, v136
	ds_read_b128 v[128:131], v146
	ds_read_b128 v[138:141], v146 offset:1024
	ds_read_b128 v[142:145], v146 offset:2048
	ds_read_b128 v[146:149], v146 offset:3072
	ds_read_b128 v[150:153], v162
	ds_read_b128 v[154:157], v162 offset:1024
	ds_read_b128 v[158:161], v162 offset:2048
	ds_read_b128 v[162:165], v162 offset:3072
	s_add_u32 s28, s38, 0x20000
	s_addc_u32 s29, s39, 0
	s_mov_b32 m0, s71
	ds_read_b128 v[166:169], v137 offset:32768
	ds_read_b128 v[170:173], v137 offset:33792
	ds_read_b128 v[174:177], v137 offset:34816
	ds_read_b128 v[178:181], v137 offset:35840
	ds_read_b128 v[182:185], v137 offset:36864
	ds_read_b128 v[186:189], v137 offset:37888
	ds_read_b128 v[190:193], v137 offset:38912
	ds_read_b128 v[200:203], v137 offset:39936
	s_nop 0
	global_load_lds_dwordx4 v132, s[28:29]
	s_mov_b32 m0, s72
	s_nop 0
	global_load_lds_dwordx4 v134, s[28:29]
	s_nop 0
	s_nop 0
	s_nop 0
	s_nop 0
	s_nop 0
	s_nop 0
	s_nop 0
	s_nop 0
	s_nop 0
	s_waitcnt vmcnt(8)
	s_waitcnt lgkmcnt(0)
	s_setprio 1
	s_barrier
	v_mfma_f32_16x16x32_bf16 v[124:127], v[128:131], v[166:169], v[124:127]
	v_mfma_f32_16x16x32_bf16 v[124:127], v[138:141], v[170:173], v[124:127]
	v_mfma_f32_16x16x32_bf16 v[120:123], v[142:145], v[166:169], v[120:123]
	v_mfma_f32_16x16x32_bf16 v[120:123], v[146:149], v[170:173], v[120:123]
	v_mfma_f32_16x16x32_bf16 v[108:111], v[128:131], v[174:177], v[108:111]
	v_mfma_f32_16x16x32_bf16 v[108:111], v[138:141], v[178:181], v[108:111]
	v_mfma_f32_16x16x32_bf16 v[104:107], v[142:145], v[174:177], v[104:107]
	v_mfma_f32_16x16x32_bf16 v[104:107], v[146:149], v[178:181], v[104:107]
	v_mfma_f32_16x16x32_bf16 v[92:95], v[128:131], v[182:185], v[92:95]
	v_mfma_f32_16x16x32_bf16 v[92:95], v[138:141], v[186:189], v[92:95]
	v_mfma_f32_16x16x32_bf16 v[88:91], v[142:145], v[182:185], v[88:91]
	v_mfma_f32_16x16x32_bf16 v[88:91], v[146:149], v[186:189], v[88:91]
	v_mfma_f32_16x16x32_bf16 v[76:79], v[128:131], v[190:193], v[76:79]
	v_mfma_f32_16x16x32_bf16 v[76:79], v[138:141], v[200:203], v[76:79]
	v_mfma_f32_16x16x32_bf16 v[72:75], v[142:145], v[190:193], v[72:75]
	v_mfma_f32_16x16x32_bf16 v[72:75], v[146:149], v[200:203], v[72:75]
	v_mfma_f32_16x16x32_bf16 v[116:119], v[150:153], v[166:169], v[116:119]
	v_mfma_f32_16x16x32_bf16 v[116:119], v[154:157], v[170:173], v[116:119]
	v_mfma_f32_16x16x32_bf16 v[112:115], v[158:161], v[166:169], v[112:115]
	v_mfma_f32_16x16x32_bf16 v[112:115], v[162:165], v[170:173], v[112:115]
	v_mfma_f32_16x16x32_bf16 v[100:103], v[150:153], v[174:177], v[100:103]
	v_mfma_f32_16x16x32_bf16 v[100:103], v[154:157], v[178:181], v[100:103]
	v_mfma_f32_16x16x32_bf16 v[96:99], v[158:161], v[174:177], v[96:99]
	v_mfma_f32_16x16x32_bf16 v[96:99], v[162:165], v[178:181], v[96:99]
	v_mfma_f32_16x16x32_bf16 v[84:87], v[150:153], v[182:185], v[84:87]
	v_mfma_f32_16x16x32_bf16 v[84:87], v[154:157], v[186:189], v[84:87]
	v_mfma_f32_16x16x32_bf16 v[80:83], v[158:161], v[182:185], v[80:83]
	v_mfma_f32_16x16x32_bf16 v[80:83], v[162:165], v[186:189], v[80:83]
	v_mfma_f32_16x16x32_bf16 v[68:71], v[150:153], v[190:193], v[68:71]
	v_mfma_f32_16x16x32_bf16 v[68:71], v[154:157], v[200:203], v[68:71]
	v_mfma_f32_16x16x32_bf16 v[64:67], v[158:161], v[190:193], v[64:67]
	v_mfma_f32_16x16x32_bf16 v[64:67], v[162:165], v[200:203], v[64:67]
	s_barrier
	s_setprio 0
	s_add_u32 s28, s36, 0x80
	s_addc_u32 s29, s37, 0
	s_add_i32 s38, s83, s97
	s_mov_b32 m0, s38
	ds_read_b128 v[166:169], v137 offset:49152
	ds_read_b128 v[170:173], v137 offset:50176
	ds_read_b128 v[174:177], v137 offset:51200
	ds_read_b128 v[178:181], v137 offset:52224
	ds_read_b128 v[182:185], v137 offset:53248
	ds_read_b128 v[186:189], v137 offset:54272
	ds_read_b128 v[190:193], v137 offset:55296
	ds_read_b128 v[200:203], v137 offset:56320
	s_nop 0
	global_load_lds_dwordx4 v133, s[28:29]
	s_add_i32 m0, s38, 0x2000
	s_nop 0
	global_load_lds_dwordx4 v135, s[28:29]
	s_add_u32 s28, s36, 0x20080
	s_addc_u32 s29, s37, 0
	s_add_i32 s36, s84, s97
	s_mov_b32 m0, s36
	s_nop 0
	global_load_lds_dwordx4 v133, s[28:29]
	s_add_i32 m0, s36, 0x2000
	s_nop 0
	global_load_lds_dwordx4 v135, s[28:29]
	s_mov_b32 m0, s80
	s_nop 0
	global_load_lds_dwordx4 v132, s[34:35]
	s_mov_b32 m0, s81
	s_nop 0
	global_load_lds_dwordx4 v134, s[34:35]
	s_nop 0
	s_nop 0
	s_nop 0
	s_nop 0
	s_nop 0
	s_nop 0
	s_nop 0
	s_nop 0
	s_waitcnt vmcnt(8)
	s_waitcnt lgkmcnt(0)
	s_setprio 1
	s_barrier
	v_mfma_f32_16x16x32_bf16 v[60:63], v[128:131], v[166:169], v[60:63]
	v_mfma_f32_16x16x32_bf16 v[60:63], v[138:141], v[170:173], v[60:63]
	v_mfma_f32_16x16x32_bf16 v[56:59], v[142:145], v[166:169], v[56:59]
	v_mfma_f32_16x16x32_bf16 v[56:59], v[146:149], v[170:173], v[56:59]
	v_mfma_f32_16x16x32_bf16 v[44:47], v[128:131], v[174:177], v[44:47]
	v_mfma_f32_16x16x32_bf16 v[44:47], v[138:141], v[178:181], v[44:47]
	v_mfma_f32_16x16x32_bf16 v[40:43], v[142:145], v[174:177], v[40:43]
	v_mfma_f32_16x16x32_bf16 v[40:43], v[146:149], v[178:181], v[40:43]
	v_mfma_f32_16x16x32_bf16 v[28:31], v[128:131], v[182:185], v[28:31]
	v_mfma_f32_16x16x32_bf16 v[28:31], v[138:141], v[186:189], v[28:31]
	v_mfma_f32_16x16x32_bf16 v[24:27], v[142:145], v[182:185], v[24:27]
	v_mfma_f32_16x16x32_bf16 v[24:27], v[146:149], v[186:189], v[24:27]
	v_mfma_f32_16x16x32_bf16 v[12:15], v[128:131], v[190:193], v[12:15]
	v_mfma_f32_16x16x32_bf16 v[12:15], v[138:141], v[200:203], v[12:15]
	v_mfma_f32_16x16x32_bf16 v[8:11], v[142:145], v[190:193], v[8:11]
	v_mfma_f32_16x16x32_bf16 v[8:11], v[146:149], v[200:203], v[8:11]
	v_mfma_f32_16x16x32_bf16 v[52:55], v[150:153], v[166:169], v[52:55]
	v_mfma_f32_16x16x32_bf16 v[52:55], v[154:157], v[170:173], v[52:55]
	v_mfma_f32_16x16x32_bf16 v[48:51], v[158:161], v[166:169], v[48:51]
	v_mfma_f32_16x16x32_bf16 v[48:51], v[162:165], v[170:173], v[48:51]
	v_mfma_f32_16x16x32_bf16 v[36:39], v[150:153], v[174:177], v[36:39]
	v_mfma_f32_16x16x32_bf16 v[36:39], v[154:157], v[178:181], v[36:39]
	v_mfma_f32_16x16x32_bf16 v[32:35], v[158:161], v[174:177], v[32:35]
	v_mfma_f32_16x16x32_bf16 v[32:35], v[162:165], v[178:181], v[32:35]
	v_mfma_f32_16x16x32_bf16 v[20:23], v[150:153], v[182:185], v[20:23]
	v_mfma_f32_16x16x32_bf16 v[20:23], v[154:157], v[186:189], v[20:23]
	v_mfma_f32_16x16x32_bf16 v[16:19], v[158:161], v[182:185], v[16:19]
	v_mfma_f32_16x16x32_bf16 v[16:19], v[162:165], v[186:189], v[16:19]
	v_mfma_f32_16x16x32_bf16 v[4:7], v[150:153], v[190:193], v[4:7]
	v_mfma_f32_16x16x32_bf16 v[4:7], v[154:157], v[200:203], v[4:7]
	v_mfma_f32_16x16x32_bf16 v[0:3], v[158:161], v[190:193], v[0:3]
	v_mfma_f32_16x16x32_bf16 v[0:3], v[162:165], v[200:203], v[0:3]
	s_barrier
	s_setprio 0
	s_add_i32 s17, s17, 2
	s_add_u32 s5, s5, 0x100
	s_addc_u32 s15, s15, 0
	s_cmp_gt_u32 s17, 5
	s_mov_b64 s[28:29], s[30:31]
	s_cbranch_scc0 .LBB0_788
	s_and_b64 vcc, exec, s[60:61]
	s_cbranch_vccz .LBB0_791
	s_barrier

.LBB0_1050:
	s_cmp_eq_u32 s83, 28
	s_cselect_b32 s56, s5, s39
	s_cselect_b32 s57, s4, s69
	s_cselect_b32 s84, s37, s72
	s_cselect_b32 s85, s11, s74
	s_add_u32 s12, s56, 0x80
	s_addc_u32 s13, s57, 0
	s_add_i32 vcc_lo, 0, 0x10000
	s_add_i32 vcc_hi, 0, 0x14000
	v_add_u32_e32 v136, vcc_lo, v184
	v_add_u32_e32 v156, vcc_hi, v184
	ds_read_b128 v[104:107], v136
	ds_read_b128 v[108:111], v136 offset:1024
	ds_read_b128 v[132:135], v136 offset:2048
	ds_read_b128 v[136:139], v136 offset:3072
	ds_read_b128 v[144:147], v156
	ds_read_b128 v[148:151], v156 offset:1024
	ds_read_b128 v[152:155], v156 offset:2048
	ds_read_b128 v[156:159], v156 offset:3072
	s_mov_b64 s[86:87], s[8:9]
	s_add_i32 m0, s92, 0xc000
	ds_read_b128 v[160:163], v185
	ds_read_b128 v[164:167], v185 offset:1024
	ds_read_b128 v[168:171], v185 offset:2048
	ds_read_b128 v[172:175], v185 offset:3072
	ds_read_b128 v[186:189], v185 offset:4096
	ds_read_b128 v[190:193], v185 offset:5120
	ds_read_b128 v[200:203], v185 offset:6144
	ds_read_b128 v[204:207], v185 offset:7168
	s_nop 0
	global_load_lds_dwordx4 v179, s[86:87]
	s_add_i32 m0, s92, 0xe000
	s_nop 0
	global_load_lds_dwordx4 v182, s[86:87]
	s_nop 0
	s_nop 0
	s_waitcnt vmcnt(8)
	s_waitcnt lgkmcnt(0)
	s_setprio 1
	s_barrier
	v_mfma_f32_16x16x32_bf16 v[140:143], v[104:107], v[160:163], v[140:143]
	v_mfma_f32_16x16x32_bf16 v[140:143], v[108:111], v[164:167], v[140:143]
	v_mfma_f32_16x16x32_bf16 v[128:131], v[132:135], v[160:163], v[128:131]
	v_mfma_f32_16x16x32_bf16 v[128:131], v[136:139], v[164:167], v[128:131]
	v_mfma_f32_16x16x32_bf16 v[124:127], v[104:107], v[168:171], v[124:127]
	v_mfma_f32_16x16x32_bf16 v[124:127], v[108:111], v[172:175], v[124:127]
	v_mfma_f32_16x16x32_bf16 v[112:115], v[132:135], v[168:171], v[112:115]
	v_mfma_f32_16x16x32_bf16 v[112:115], v[136:139], v[172:175], v[112:115]
	v_mfma_f32_16x16x32_bf16 v[96:99], v[104:107], v[186:189], v[96:99]
	v_mfma_f32_16x16x32_bf16 v[96:99], v[108:111], v[190:193], v[96:99]
	v_mfma_f32_16x16x32_bf16 v[88:91], v[132:135], v[186:189], v[88:91]
	v_mfma_f32_16x16x32_bf16 v[88:91], v[136:139], v[190:193], v[88:91]
	v_mfma_f32_16x16x32_bf16 v[84:87], v[104:107], v[200:203], v[84:87]
	v_mfma_f32_16x16x32_bf16 v[84:87], v[108:111], v[204:207], v[84:87]
	v_mfma_f32_16x16x32_bf16 v[72:75], v[132:135], v[200:203], v[72:75]
	v_mfma_f32_16x16x32_bf16 v[72:75], v[136:139], v[204:207], v[72:75]
	v_mfma_f32_16x16x32_bf16 v[120:123], v[144:147], v[160:163], v[120:123]
	v_mfma_f32_16x16x32_bf16 v[120:123], v[148:151], v[164:167], v[120:123]
	v_mfma_f32_16x16x32_bf16 v[116:119], v[152:155], v[160:163], v[116:119]
	v_mfma_f32_16x16x32_bf16 v[116:119], v[156:159], v[164:167], v[116:119]
	v_mfma_f32_16x16x32_bf16 v[100:103], v[144:147], v[168:171], v[100:103]
	v_mfma_f32_16x16x32_bf16 v[100:103], v[148:151], v[172:175], v[100:103]
	v_mfma_f32_16x16x32_bf16 v[92:95], v[152:155], v[168:171], v[92:95]
	v_mfma_f32_16x16x32_bf16 v[92:95], v[156:159], v[172:175], v[92:95]
	v_mfma_f32_16x16x32_bf16 v[80:83], v[144:147], v[186:189], v[80:83]
	v_mfma_f32_16x16x32_bf16 v[80:83], v[148:151], v[190:193], v[80:83]
	v_mfma_f32_16x16x32_bf16 v[76:79], v[152:155], v[186:189], v[76:79]
	v_mfma_f32_16x16x32_bf16 v[76:79], v[156:159], v[190:193], v[76:79]
	v_mfma_f32_16x16x32_bf16 v[68:71], v[144:147], v[200:203], v[68:71]
	v_mfma_f32_16x16x32_bf16 v[68:71], v[148:151], v[204:207], v[68:71]
	v_mfma_f32_16x16x32_bf16 v[64:67], v[152:155], v[200:203], v[64:67]
	v_mfma_f32_16x16x32_bf16 v[64:67], v[156:159], v[204:207], v[64:67]
	s_barrier
	s_setprio 0
	s_add_i32 vcc_lo, vcc_lo, s97
	s_mov_b64 s[86:87], s[84:85]
	s_mov_b32 m0, vcc_lo
	ds_read_b128 v[160:163], v185 offset:16384
	ds_read_b128 v[164:167], v185 offset:17408
	ds_read_b128 v[168:171], v185 offset:18432
	ds_read_b128 v[172:175], v185 offset:19456
	ds_read_b128 v[186:189], v185 offset:20480
	ds_read_b128 v[190:193], v185 offset:21504
	ds_read_b128 v[200:203], v185 offset:22528
	ds_read_b128 v[204:207], v185 offset:23552
	s_nop 0
	global_load_lds_dwordx4 v181, s[86:87]
	s_add_i32 m0, vcc_lo, 0x2000
	s_nop 0
	global_load_lds_dwordx4 v183, s[86:87]
	s_add_u32 s86, s84, 0x80000
	s_addc_u32 s87, s85, 0
	s_add_i32 vcc_lo, vcc_hi, s97
	s_mov_b32 m0, vcc_lo
	s_nop 0
	global_load_lds_dwordx4 v181, s[86:87]
	s_add_i32 m0, vcc_lo, 0x2000
	s_nop 0
	global_load_lds_dwordx4 v183, s[86:87]
	s_mov_b64 s[86:87], s[56:57]
	s_mov_b32 m0, s92
	s_nop 0
	global_load_lds_dwordx4 v179, s[86:87]
	s_mov_b32 m0, s93
	s_nop 0
	global_load_lds_dwordx4 v182, s[86:87]
	s_nop 0
	s_nop 0
	s_nop 0
	s_nop 0
	s_nop 0
	s_nop 0
	s_nop 0
	s_nop 0
	s_nop 0
	s_waitcnt vmcnt(8)
	s_waitcnt lgkmcnt(0)
	s_setprio 1
	s_barrier
	v_mfma_f32_16x16x32_bf16 v[60:63], v[104:107], v[160:163], v[60:63]
	v_mfma_f32_16x16x32_bf16 v[60:63], v[108:111], v[164:167], v[60:63]
	v_mfma_f32_16x16x32_bf16 v[56:59], v[132:135], v[160:163], v[56:59]
	v_mfma_f32_16x16x32_bf16 v[56:59], v[136:139], v[164:167], v[56:59]
	v_mfma_f32_16x16x32_bf16 v[48:51], v[104:107], v[168:171], v[48:51]
	v_mfma_f32_16x16x32_bf16 v[48:51], v[108:111], v[172:175], v[48:51]
	v_mfma_f32_16x16x32_bf16 v[40:43], v[132:135], v[168:171], v[40:43]
	v_mfma_f32_16x16x32_bf16 v[40:43], v[136:139], v[172:175], v[40:43]
	v_mfma_f32_16x16x32_bf16 v[32:35], v[104:107], v[186:189], v[32:35]
	v_mfma_f32_16x16x32_bf16 v[32:35], v[108:111], v[190:193], v[32:35]
	v_mfma_f32_16x16x32_bf16 v[24:27], v[132:135], v[186:189], v[24:27]
	v_mfma_f32_16x16x32_bf16 v[24:27], v[136:139], v[190:193], v[24:27]
	v_mfma_f32_16x16x32_bf16 v[16:19], v[104:107], v[200:203], v[16:19]
	v_mfma_f32_16x16x32_bf16 v[16:19], v[108:111], v[204:207], v[16:19]
	v_mfma_f32_16x16x32_bf16 v[8:11], v[132:135], v[200:203], v[8:11]
	v_mfma_f32_16x16x32_bf16 v[8:11], v[136:139], v[204:207], v[8:11]
	v_mfma_f32_16x16x32_bf16 v[52:55], v[144:147], v[160:163], v[52:55]
	v_mfma_f32_16x16x32_bf16 v[52:55], v[148:151], v[164:167], v[52:55]
	v_mfma_f32_16x16x32_bf16 v[44:47], v[152:155], v[160:163], v[44:47]
	v_mfma_f32_16x16x32_bf16 v[44:47], v[156:159], v[164:167], v[44:47]
	v_mfma_f32_16x16x32_bf16 v[36:39], v[144:147], v[168:171], v[36:39]
	v_mfma_f32_16x16x32_bf16 v[36:39], v[148:151], v[172:175], v[36:39]
	v_mfma_f32_16x16x32_bf16 v[28:31], v[152:155], v[168:171], v[28:31]
	v_mfma_f32_16x16x32_bf16 v[28:31], v[156:159], v[172:175], v[28:31]
	v_mfma_f32_16x16x32_bf16 v[20:23], v[144:147], v[186:189], v[20:23]
	v_mfma_f32_16x16x32_bf16 v[20:23], v[148:151], v[190:193], v[20:23]
	v_mfma_f32_16x16x32_bf16 v[12:15], v[152:155], v[186:189], v[12:15]
	v_mfma_f32_16x16x32_bf16 v[12:15], v[156:159], v[190:193], v[12:15]
	v_mfma_f32_16x16x32_bf16 v[4:7], v[144:147], v[200:203], v[4:7]
	v_mfma_f32_16x16x32_bf16 v[4:7], v[148:151], v[204:207], v[4:7]
	v_mfma_f32_16x16x32_bf16 v[0:3], v[152:155], v[200:203], v[0:3]
	v_mfma_f32_16x16x32_bf16 v[0:3], v[156:159], v[204:207], v[0:3]
	s_barrier
	s_setprio 0
	s_add_i32 s86, 0, 0x18000
	s_add_i32 s87, 0, 0x1c000
	v_add_u32_e32 v136, s86, v184
	v_add_u32_e32 v156, s87, v184
	ds_read_b128 v[104:107], v136
	ds_read_b128 v[108:111], v136 offset:1024
	ds_read_b128 v[132:135], v136 offset:2048
	ds_read_b128 v[136:139], v136 offset:3072
	ds_read_b128 v[144:147], v156
	ds_read_b128 v[148:151], v156 offset:1024
	ds_read_b128 v[152:155], v156 offset:2048
	ds_read_b128 v[156:159], v156 offset:3072
	s_add_u32 s56, s56, 0x80000
	s_addc_u32 s57, s57, 0
	s_mov_b32 m0, s80
	ds_read_b128 v[160:163], v185 offset:32768
	ds_read_b128 v[164:167], v185 offset:33792
	ds_read_b128 v[168:171], v185 offset:34816
	ds_read_b128 v[172:175], v185 offset:35840
	ds_read_b128 v[186:189], v185 offset:36864
	ds_read_b128 v[190:193], v185 offset:37888
	ds_read_b128 v[200:203], v185 offset:38912
	ds_read_b128 v[204:207], v185 offset:39936
	s_nop 0
	global_load_lds_dwordx4 v179, s[56:57]
	s_mov_b32 m0, s48
	s_nop 0
	global_load_lds_dwordx4 v182, s[56:57]
	s_nop 0
	s_nop 0
	s_nop 0
	s_nop 0
	s_nop 0
	s_nop 0
	s_nop 0
	s_nop 0
	s_nop 0
	s_waitcnt vmcnt(8)
	s_waitcnt lgkmcnt(0)
	s_setprio 1
	s_barrier
	v_mfma_f32_16x16x32_bf16 v[140:143], v[104:107], v[160:163], v[140:143]
	v_mfma_f32_16x16x32_bf16 v[140:143], v[108:111], v[164:167], v[140:143]
	v_mfma_f32_16x16x32_bf16 v[128:131], v[132:135], v[160:163], v[128:131]
	v_mfma_f32_16x16x32_bf16 v[128:131], v[136:139], v[164:167], v[128:131]
	v_mfma_f32_16x16x32_bf16 v[124:127], v[104:107], v[168:171], v[124:127]
	v_mfma_f32_16x16x32_bf16 v[124:127], v[108:111], v[172:175], v[124:127]
	v_mfma_f32_16x16x32_bf16 v[112:115], v[132:135], v[168:171], v[112:115]
	v_mfma_f32_16x16x32_bf16 v[112:115], v[136:139], v[172:175], v[112:115]
	v_mfma_f32_16x16x32_bf16 v[96:99], v[104:107], v[186:189], v[96:99]
	v_mfma_f32_16x16x32_bf16 v[96:99], v[108:111], v[190:193], v[96:99]
	v_mfma_f32_16x16x32_bf16 v[88:91], v[132:135], v[186:189], v[88:91]
	v_mfma_f32_16x16x32_bf16 v[88:91], v[136:139], v[190:193], v[88:91]
	v_mfma_f32_16x16x32_bf16 v[84:87], v[104:107], v[200:203], v[84:87]
	v_mfma_f32_16x16x32_bf16 v[84:87], v[108:111], v[204:207], v[84:87]
	v_mfma_f32_16x16x32_bf16 v[72:75], v[132:135], v[200:203], v[72:75]
	v_mfma_f32_16x16x32_bf16 v[72:75], v[136:139], v[204:207], v[72:75]
	v_mfma_f32_16x16x32_bf16 v[120:123], v[144:147], v[160:163], v[120:123]
	v_mfma_f32_16x16x32_bf16 v[120:123], v[148:151], v[164:167], v[120:123]
	v_mfma_f32_16x16x32_bf16 v[116:119], v[152:155], v[160:163], v[116:119]
	v_mfma_f32_16x16x32_bf16 v[116:119], v[156:159], v[164:167], v[116:119]
	v_mfma_f32_16x16x32_bf16 v[100:103], v[144:147], v[168:171], v[100:103]
	v_mfma_f32_16x16x32_bf16 v[100:103], v[148:151], v[172:175], v[100:103]
	v_mfma_f32_16x16x32_bf16 v[92:95], v[152:155], v[168:171], v[92:95]
	v_mfma_f32_16x16x32_bf16 v[92:95], v[156:159], v[172:175], v[92:95]
	v_mfma_f32_16x16x32_bf16 v[80:83], v[144:147], v[186:189], v[80:83]
	v_mfma_f32_16x16x32_bf16 v[80:83], v[148:151], v[190:193], v[80:83]
	v_mfma_f32_16x16x32_bf16 v[76:79], v[152:155], v[186:189], v[76:79]
	v_mfma_f32_16x16x32_bf16 v[76:79], v[156:159], v[190:193], v[76:79]
	v_mfma_f32_16x16x32_bf16 v[68:71], v[144:147], v[200:203], v[68:71]
	v_mfma_f32_16x16x32_bf16 v[68:71], v[148:151], v[204:207], v[68:71]
	v_mfma_f32_16x16x32_bf16 v[64:67], v[152:155], v[200:203], v[64:67]
	v_mfma_f32_16x16x32_bf16 v[64:67], v[156:159], v[204:207], v[64:67]
	s_barrier
	s_setprio 0
	s_add_u32 s56, s84, 0x80
	s_addc_u32 s57, s85, 0
	s_add_i32 s86, s86, s97
	s_mov_b32 m0, s86
	ds_read_b128 v[160:163], v185 offset:49152
	ds_read_b128 v[164:167], v185 offset:50176
	ds_read_b128 v[168:171], v185 offset:51200
	ds_read_b128 v[172:175], v185 offset:52224
	ds_read_b128 v[186:189], v185 offset:53248
	ds_read_b128 v[190:193], v185 offset:54272
	ds_read_b128 v[200:203], v185 offset:55296
	ds_read_b128 v[204:207], v185 offset:56320
	s_nop 0
	global_load_lds_dwordx4 v181, s[56:57]
	s_add_i32 m0, s86, 0x2000
	s_nop 0
	global_load_lds_dwordx4 v183, s[56:57]
	s_add_u32 s56, s84, 0x80080
	s_addc_u32 s57, s85, 0
	s_add_i32 s84, s87, s97
	s_mov_b32 m0, s84
	s_nop 0
	global_load_lds_dwordx4 v181, s[56:57]
	s_add_i32 m0, s84, 0x2000
	s_nop 0
	global_load_lds_dwordx4 v183, s[56:57]
	s_mov_b32 m0, s81
	s_nop 0
	global_load_lds_dwordx4 v179, s[12:13]
	s_mov_b32 m0, s70
	s_nop 0
	global_load_lds_dwordx4 v182, s[12:13]
	s_nop 0
	s_nop 0
	s_nop 0
	s_nop 0
	s_nop 0
	s_nop 0
	s_nop 0
	s_nop 0
	s_waitcnt vmcnt(8)
	s_waitcnt lgkmcnt(0)
	s_setprio 1
	s_barrier
	v_mfma_f32_16x16x32_bf16 v[60:63], v[104:107], v[160:163], v[60:63]
	v_mfma_f32_16x16x32_bf16 v[60:63], v[108:111], v[164:167], v[60:63]
	v_mfma_f32_16x16x32_bf16 v[56:59], v[132:135], v[160:163], v[56:59]
	v_mfma_f32_16x16x32_bf16 v[56:59], v[136:139], v[164:167], v[56:59]
	v_mfma_f32_16x16x32_bf16 v[48:51], v[104:107], v[168:171], v[48:51]
	v_mfma_f32_16x16x32_bf16 v[48:51], v[108:111], v[172:175], v[48:51]
	v_mfma_f32_16x16x32_bf16 v[40:43], v[132:135], v[168:171], v[40:43]
	v_mfma_f32_16x16x32_bf16 v[40:43], v[136:139], v[172:175], v[40:43]
	v_mfma_f32_16x16x32_bf16 v[32:35], v[104:107], v[186:189], v[32:35]
	v_mfma_f32_16x16x32_bf16 v[32:35], v[108:111], v[190:193], v[32:35]
	v_mfma_f32_16x16x32_bf16 v[24:27], v[132:135], v[186:189], v[24:27]
	v_mfma_f32_16x16x32_bf16 v[24:27], v[136:139], v[190:193], v[24:27]
	v_mfma_f32_16x16x32_bf16 v[16:19], v[104:107], v[200:203], v[16:19]
	v_mfma_f32_16x16x32_bf16 v[16:19], v[108:111], v[204:207], v[16:19]
	v_mfma_f32_16x16x32_bf16 v[8:11], v[132:135], v[200:203], v[8:11]
	v_mfma_f32_16x16x32_bf16 v[8:11], v[136:139], v[204:207], v[8:11]
	v_mfma_f32_16x16x32_bf16 v[52:55], v[144:147], v[160:163], v[52:55]
	v_mfma_f32_16x16x32_bf16 v[52:55], v[148:151], v[164:167], v[52:55]
	v_mfma_f32_16x16x32_bf16 v[44:47], v[152:155], v[160:163], v[44:47]
	v_mfma_f32_16x16x32_bf16 v[44:47], v[156:159], v[164:167], v[44:47]
	v_mfma_f32_16x16x32_bf16 v[36:39], v[144:147], v[168:171], v[36:39]
	v_mfma_f32_16x16x32_bf16 v[36:39], v[148:151], v[172:175], v[36:39]
	v_mfma_f32_16x16x32_bf16 v[28:31], v[152:155], v[168:171], v[28:31]
	v_mfma_f32_16x16x32_bf16 v[28:31], v[156:159], v[172:175], v[28:31]
	v_mfma_f32_16x16x32_bf16 v[20:23], v[144:147], v[186:189], v[20:23]
	v_mfma_f32_16x16x32_bf16 v[20:23], v[148:151], v[190:193], v[20:23]
	v_mfma_f32_16x16x32_bf16 v[12:15], v[152:155], v[186:189], v[12:15]
	v_mfma_f32_16x16x32_bf16 v[12:15], v[156:159], v[190:193], v[12:15]
	v_mfma_f32_16x16x32_bf16 v[4:7], v[144:147], v[200:203], v[4:7]
	v_mfma_f32_16x16x32_bf16 v[4:7], v[148:151], v[204:207], v[4:7]
	v_mfma_f32_16x16x32_bf16 v[0:3], v[152:155], v[200:203], v[0:3]
	v_mfma_f32_16x16x32_bf16 v[0:3], v[156:159], v[204:207], v[0:3]
	s_barrier
	s_setprio 0
	s_add_i32 s83, s83, 2
	s_add_u32 s39, s39, 0x100
	s_addc_u32 s69, s69, 0
	s_add_u32 s72, s72, 0x100
	s_addc_u32 s74, s74, 0
	s_add_u32 s8, s8, 0x100
	s_addc_u32 s9, s9, 0
	s_cmp_gt_u32 s83, 29
	s_cbranch_scc0 .LBB0_1050
	s_and_b64 vcc, exec, s[60:61]
	s_cbranch_vccz .LBB0_1053
	s_barrier

.LBB0_1127:
	s_cmp_eq_u32 s21, 4
	s_cselect_b32 s38, s22, s4
	s_cselect_b32 s39, s23, s5
	s_cselect_b32 s36, s24, s15
	s_cselect_b32 s37, s25, s17
	s_add_u32 s34, s38, 0x80
	s_addc_u32 s35, s39, 0
	s_add_i32 s65, 0, 0x10000
	s_add_i32 s69, 0, 0x14000
	v_add_u32_e32 v132, s65, v154
	v_add_u32_e32 v148, s69, v154
	ds_read_b128 v[112:115], v132
	ds_read_b128 v[120:123], v132 offset:1024
	ds_read_b128 v[128:131], v132 offset:2048
	ds_read_b128 v[132:135], v132 offset:3072
	ds_read_b128 v[144:147], v148
	ds_read_b128 v[156:159], v148 offset:1024
	ds_read_b128 v[160:163], v148 offset:2048
	ds_read_b128 v[164:167], v148 offset:3072
	s_add_u32 s56, s4, 0x7ff80
	s_addc_u32 s57, s5, 0
	s_add_i32 m0, s27, 0xc000
	ds_read_b128 v[168:171], v155
	ds_read_b128 v[172:175], v155 offset:1024
	ds_read_b128 v[176:179], v155 offset:2048
	ds_read_b128 v[180:183], v155 offset:3072
	ds_read_b128 v[184:187], v155 offset:4096
	ds_read_b128 v[188:191], v155 offset:5120
	ds_read_b128 v[192:195], v155 offset:6144
	ds_read_b128 v[200:203], v155 offset:7168
	s_nop 0
	global_load_lds_dwordx4 v151, s[56:57]
	s_add_i32 m0, s27, 0xe000
	s_nop 0
	global_load_lds_dwordx4 v150, s[56:57]
	s_nop 0
	s_nop 0
	s_nop 0
	s_nop 0
	s_nop 0
	s_nop 0
	s_nop 0
	s_nop 0
	s_nop 0
	s_nop 0
	s_waitcnt vmcnt(8)
	s_waitcnt lgkmcnt(0)
	s_setprio 1
	s_barrier
	v_mfma_f32_16x16x32_bf16 v[140:143], v[112:115], v[168:171], v[140:143]
	v_mfma_f32_16x16x32_bf16 v[140:143], v[120:123], v[172:175], v[140:143]
	v_mfma_f32_16x16x32_bf16 v[136:139], v[128:131], v[168:171], v[136:139]
	v_mfma_f32_16x16x32_bf16 v[136:139], v[132:135], v[172:175], v[136:139]
	v_mfma_f32_16x16x32_bf16 v[108:111], v[112:115], v[176:179], v[108:111]
	v_mfma_f32_16x16x32_bf16 v[108:111], v[120:123], v[180:183], v[108:111]
	v_mfma_f32_16x16x32_bf16 v[104:107], v[128:131], v[176:179], v[104:107]
	v_mfma_f32_16x16x32_bf16 v[104:107], v[132:135], v[180:183], v[104:107]
	v_mfma_f32_16x16x32_bf16 v[92:95], v[112:115], v[184:187], v[92:95]
	v_mfma_f32_16x16x32_bf16 v[92:95], v[120:123], v[188:191], v[92:95]
	v_mfma_f32_16x16x32_bf16 v[88:91], v[128:131], v[184:187], v[88:91]
	v_mfma_f32_16x16x32_bf16 v[88:91], v[132:135], v[188:191], v[88:91]
	v_mfma_f32_16x16x32_bf16 v[76:79], v[112:115], v[192:195], v[76:79]
	v_mfma_f32_16x16x32_bf16 v[76:79], v[120:123], v[200:203], v[76:79]
	v_mfma_f32_16x16x32_bf16 v[72:75], v[128:131], v[192:195], v[72:75]
	v_mfma_f32_16x16x32_bf16 v[72:75], v[132:135], v[200:203], v[72:75]
	v_mfma_f32_16x16x32_bf16 v[124:127], v[144:147], v[168:171], v[124:127]
	v_mfma_f32_16x16x32_bf16 v[124:127], v[156:159], v[172:175], v[124:127]
	v_mfma_f32_16x16x32_bf16 v[116:119], v[160:163], v[168:171], v[116:119]
	v_mfma_f32_16x16x32_bf16 v[116:119], v[164:167], v[172:175], v[116:119]
	v_mfma_f32_16x16x32_bf16 v[100:103], v[144:147], v[176:179], v[100:103]
	v_mfma_f32_16x16x32_bf16 v[100:103], v[156:159], v[180:183], v[100:103]
	v_mfma_f32_16x16x32_bf16 v[96:99], v[160:163], v[176:179], v[96:99]
	v_mfma_f32_16x16x32_bf16 v[96:99], v[164:167], v[180:183], v[96:99]
	v_mfma_f32_16x16x32_bf16 v[84:87], v[144:147], v[184:187], v[84:87]
	v_mfma_f32_16x16x32_bf16 v[84:87], v[156:159], v[188:191], v[84:87]
	v_mfma_f32_16x16x32_bf16 v[80:83], v[160:163], v[184:187], v[80:83]
	v_mfma_f32_16x16x32_bf16 v[80:83], v[164:167], v[188:191], v[80:83]
	v_mfma_f32_16x16x32_bf16 v[68:71], v[144:147], v[192:195], v[68:71]
	v_mfma_f32_16x16x32_bf16 v[68:71], v[156:159], v[200:203], v[68:71]
	v_mfma_f32_16x16x32_bf16 v[64:67], v[160:163], v[192:195], v[64:67]
	v_mfma_f32_16x16x32_bf16 v[64:67], v[164:167], v[200:203], v[64:67]
	s_barrier
	s_setprio 0
	s_add_i32 s65, s65, s97
	s_mov_b64 s[56:57], s[36:37]
	s_mov_b32 m0, s65
	ds_read_b128 v[168:171], v155 offset:16384
	ds_read_b128 v[172:175], v155 offset:17408
	ds_read_b128 v[176:179], v155 offset:18432
	ds_read_b128 v[180:183], v155 offset:19456
	ds_read_b128 v[184:187], v155 offset:20480
	ds_read_b128 v[188:191], v155 offset:21504
	ds_read_b128 v[192:195], v155 offset:22528
	ds_read_b128 v[200:203], v155 offset:23552
	s_nop 0
	global_load_lds_dwordx4 v152, s[56:57]
	s_add_i32 m0, s65, 0x2000
	s_nop 0
	global_load_lds_dwordx4 v153, s[56:57]
	s_add_u32 s56, s36, 0x80000
	s_addc_u32 s57, s37, 0
	s_add_i32 s65, s69, s97
	s_mov_b32 m0, s65
	s_nop 0
	global_load_lds_dwordx4 v152, s[56:57]
	s_add_i32 m0, s65, 0x2000
	s_nop 0
	global_load_lds_dwordx4 v153, s[56:57]
	s_mov_b64 s[56:57], s[38:39]
	s_mov_b32 m0, s27
	s_nop 0
	global_load_lds_dwordx4 v151, s[56:57]
	s_mov_b32 m0, s29
	s_nop 0
	global_load_lds_dwordx4 v150, s[56:57]
	s_nop 0
	s_nop 0
	s_nop 0
	s_nop 0
	s_nop 0
	s_nop 0
	s_nop 0
	s_nop 0
	s_nop 0
	s_waitcnt vmcnt(8)
	s_waitcnt lgkmcnt(0)
	s_setprio 1
	s_barrier
	v_mfma_f32_16x16x32_bf16 v[60:63], v[112:115], v[168:171], v[60:63]
	v_mfma_f32_16x16x32_bf16 v[60:63], v[120:123], v[172:175], v[60:63]
	v_mfma_f32_16x16x32_bf16 v[56:59], v[128:131], v[168:171], v[56:59]
	v_mfma_f32_16x16x32_bf16 v[56:59], v[132:135], v[172:175], v[56:59]
	v_mfma_f32_16x16x32_bf16 v[52:55], v[112:115], v[176:179], v[52:55]
	v_mfma_f32_16x16x32_bf16 v[52:55], v[120:123], v[180:183], v[52:55]
	v_mfma_f32_16x16x32_bf16 v[44:47], v[128:131], v[176:179], v[44:47]
	v_mfma_f32_16x16x32_bf16 v[44:47], v[132:135], v[180:183], v[44:47]
	v_mfma_f32_16x16x32_bf16 v[36:39], v[112:115], v[184:187], v[36:39]
	v_mfma_f32_16x16x32_bf16 v[36:39], v[120:123], v[188:191], v[36:39]
	v_mfma_f32_16x16x32_bf16 v[28:31], v[128:131], v[184:187], v[28:31]
	v_mfma_f32_16x16x32_bf16 v[28:31], v[132:135], v[188:191], v[28:31]
	v_mfma_f32_16x16x32_bf16 v[20:23], v[112:115], v[192:195], v[20:23]
	v_mfma_f32_16x16x32_bf16 v[20:23], v[120:123], v[200:203], v[20:23]
	v_mfma_f32_16x16x32_bf16 v[8:11], v[128:131], v[192:195], v[8:11]
	v_mfma_f32_16x16x32_bf16 v[8:11], v[132:135], v[200:203], v[8:11]
	v_mfma_f32_16x16x32_bf16 v[48:51], v[144:147], v[168:171], v[48:51]
	v_mfma_f32_16x16x32_bf16 v[48:51], v[156:159], v[172:175], v[48:51]
	v_mfma_f32_16x16x32_bf16 v[40:43], v[160:163], v[168:171], v[40:43]
	v_mfma_f32_16x16x32_bf16 v[40:43], v[164:167], v[172:175], v[40:43]
	v_mfma_f32_16x16x32_bf16 v[32:35], v[144:147], v[176:179], v[32:35]
	v_mfma_f32_16x16x32_bf16 v[32:35], v[156:159], v[180:183], v[32:35]
	v_mfma_f32_16x16x32_bf16 v[24:27], v[160:163], v[176:179], v[24:27]
	v_mfma_f32_16x16x32_bf16 v[24:27], v[164:167], v[180:183], v[24:27]
	v_mfma_f32_16x16x32_bf16 v[16:19], v[144:147], v[184:187], v[16:19]
	v_mfma_f32_16x16x32_bf16 v[16:19], v[156:159], v[188:191], v[16:19]
	v_mfma_f32_16x16x32_bf16 v[12:15], v[160:163], v[184:187], v[12:15]
	v_mfma_f32_16x16x32_bf16 v[12:15], v[164:167], v[188:191], v[12:15]
	v_mfma_f32_16x16x32_bf16 v[4:7], v[144:147], v[192:195], v[4:7]
	v_mfma_f32_16x16x32_bf16 v[4:7], v[156:159], v[200:203], v[4:7]
	v_mfma_f32_16x16x32_bf16 v[0:3], v[160:163], v[192:195], v[0:3]
	v_mfma_f32_16x16x32_bf16 v[0:3], v[164:167], v[200:203], v[0:3]
	s_barrier
	s_setprio 0
	s_add_i32 s56, 0, 0x18000
	s_add_i32 s57, 0, 0x1c000
	v_add_u32_e32 v132, s56, v154
	v_add_u32_e32 v148, s57, v154
	ds_read_b128 v[112:115], v132
	ds_read_b128 v[120:123], v132 offset:1024
	ds_read_b128 v[128:131], v132 offset:2048
	ds_read_b128 v[132:135], v132 offset:3072
	ds_read_b128 v[144:147], v148
	ds_read_b128 v[156:159], v148 offset:1024
	ds_read_b128 v[160:163], v148 offset:2048
	ds_read_b128 v[164:167], v148 offset:3072
	s_add_u32 s38, s38, 0x80000
	s_addc_u32 s39, s39, 0
	s_mov_b32 m0, s31
	ds_read_b128 v[168:171], v155 offset:32768
	ds_read_b128 v[172:175], v155 offset:33792
	ds_read_b128 v[176:179], v155 offset:34816
	ds_read_b128 v[180:183], v155 offset:35840
	ds_read_b128 v[184:187], v155 offset:36864
	ds_read_b128 v[188:191], v155 offset:37888
	ds_read_b128 v[192:195], v155 offset:38912
	ds_read_b128 v[200:203], v155 offset:39936
	s_nop 0
	global_load_lds_dwordx4 v151, s[38:39]
	s_mov_b32 m0, s46
	s_nop 0
	global_load_lds_dwordx4 v150, s[38:39]
	s_nop 0
	s_nop 0
	s_nop 0
	s_nop 0
	s_nop 0
	s_nop 0
	s_nop 0
	s_nop 0
	s_nop 0
	s_waitcnt vmcnt(8)
	s_waitcnt lgkmcnt(0)
	s_setprio 1
	s_barrier
	v_mfma_f32_16x16x32_bf16 v[140:143], v[112:115], v[168:171], v[140:143]
	v_mfma_f32_16x16x32_bf16 v[140:143], v[120:123], v[172:175], v[140:143]
	v_mfma_f32_16x16x32_bf16 v[136:139], v[128:131], v[168:171], v[136:139]
	v_mfma_f32_16x16x32_bf16 v[136:139], v[132:135], v[172:175], v[136:139]
	v_mfma_f32_16x16x32_bf16 v[108:111], v[112:115], v[176:179], v[108:111]
	v_mfma_f32_16x16x32_bf16 v[108:111], v[120:123], v[180:183], v[108:111]
	v_mfma_f32_16x16x32_bf16 v[104:107], v[128:131], v[176:179], v[104:107]
	v_mfma_f32_16x16x32_bf16 v[104:107], v[132:135], v[180:183], v[104:107]
	v_mfma_f32_16x16x32_bf16 v[92:95], v[112:115], v[184:187], v[92:95]
	v_mfma_f32_16x16x32_bf16 v[92:95], v[120:123], v[188:191], v[92:95]
	v_mfma_f32_16x16x32_bf16 v[88:91], v[128:131], v[184:187], v[88:91]
	v_mfma_f32_16x16x32_bf16 v[88:91], v[132:135], v[188:191], v[88:91]
	v_mfma_f32_16x16x32_bf16 v[76:79], v[112:115], v[192:195], v[76:79]
	v_mfma_f32_16x16x32_bf16 v[76:79], v[120:123], v[200:203], v[76:79]
	v_mfma_f32_16x16x32_bf16 v[72:75], v[128:131], v[192:195], v[72:75]
	v_mfma_f32_16x16x32_bf16 v[72:75], v[132:135], v[200:203], v[72:75]
	v_mfma_f32_16x16x32_bf16 v[124:127], v[144:147], v[168:171], v[124:127]
	v_mfma_f32_16x16x32_bf16 v[124:127], v[156:159], v[172:175], v[124:127]
	v_mfma_f32_16x16x32_bf16 v[116:119], v[160:163], v[168:171], v[116:119]
	v_mfma_f32_16x16x32_bf16 v[116:119], v[164:167], v[172:175], v[116:119]
	v_mfma_f32_16x16x32_bf16 v[100:103], v[144:147], v[176:179], v[100:103]
	v_mfma_f32_16x16x32_bf16 v[100:103], v[156:159], v[180:183], v[100:103]
	v_mfma_f32_16x16x32_bf16 v[96:99], v[160:163], v[176:179], v[96:99]
	v_mfma_f32_16x16x32_bf16 v[96:99], v[164:167], v[180:183], v[96:99]
	v_mfma_f32_16x16x32_bf16 v[84:87], v[144:147], v[184:187], v[84:87]
	v_mfma_f32_16x16x32_bf16 v[84:87], v[156:159], v[188:191], v[84:87]
	v_mfma_f32_16x16x32_bf16 v[80:83], v[160:163], v[184:187], v[80:83]
	v_mfma_f32_16x16x32_bf16 v[80:83], v[164:167], v[188:191], v[80:83]
	v_mfma_f32_16x16x32_bf16 v[68:71], v[144:147], v[192:195], v[68:71]
	v_mfma_f32_16x16x32_bf16 v[68:71], v[156:159], v[200:203], v[68:71]
	v_mfma_f32_16x16x32_bf16 v[64:67], v[160:163], v[192:195], v[64:67]
	v_mfma_f32_16x16x32_bf16 v[64:67], v[164:167], v[200:203], v[64:67]
	s_barrier
	s_setprio 0
	s_add_u32 s38, s36, 0x80
	s_addc_u32 s39, s37, 0
	s_add_i32 s56, s56, s97
	s_mov_b32 m0, s56
	ds_read_b128 v[168:171], v155 offset:49152
	ds_read_b128 v[172:175], v155 offset:50176
	ds_read_b128 v[176:179], v155 offset:51200
	ds_read_b128 v[180:183], v155 offset:52224
	ds_read_b128 v[184:187], v155 offset:53248
	ds_read_b128 v[188:191], v155 offset:54272
	ds_read_b128 v[192:195], v155 offset:55296
	ds_read_b128 v[200:203], v155 offset:56320
	s_nop 0
	global_load_lds_dwordx4 v152, s[38:39]
	s_add_i32 m0, s56, 0x2000
	s_add_u32 s36, s36, 0x80080
	s_addc_u32 s37, s37, 0
	global_load_lds_dwordx4 v153, s[38:39]
	s_add_i32 s38, s57, s97
	s_mov_b32 m0, s38
	s_nop 0
	global_load_lds_dwordx4 v152, s[36:37]
	s_add_i32 m0, s38, 0x2000
	s_nop 0
	global_load_lds_dwordx4 v153, s[36:37]
	s_mov_b32 m0, s47
	s_nop 0
	global_load_lds_dwordx4 v151, s[34:35]
	s_mov_b32 m0, s48
	s_nop 0
	global_load_lds_dwordx4 v150, s[34:35]
	s_nop 0
	s_nop 0
	s_nop 0
	s_nop 0
	s_nop 0
	s_nop 0
	s_nop 0
	s_nop 0
	s_nop 0
	s_waitcnt vmcnt(8)
	s_waitcnt lgkmcnt(0)
	s_setprio 1
	s_barrier
	v_mfma_f32_16x16x32_bf16 v[60:63], v[112:115], v[168:171], v[60:63]
	v_mfma_f32_16x16x32_bf16 v[60:63], v[120:123], v[172:175], v[60:63]
	v_mfma_f32_16x16x32_bf16 v[56:59], v[128:131], v[168:171], v[56:59]
	v_mfma_f32_16x16x32_bf16 v[56:59], v[132:135], v[172:175], v[56:59]
	v_mfma_f32_16x16x32_bf16 v[52:55], v[112:115], v[176:179], v[52:55]
	v_mfma_f32_16x16x32_bf16 v[52:55], v[120:123], v[180:183], v[52:55]
	v_mfma_f32_16x16x32_bf16 v[44:47], v[128:131], v[176:179], v[44:47]
	v_mfma_f32_16x16x32_bf16 v[44:47], v[132:135], v[180:183], v[44:47]
	v_mfma_f32_16x16x32_bf16 v[36:39], v[112:115], v[184:187], v[36:39]
	v_mfma_f32_16x16x32_bf16 v[36:39], v[120:123], v[188:191], v[36:39]
	v_mfma_f32_16x16x32_bf16 v[28:31], v[128:131], v[184:187], v[28:31]
	v_mfma_f32_16x16x32_bf16 v[28:31], v[132:135], v[188:191], v[28:31]
	v_mfma_f32_16x16x32_bf16 v[20:23], v[112:115], v[192:195], v[20:23]
	v_mfma_f32_16x16x32_bf16 v[20:23], v[120:123], v[200:203], v[20:23]
	v_mfma_f32_16x16x32_bf16 v[8:11], v[128:131], v[192:195], v[8:11]
	v_mfma_f32_16x16x32_bf16 v[8:11], v[132:135], v[200:203], v[8:11]
	v_mfma_f32_16x16x32_bf16 v[48:51], v[144:147], v[168:171], v[48:51]
	v_mfma_f32_16x16x32_bf16 v[48:51], v[156:159], v[172:175], v[48:51]
	v_mfma_f32_16x16x32_bf16 v[40:43], v[160:163], v[168:171], v[40:43]
	v_mfma_f32_16x16x32_bf16 v[40:43], v[164:167], v[172:175], v[40:43]
	v_mfma_f32_16x16x32_bf16 v[32:35], v[144:147], v[176:179], v[32:35]
	v_mfma_f32_16x16x32_bf16 v[32:35], v[156:159], v[180:183], v[32:35]
	v_mfma_f32_16x16x32_bf16 v[24:27], v[160:163], v[176:179], v[24:27]
	v_mfma_f32_16x16x32_bf16 v[24:27], v[164:167], v[180:183], v[24:27]
	v_mfma_f32_16x16x32_bf16 v[16:19], v[144:147], v[184:187], v[16:19]
	v_mfma_f32_16x16x32_bf16 v[16:19], v[156:159], v[188:191], v[16:19]
	v_mfma_f32_16x16x32_bf16 v[12:15], v[160:163], v[184:187], v[12:15]
	v_mfma_f32_16x16x32_bf16 v[12:15], v[164:167], v[188:191], v[12:15]
	v_mfma_f32_16x16x32_bf16 v[4:7], v[144:147], v[192:195], v[4:7]
	v_mfma_f32_16x16x32_bf16 v[4:7], v[156:159], v[200:203], v[4:7]
	v_mfma_f32_16x16x32_bf16 v[0:3], v[160:163], v[192:195], v[0:3]
	v_mfma_f32_16x16x32_bf16 v[0:3], v[164:167], v[200:203], v[0:3]
	s_barrier
	s_setprio 0
	s_add_i32 s21, s21, 2
	s_add_u32 s4, s4, 0x100
	s_addc_u32 s5, s5, 0
	s_add_u32 s15, s15, 0x100
	s_addc_u32 s17, s17, 0
	s_cmp_gt_u32 s21, 5
	s_cbranch_scc0 .LBB0_1127
	s_and_b64 vcc, exec, s[60:61]
	s_cbranch_vccz .LBB0_1130
	s_barrier

.LBB0_1253:
	s_add_u32 s34, s10, 0x100
	s_addc_u32 s35, s11, 0
	s_cmp_eq_u32 vcc_hi, 28
	s_cselect_b32 s40, s5, s34
	s_cselect_b32 s41, s4, s35
	s_cselect_b32 s38, s25, s27
	s_cselect_b32 s39, s9, vcc_lo
	s_add_u32 s36, s40, 0x80
	s_addc_u32 s37, s41, 0
	s_add_i32 s75, 0, 0x10000
	s_add_i32 s46, 0, 0x14000
	v_add_u32_e32 v140, s75, v196
	v_add_u32_e32 v156, s46, v196
	ds_read_b128 v[128:131], v140
	ds_read_b128 v[132:135], v140 offset:1024
	ds_read_b128 v[136:139], v140 offset:2048
	ds_read_b128 v[140:143], v140 offset:3072
	ds_read_b128 v[144:147], v156
	ds_read_b128 v[148:151], v156 offset:1024
	ds_read_b128 v[152:155], v156 offset:2048
	ds_read_b128 v[156:159], v156 offset:3072
	s_add_u32 s10, s10, 0x80080
	s_addc_u32 s11, s11, 0
	s_add_i32 m0, s15, 0xc000
	ds_read_b128 v[160:163], v200
	ds_read_b128 v[164:167], v200 offset:1024
	ds_read_b128 v[168:171], v200 offset:2048
	ds_read_b128 v[172:175], v200 offset:3072
	ds_read_b128 v[176:179], v200 offset:4096
	ds_read_b128 v[180:183], v200 offset:5120
	ds_read_b128 v[184:187], v200 offset:6144
	ds_read_b128 v[188:191], v200 offset:7168
	s_nop 0
	global_load_lds_dwordx4 v192, s[10:11]
	s_add_i32 m0, s15, 0xe000
	s_nop 0
	global_load_lds_dwordx4 v194, s[10:11]
	s_nop 0
	s_nop 0
	s_waitcnt vmcnt(8)
	s_waitcnt lgkmcnt(0)
	s_setprio 1
	s_barrier
	v_mfma_f32_16x16x32_bf16 v[124:127], v[128:131], v[160:163], v[124:127]
	v_mfma_f32_16x16x32_bf16 v[124:127], v[132:135], v[164:167], v[124:127]
	v_mfma_f32_16x16x32_bf16 v[60:63], v[136:139], v[160:163], v[60:63]
	v_mfma_f32_16x16x32_bf16 v[60:63], v[140:143], v[164:167], v[60:63]
	v_mfma_f32_16x16x32_bf16 v[120:123], v[128:131], v[168:171], v[120:123]
	v_mfma_f32_16x16x32_bf16 v[120:123], v[132:135], v[172:175], v[120:123]
	v_mfma_f32_16x16x32_bf16 v[56:59], v[136:139], v[168:171], v[56:59]
	v_mfma_f32_16x16x32_bf16 v[56:59], v[140:143], v[172:175], v[56:59]
	v_mfma_f32_16x16x32_bf16 v[116:119], v[128:131], v[176:179], v[116:119]
	v_mfma_f32_16x16x32_bf16 v[116:119], v[132:135], v[180:183], v[116:119]
	v_mfma_f32_16x16x32_bf16 v[52:55], v[136:139], v[176:179], v[52:55]
	v_mfma_f32_16x16x32_bf16 v[52:55], v[140:143], v[180:183], v[52:55]
	v_mfma_f32_16x16x32_bf16 v[112:115], v[128:131], v[184:187], v[112:115]
	v_mfma_f32_16x16x32_bf16 v[112:115], v[132:135], v[188:191], v[112:115]
	v_mfma_f32_16x16x32_bf16 v[48:51], v[136:139], v[184:187], v[48:51]
	v_mfma_f32_16x16x32_bf16 v[48:51], v[140:143], v[188:191], v[48:51]
	v_mfma_f32_16x16x32_bf16 v[108:111], v[144:147], v[160:163], v[108:111]
	v_mfma_f32_16x16x32_bf16 v[108:111], v[148:151], v[164:167], v[108:111]
	v_mfma_f32_16x16x32_bf16 v[44:47], v[152:155], v[160:163], v[44:47]
	v_mfma_f32_16x16x32_bf16 v[44:47], v[156:159], v[164:167], v[44:47]
	v_mfma_f32_16x16x32_bf16 v[104:107], v[144:147], v[168:171], v[104:107]
	v_mfma_f32_16x16x32_bf16 v[104:107], v[148:151], v[172:175], v[104:107]
	v_mfma_f32_16x16x32_bf16 v[40:43], v[152:155], v[168:171], v[40:43]
	v_mfma_f32_16x16x32_bf16 v[40:43], v[156:159], v[172:175], v[40:43]
	v_mfma_f32_16x16x32_bf16 v[100:103], v[144:147], v[176:179], v[100:103]
	v_mfma_f32_16x16x32_bf16 v[100:103], v[148:151], v[180:183], v[100:103]
	v_mfma_f32_16x16x32_bf16 v[36:39], v[152:155], v[176:179], v[36:39]
	v_mfma_f32_16x16x32_bf16 v[36:39], v[156:159], v[180:183], v[36:39]
	v_mfma_f32_16x16x32_bf16 v[96:99], v[144:147], v[184:187], v[96:99]
	v_mfma_f32_16x16x32_bf16 v[96:99], v[148:151], v[188:191], v[96:99]
	v_mfma_f32_16x16x32_bf16 v[32:35], v[152:155], v[184:187], v[32:35]
	v_mfma_f32_16x16x32_bf16 v[32:35], v[156:159], v[188:191], v[32:35]
	s_barrier
	s_setprio 0
	s_add_i32 s47, s75, s97
	s_mov_b64 s[10:11], s[38:39]
	s_mov_b32 m0, s47
	ds_read_b128 v[160:163], v200 offset:16384
	ds_read_b128 v[164:167], v200 offset:17408
	ds_read_b128 v[168:171], v200 offset:18432
	ds_read_b128 v[172:175], v200 offset:19456
	ds_read_b128 v[176:179], v200 offset:20480
	ds_read_b128 v[180:183], v200 offset:21504
	ds_read_b128 v[184:187], v200 offset:22528
	ds_read_b128 v[188:191], v200 offset:23552
	s_nop 0
	global_load_lds_dwordx4 v193, s[10:11]
	s_add_i32 m0, s47, 0x2000
	s_nop 0
	global_load_lds_dwordx4 v195, s[10:11]
	s_add_u32 s10, s38, 0x80000
	s_addc_u32 s11, s39, 0
	s_add_i32 s46, s46, s97
	s_mov_b32 m0, s46
	s_nop 0
	global_load_lds_dwordx4 v193, s[10:11]
	s_add_i32 m0, s46, 0x2000
	s_nop 0
	global_load_lds_dwordx4 v195, s[10:11]
	s_mov_b64 s[10:11], s[40:41]
	s_mov_b32 m0, s15
	s_nop 0
	global_load_lds_dwordx4 v192, s[10:11]
	s_mov_b32 m0, s69
	s_nop 0
	global_load_lds_dwordx4 v194, s[10:11]
	s_nop 0
	s_nop 0
	s_nop 0
	s_nop 0
	s_nop 0
	s_nop 0
	s_nop 0
	s_nop 0
	s_nop 0
	s_waitcnt vmcnt(8)
	s_waitcnt lgkmcnt(0)
	s_setprio 1
	s_barrier
	v_mfma_f32_16x16x32_bf16 v[92:95], v[128:131], v[160:163], v[92:95]
	v_mfma_f32_16x16x32_bf16 v[92:95], v[132:135], v[164:167], v[92:95]
	v_mfma_f32_16x16x32_bf16 v[28:31], v[136:139], v[160:163], v[28:31]
	v_mfma_f32_16x16x32_bf16 v[28:31], v[140:143], v[164:167], v[28:31]
	v_mfma_f32_16x16x32_bf16 v[88:91], v[128:131], v[168:171], v[88:91]
	v_mfma_f32_16x16x32_bf16 v[88:91], v[132:135], v[172:175], v[88:91]
	v_mfma_f32_16x16x32_bf16 v[16:19], v[136:139], v[168:171], v[16:19]
	v_mfma_f32_16x16x32_bf16 v[16:19], v[140:143], v[172:175], v[16:19]
	v_mfma_f32_16x16x32_bf16 v[84:87], v[128:131], v[176:179], v[84:87]
	v_mfma_f32_16x16x32_bf16 v[84:87], v[132:135], v[180:183], v[84:87]
	v_mfma_f32_16x16x32_bf16 v[20:23], v[136:139], v[176:179], v[20:23]
	v_mfma_f32_16x16x32_bf16 v[20:23], v[140:143], v[180:183], v[20:23]
	v_mfma_f32_16x16x32_bf16 v[80:83], v[128:131], v[184:187], v[80:83]
	v_mfma_f32_16x16x32_bf16 v[80:83], v[132:135], v[188:191], v[80:83]
	v_mfma_f32_16x16x32_bf16 v[8:11], v[136:139], v[184:187], v[8:11]
	v_mfma_f32_16x16x32_bf16 v[8:11], v[140:143], v[188:191], v[8:11]
	v_mfma_f32_16x16x32_bf16 v[76:79], v[144:147], v[160:163], v[76:79]
	v_mfma_f32_16x16x32_bf16 v[76:79], v[148:151], v[164:167], v[76:79]
	v_mfma_f32_16x16x32_bf16 v[24:27], v[152:155], v[160:163], v[24:27]
	v_mfma_f32_16x16x32_bf16 v[24:27], v[156:159], v[164:167], v[24:27]
	v_mfma_f32_16x16x32_bf16 v[72:75], v[144:147], v[168:171], v[72:75]
	v_mfma_f32_16x16x32_bf16 v[72:75], v[148:151], v[172:175], v[72:75]
	v_mfma_f32_16x16x32_bf16 v[12:15], v[152:155], v[168:171], v[12:15]
	v_mfma_f32_16x16x32_bf16 v[12:15], v[156:159], v[172:175], v[12:15]
	v_mfma_f32_16x16x32_bf16 v[68:71], v[144:147], v[176:179], v[68:71]
	v_mfma_f32_16x16x32_bf16 v[68:71], v[148:151], v[180:183], v[68:71]
	v_mfma_f32_16x16x32_bf16 v[4:7], v[152:155], v[176:179], v[4:7]
	v_mfma_f32_16x16x32_bf16 v[4:7], v[156:159], v[180:183], v[4:7]
	v_mfma_f32_16x16x32_bf16 v[64:67], v[144:147], v[184:187], v[64:67]
	v_mfma_f32_16x16x32_bf16 v[64:67], v[148:151], v[188:191], v[64:67]
	v_mfma_f32_16x16x32_bf16 v[0:3], v[152:155], v[184:187], v[0:3]
	v_mfma_f32_16x16x32_bf16 v[0:3], v[156:159], v[188:191], v[0:3]
	s_barrier
	s_setprio 0
	s_add_i32 s46, 0, 0x18000
	s_add_i32 s47, 0, 0x1c000
	v_add_u32_e32 v140, s46, v196
	v_add_u32_e32 v156, s47, v196
	ds_read_b128 v[128:131], v140
	ds_read_b128 v[132:135], v140 offset:1024
	ds_read_b128 v[136:139], v140 offset:2048
	ds_read_b128 v[140:143], v140 offset:3072
	ds_read_b128 v[144:147], v156
	ds_read_b128 v[148:151], v156 offset:1024
	ds_read_b128 v[152:155], v156 offset:2048
	ds_read_b128 v[156:159], v156 offset:3072
	s_add_u32 s10, s40, 0x80000
	s_addc_u32 s11, s41, 0
	s_mov_b32 m0, s78
	ds_read_b128 v[160:163], v200 offset:32768
	ds_read_b128 v[164:167], v200 offset:33792
	ds_read_b128 v[168:171], v200 offset:34816
	ds_read_b128 v[172:175], v200 offset:35840
	ds_read_b128 v[176:179], v200 offset:36864
	ds_read_b128 v[180:183], v200 offset:37888
	ds_read_b128 v[184:187], v200 offset:38912
	ds_read_b128 v[188:191], v200 offset:39936
	s_nop 0
	global_load_lds_dwordx4 v192, s[10:11]
	s_mov_b32 m0, s80
	s_nop 0
	global_load_lds_dwordx4 v194, s[10:11]
	s_nop 0
	s_nop 0
	s_nop 0
	s_nop 0
	s_nop 0
	s_nop 0
	s_nop 0
	s_nop 0
	s_nop 0
	s_waitcnt vmcnt(8)
	s_waitcnt lgkmcnt(0)
	s_setprio 1
	s_barrier
	v_mfma_f32_16x16x32_bf16 v[124:127], v[128:131], v[160:163], v[124:127]
	v_mfma_f32_16x16x32_bf16 v[124:127], v[132:135], v[164:167], v[124:127]
	v_mfma_f32_16x16x32_bf16 v[60:63], v[136:139], v[160:163], v[60:63]
	v_mfma_f32_16x16x32_bf16 v[60:63], v[140:143], v[164:167], v[60:63]
	v_mfma_f32_16x16x32_bf16 v[120:123], v[128:131], v[168:171], v[120:123]
	v_mfma_f32_16x16x32_bf16 v[120:123], v[132:135], v[172:175], v[120:123]
	v_mfma_f32_16x16x32_bf16 v[56:59], v[136:139], v[168:171], v[56:59]
	v_mfma_f32_16x16x32_bf16 v[56:59], v[140:143], v[172:175], v[56:59]
	v_mfma_f32_16x16x32_bf16 v[116:119], v[128:131], v[176:179], v[116:119]
	v_mfma_f32_16x16x32_bf16 v[116:119], v[132:135], v[180:183], v[116:119]
	v_mfma_f32_16x16x32_bf16 v[52:55], v[136:139], v[176:179], v[52:55]
	v_mfma_f32_16x16x32_bf16 v[52:55], v[140:143], v[180:183], v[52:55]
	v_mfma_f32_16x16x32_bf16 v[112:115], v[128:131], v[184:187], v[112:115]
	v_mfma_f32_16x16x32_bf16 v[112:115], v[132:135], v[188:191], v[112:115]
	v_mfma_f32_16x16x32_bf16 v[48:51], v[136:139], v[184:187], v[48:51]
	v_mfma_f32_16x16x32_bf16 v[48:51], v[140:143], v[188:191], v[48:51]
	v_mfma_f32_16x16x32_bf16 v[108:111], v[144:147], v[160:163], v[108:111]
	v_mfma_f32_16x16x32_bf16 v[108:111], v[148:151], v[164:167], v[108:111]
	v_mfma_f32_16x16x32_bf16 v[44:47], v[152:155], v[160:163], v[44:47]
	v_mfma_f32_16x16x32_bf16 v[44:47], v[156:159], v[164:167], v[44:47]
	v_mfma_f32_16x16x32_bf16 v[104:107], v[144:147], v[168:171], v[104:107]
	v_mfma_f32_16x16x32_bf16 v[104:107], v[148:151], v[172:175], v[104:107]
	v_mfma_f32_16x16x32_bf16 v[40:43], v[152:155], v[168:171], v[40:43]
	v_mfma_f32_16x16x32_bf16 v[40:43], v[156:159], v[172:175], v[40:43]
	v_mfma_f32_16x16x32_bf16 v[100:103], v[144:147], v[176:179], v[100:103]
	v_mfma_f32_16x16x32_bf16 v[100:103], v[148:151], v[180:183], v[100:103]
	v_mfma_f32_16x16x32_bf16 v[36:39], v[152:155], v[176:179], v[36:39]
	v_mfma_f32_16x16x32_bf16 v[36:39], v[156:159], v[180:183], v[36:39]
	v_mfma_f32_16x16x32_bf16 v[96:99], v[144:147], v[184:187], v[96:99]
	v_mfma_f32_16x16x32_bf16 v[96:99], v[148:151], v[188:191], v[96:99]
	v_mfma_f32_16x16x32_bf16 v[32:35], v[152:155], v[184:187], v[32:35]
	v_mfma_f32_16x16x32_bf16 v[32:35], v[156:159], v[188:191], v[32:35]
	s_barrier
	s_setprio 0
	s_add_u32 s10, s38, 0x80
	s_addc_u32 s11, s39, 0
	s_add_i32 s40, s46, s97
	s_mov_b32 m0, s40
	ds_read_b128 v[160:163], v200 offset:49152
	ds_read_b128 v[164:167], v200 offset:50176
	ds_read_b128 v[168:171], v200 offset:51200
	ds_read_b128 v[172:175], v200 offset:52224
	ds_read_b128 v[176:179], v200 offset:53248
	ds_read_b128 v[180:183], v200 offset:54272
	ds_read_b128 v[184:187], v200 offset:55296
	ds_read_b128 v[188:191], v200 offset:56320
	s_nop 0
	global_load_lds_dwordx4 v193, s[10:11]
	s_add_i32 m0, s40, 0x2000
	s_nop 0
	global_load_lds_dwordx4 v195, s[10:11]
	s_add_u32 s10, s38, 0x80080
	s_addc_u32 s11, s39, 0
	s_add_i32 s38, s47, s97
	s_mov_b32 m0, s38
	s_nop 0
	global_load_lds_dwordx4 v193, s[10:11]
	s_add_i32 m0, s38, 0x2000
	s_nop 0
	global_load_lds_dwordx4 v195, s[10:11]
	s_mov_b32 m0, s85
	s_nop 0
	global_load_lds_dwordx4 v192, s[36:37]
	s_mov_b32 m0, s86
	s_nop 0
	global_load_lds_dwordx4 v194, s[36:37]
	s_nop 0
	s_nop 0
	s_nop 0
	s_nop 0
	s_nop 0
	s_nop 0
	s_nop 0
	s_nop 0
	s_waitcnt vmcnt(8)
	s_waitcnt lgkmcnt(0)
	s_setprio 1
	s_barrier
	v_mfma_f32_16x16x32_bf16 v[92:95], v[128:131], v[160:163], v[92:95]
	v_mfma_f32_16x16x32_bf16 v[92:95], v[132:135], v[164:167], v[92:95]
	v_mfma_f32_16x16x32_bf16 v[28:31], v[136:139], v[160:163], v[28:31]
	v_mfma_f32_16x16x32_bf16 v[28:31], v[140:143], v[164:167], v[28:31]
	v_mfma_f32_16x16x32_bf16 v[88:91], v[128:131], v[168:171], v[88:91]
	v_mfma_f32_16x16x32_bf16 v[88:91], v[132:135], v[172:175], v[88:91]
	v_mfma_f32_16x16x32_bf16 v[16:19], v[136:139], v[168:171], v[16:19]
	v_mfma_f32_16x16x32_bf16 v[16:19], v[140:143], v[172:175], v[16:19]
	v_mfma_f32_16x16x32_bf16 v[84:87], v[128:131], v[176:179], v[84:87]
	v_mfma_f32_16x16x32_bf16 v[84:87], v[132:135], v[180:183], v[84:87]
	v_mfma_f32_16x16x32_bf16 v[20:23], v[136:139], v[176:179], v[20:23]
	v_mfma_f32_16x16x32_bf16 v[20:23], v[140:143], v[180:183], v[20:23]
	v_mfma_f32_16x16x32_bf16 v[80:83], v[128:131], v[184:187], v[80:83]
	v_mfma_f32_16x16x32_bf16 v[80:83], v[132:135], v[188:191], v[80:83]
	v_mfma_f32_16x16x32_bf16 v[8:11], v[136:139], v[184:187], v[8:11]
	v_mfma_f32_16x16x32_bf16 v[8:11], v[140:143], v[188:191], v[8:11]
	v_mfma_f32_16x16x32_bf16 v[76:79], v[144:147], v[160:163], v[76:79]
	v_mfma_f32_16x16x32_bf16 v[76:79], v[148:151], v[164:167], v[76:79]
	v_mfma_f32_16x16x32_bf16 v[24:27], v[152:155], v[160:163], v[24:27]
	v_mfma_f32_16x16x32_bf16 v[24:27], v[156:159], v[164:167], v[24:27]
	v_mfma_f32_16x16x32_bf16 v[72:75], v[144:147], v[168:171], v[72:75]
	v_mfma_f32_16x16x32_bf16 v[72:75], v[148:151], v[172:175], v[72:75]
	v_mfma_f32_16x16x32_bf16 v[12:15], v[152:155], v[168:171], v[12:15]
	v_mfma_f32_16x16x32_bf16 v[12:15], v[156:159], v[172:175], v[12:15]
	v_mfma_f32_16x16x32_bf16 v[68:71], v[144:147], v[176:179], v[68:71]
	v_mfma_f32_16x16x32_bf16 v[68:71], v[148:151], v[180:183], v[68:71]
	v_mfma_f32_16x16x32_bf16 v[4:7], v[152:155], v[176:179], v[4:7]
	v_mfma_f32_16x16x32_bf16 v[4:7], v[156:159], v[180:183], v[4:7]
	v_mfma_f32_16x16x32_bf16 v[64:67], v[144:147], v[184:187], v[64:67]
	v_mfma_f32_16x16x32_bf16 v[64:67], v[148:151], v[188:191], v[64:67]
	v_mfma_f32_16x16x32_bf16 v[0:3], v[152:155], v[184:187], v[0:3]
	v_mfma_f32_16x16x32_bf16 v[0:3], v[156:159], v[188:191], v[0:3]
	s_barrier
	s_setprio 0
	s_add_i32 vcc_hi, vcc_hi, 2
	s_add_u32 s27, s27, 0x100
	s_addc_u32 vcc_lo, vcc_lo, 0
	s_cmp_gt_u32 vcc_hi, 29
	s_mov_b64 s[10:11], s[34:35]
	s_cbranch_scc0 .LBB0_1253
	v_mbcnt_lo_u32_b32 v205, -1, 0
	v_mbcnt_hi_u32_b32 v205, -1, v205
	v_and_b32_e32 v201, 15, v205
	v_ashrrev_i32_e32 v205, 1, v205
	v_and_b32_e32 v205, -8, v205
	v_add_u32_e32 v160, s68, v205
	v_lshl_add_u32 v176, s8, 7, v160
	v_ashrrev_i32_e32 v177, 31, v176
	v_lshlrev_b64 v[128:129], 2, v[176:177]
	v_lshl_add_u64 v[180:181], s[16:17], 0, v[128:129]
	v_add_co_u32_e32 v136, vcc, 0xb000, v180
	s_mov_b32 s4, 0x16000
	s_nop 0
	v_addc_co_u32_e32 v137, vcc, 0, v181, vcc
	v_add_co_u32_e32 v184, vcc, s4, v180
	v_lshl_add_u64 v[178:179], s[20:21], 0, v[128:129]
	s_nop 0
	v_addc_co_u32_e32 v185, vcc, 0, v181, vcc
	s_movk_i32 s4, 0x5000
	v_add_co_u32_e32 v182, vcc, s4, v178
	s_nop 0
	s_nop 0
	v_addc_co_u32_e32 v183, vcc, 0, v179, vcc
	v_add_co_u32_e32 v186, vcc, s4, v180
	s_mov_b32 s4, 0x10000
	s_nop 0
	v_addc_co_u32_e32 v187, vcc, 0, v181, vcc
	v_add_co_u32_e32 v188, vcc, s4, v180
	s_mov_b32 s4, 0x1b000
	s_nop 0
	v_addc_co_u32_e32 v189, vcc, 0, v181, vcc
	global_load_dwordx4 v[128:131], v[178:179], off
	global_load_dwordx4 v[132:135], v[180:181], off
	global_load_dwordx4 v[148:151], v[136:137], off
	global_load_dwordx4 v[216:219], v[136:137], off offset:16
	global_load_dwordx4 v[152:155], v[184:185], off
	s_nop 0
	global_load_dwordx4 v[136:139], v[182:183], off offset:2048
	global_load_dwordx4 v[140:143], v[186:187], off offset:2048
	global_load_dwordx4 v[144:147], v[188:189], off offset:2048
	v_add_co_u32_e32 v190, vcc, s4, v180
	s_nop 0
	s_nop 0
	v_addc_co_u32_e32 v191, vcc, 0, v181, vcc
	global_load_dwordx4 v[156:159], v[190:191], off offset:2048
	global_load_dwordx4 v[224:227], v[178:179], off offset:16
	global_load_dwordx4 v[228:231], v[180:181], off offset:16
	global_load_dwordx4 v[232:235], v[184:185], off offset:16
	global_load_dwordx4 v[236:239], v[188:189], off offset:2064
	global_load_dwordx4 v[240:243], v[182:183], off offset:2064
	global_load_dwordx4 v[244:247], v[186:187], off offset:2064
	global_load_dwordx4 v[248:251], v[190:191], off offset:2064
	s_and_b64 vcc, exec, s[60:61]
	s_cbranch_vccz .LBB0_1256
	s_barrier

.LBB0_1290:
	s_cmp_eq_u32 s21, 12
	s_cselect_b32 s40, s24, s4
	s_cselect_b32 s41, s25, s5
	s_cselect_b32 s38, s30, s15
	s_cselect_b32 s39, s31, s17
	s_add_u32 s36, s40, 0x80
	s_addc_u32 s37, s41, 0
	s_add_i32 s23, 0, 0x10000
	v_add_u32_e32 v128, s23, v134
	s_add_i32 s46, 0, 0x14000
	ds_read_b128 v[136:139], v128
	ds_read_b128 v[140:143], v128 offset:1024
	ds_read_b128 v[144:147], v128 offset:2048
	ds_read_b128 v[148:151], v128 offset:3072
	v_add_u32_e32 v128, s46, v134
	ds_read_b128 v[152:155], v128
	ds_read_b128 v[156:159], v128 offset:1024
	ds_read_b128 v[160:163], v128 offset:2048
	ds_read_b128 v[164:167], v128 offset:3072
	s_mov_b64 s[74:75], s[34:35]
	s_add_i32 m0, s27, 0xc000
	ds_read_b128 v[168:171], v135
	ds_read_b128 v[172:175], v135 offset:1024
	ds_read_b128 v[176:179], v135 offset:2048
	ds_read_b128 v[180:183], v135 offset:3072
	ds_read_b128 v[184:187], v135 offset:4096
	ds_read_b128 v[188:191], v135 offset:5120
	ds_read_b128 v[192:195], v135 offset:6144
	ds_read_b128 v[200:203], v135 offset:7168
	s_nop 0
	global_load_lds_dwordx4 v133, s[74:75]
	s_add_i32 m0, s27, 0xe000
	s_nop 0
	global_load_lds_dwordx4 v131, s[74:75]
	s_nop 0
	s_nop 0
	s_nop 0
	s_nop 0
	s_nop 0
	s_nop 0
	s_nop 0
	s_nop 0
	s_nop 0
	s_nop 0
	s_nop 0
	s_nop 0
	s_waitcnt vmcnt(8)
	s_waitcnt lgkmcnt(0)
	s_setprio 1
	s_barrier
	v_mfma_f32_16x16x32_bf16 v[124:127], v[136:139], v[168:171], v[124:127]
	v_mfma_f32_16x16x32_bf16 v[124:127], v[140:143], v[172:175], v[124:127]
	v_mfma_f32_16x16x32_bf16 v[120:123], v[144:147], v[168:171], v[120:123]
	v_mfma_f32_16x16x32_bf16 v[120:123], v[148:151], v[172:175], v[120:123]
	v_mfma_f32_16x16x32_bf16 v[116:119], v[136:139], v[176:179], v[116:119]
	v_mfma_f32_16x16x32_bf16 v[116:119], v[140:143], v[180:183], v[116:119]
	v_mfma_f32_16x16x32_bf16 v[108:111], v[144:147], v[176:179], v[108:111]
	v_mfma_f32_16x16x32_bf16 v[108:111], v[148:151], v[180:183], v[108:111]
	v_mfma_f32_16x16x32_bf16 v[100:103], v[136:139], v[184:187], v[100:103]
	v_mfma_f32_16x16x32_bf16 v[100:103], v[140:143], v[188:191], v[100:103]
	v_mfma_f32_16x16x32_bf16 v[92:95], v[144:147], v[184:187], v[92:95]
	v_mfma_f32_16x16x32_bf16 v[92:95], v[148:151], v[188:191], v[92:95]
	v_mfma_f32_16x16x32_bf16 v[84:87], v[136:139], v[192:195], v[84:87]
	v_mfma_f32_16x16x32_bf16 v[84:87], v[140:143], v[200:203], v[84:87]
	v_mfma_f32_16x16x32_bf16 v[76:79], v[144:147], v[192:195], v[76:79]
	v_mfma_f32_16x16x32_bf16 v[76:79], v[148:151], v[200:203], v[76:79]
	v_mfma_f32_16x16x32_bf16 v[112:115], v[152:155], v[168:171], v[112:115]
	v_mfma_f32_16x16x32_bf16 v[112:115], v[156:159], v[172:175], v[112:115]
	v_mfma_f32_16x16x32_bf16 v[104:107], v[160:163], v[168:171], v[104:107]
	v_mfma_f32_16x16x32_bf16 v[104:107], v[164:167], v[172:175], v[104:107]
	v_mfma_f32_16x16x32_bf16 v[96:99], v[152:155], v[176:179], v[96:99]
	v_mfma_f32_16x16x32_bf16 v[96:99], v[156:159], v[180:183], v[96:99]
	v_mfma_f32_16x16x32_bf16 v[88:91], v[160:163], v[176:179], v[88:91]
	v_mfma_f32_16x16x32_bf16 v[88:91], v[164:167], v[180:183], v[88:91]
	v_mfma_f32_16x16x32_bf16 v[80:83], v[152:155], v[184:187], v[80:83]
	v_mfma_f32_16x16x32_bf16 v[80:83], v[156:159], v[188:191], v[80:83]
	v_mfma_f32_16x16x32_bf16 v[72:75], v[160:163], v[184:187], v[72:75]
	v_mfma_f32_16x16x32_bf16 v[72:75], v[164:167], v[188:191], v[72:75]
	v_mfma_f32_16x16x32_bf16 v[68:71], v[152:155], v[192:195], v[68:71]
	v_mfma_f32_16x16x32_bf16 v[68:71], v[156:159], v[200:203], v[68:71]
	v_mfma_f32_16x16x32_bf16 v[64:67], v[160:163], v[192:195], v[64:67]
	v_mfma_f32_16x16x32_bf16 v[64:67], v[164:167], v[200:203], v[64:67]
	s_barrier
	s_setprio 0
	s_add_i32 s23, s23, s97
	s_mov_b64 s[74:75], s[38:39]
	s_mov_b32 m0, s23
	ds_read_b128 v[168:171], v135 offset:16384
	ds_read_b128 v[172:175], v135 offset:17408
	ds_read_b128 v[176:179], v135 offset:18432
	ds_read_b128 v[180:183], v135 offset:19456
	ds_read_b128 v[184:187], v135 offset:20480
	ds_read_b128 v[188:191], v135 offset:21504
	ds_read_b128 v[192:195], v135 offset:22528
	ds_read_b128 v[200:203], v135 offset:23552
	s_nop 0
	global_load_lds_dwordx4 v132, s[74:75]
	s_add_i32 m0, s23, 0x2000
	s_nop 0
	global_load_lds_dwordx4 v130, s[74:75]
	s_add_u32 s74, s38, 0x80000
	s_addc_u32 s75, s39, 0
	s_add_i32 s23, s46, s97
	s_mov_b32 m0, s23
	s_nop 0
	global_load_lds_dwordx4 v132, s[74:75]
	s_add_i32 m0, s23, 0x2000
	s_nop 0
	global_load_lds_dwordx4 v130, s[74:75]
	s_mov_b64 s[74:75], s[40:41]
	s_mov_b32 m0, s27
	s_nop 0
	global_load_lds_dwordx4 v133, s[74:75]
	s_mov_b32 m0, s29
	s_nop 0
	global_load_lds_dwordx4 v131, s[74:75]
	s_nop 0
	s_nop 0
	s_nop 0
	s_nop 0
	s_nop 0
	s_nop 0
	s_nop 0
	s_nop 0
	s_nop 0
	s_waitcnt vmcnt(8)
	s_waitcnt lgkmcnt(0)
	s_setprio 1
	s_barrier
	v_mfma_f32_16x16x32_bf16 v[60:63], v[136:139], v[168:171], v[60:63]
	v_mfma_f32_16x16x32_bf16 v[60:63], v[140:143], v[172:175], v[60:63]
	v_mfma_f32_16x16x32_bf16 v[56:59], v[144:147], v[168:171], v[56:59]
	v_mfma_f32_16x16x32_bf16 v[56:59], v[148:151], v[172:175], v[56:59]
	v_mfma_f32_16x16x32_bf16 v[52:55], v[136:139], v[176:179], v[52:55]
	v_mfma_f32_16x16x32_bf16 v[52:55], v[140:143], v[180:183], v[52:55]
	v_mfma_f32_16x16x32_bf16 v[44:47], v[144:147], v[176:179], v[44:47]
	v_mfma_f32_16x16x32_bf16 v[44:47], v[148:151], v[180:183], v[44:47]
	v_mfma_f32_16x16x32_bf16 v[36:39], v[136:139], v[184:187], v[36:39]
	v_mfma_f32_16x16x32_bf16 v[36:39], v[140:143], v[188:191], v[36:39]
	v_mfma_f32_16x16x32_bf16 v[28:31], v[144:147], v[184:187], v[28:31]
	v_mfma_f32_16x16x32_bf16 v[28:31], v[148:151], v[188:191], v[28:31]
	v_mfma_f32_16x16x32_bf16 v[20:23], v[136:139], v[192:195], v[20:23]
	v_mfma_f32_16x16x32_bf16 v[20:23], v[140:143], v[200:203], v[20:23]
	v_mfma_f32_16x16x32_bf16 v[12:15], v[144:147], v[192:195], v[12:15]
	v_mfma_f32_16x16x32_bf16 v[12:15], v[148:151], v[200:203], v[12:15]
	v_mfma_f32_16x16x32_bf16 v[48:51], v[152:155], v[168:171], v[48:51]
	v_mfma_f32_16x16x32_bf16 v[48:51], v[156:159], v[172:175], v[48:51]
	v_mfma_f32_16x16x32_bf16 v[40:43], v[160:163], v[168:171], v[40:43]
	v_mfma_f32_16x16x32_bf16 v[40:43], v[164:167], v[172:175], v[40:43]
	v_mfma_f32_16x16x32_bf16 v[32:35], v[152:155], v[176:179], v[32:35]
	v_mfma_f32_16x16x32_bf16 v[32:35], v[156:159], v[180:183], v[32:35]
	v_mfma_f32_16x16x32_bf16 v[24:27], v[160:163], v[176:179], v[24:27]
	v_mfma_f32_16x16x32_bf16 v[24:27], v[164:167], v[180:183], v[24:27]
	v_mfma_f32_16x16x32_bf16 v[16:19], v[152:155], v[184:187], v[16:19]
	v_mfma_f32_16x16x32_bf16 v[16:19], v[156:159], v[188:191], v[16:19]
	v_mfma_f32_16x16x32_bf16 v[8:11], v[160:163], v[184:187], v[8:11]
	v_mfma_f32_16x16x32_bf16 v[8:11], v[164:167], v[188:191], v[8:11]
	v_mfma_f32_16x16x32_bf16 v[4:7], v[152:155], v[192:195], v[4:7]
	v_mfma_f32_16x16x32_bf16 v[4:7], v[156:159], v[200:203], v[4:7]
	v_mfma_f32_16x16x32_bf16 v[0:3], v[160:163], v[192:195], v[0:3]
	v_mfma_f32_16x16x32_bf16 v[0:3], v[164:167], v[200:203], v[0:3]
	s_barrier
	s_setprio 0
	s_add_i32 s23, 0, 0x18000
	v_add_u32_e32 v128, s23, v134
	s_add_i32 s46, 0, 0x1c000
	ds_read_b128 v[136:139], v128
	ds_read_b128 v[140:143], v128 offset:1024
	ds_read_b128 v[144:147], v128 offset:2048
	ds_read_b128 v[148:151], v128 offset:3072
	v_add_u32_e32 v128, s46, v134
	ds_read_b128 v[152:155], v128
	ds_read_b128 v[156:159], v128 offset:1024
	ds_read_b128 v[160:163], v128 offset:2048
	ds_read_b128 v[164:167], v128 offset:3072
	s_add_u32 s40, s40, 0x80000
	s_addc_u32 s41, s41, 0
	s_mov_b32 m0, s56
	ds_read_b128 v[168:171], v135 offset:32768
	ds_read_b128 v[172:175], v135 offset:33792
	ds_read_b128 v[176:179], v135 offset:34816
	ds_read_b128 v[180:183], v135 offset:35840
	ds_read_b128 v[184:187], v135 offset:36864
	ds_read_b128 v[188:191], v135 offset:37888
	ds_read_b128 v[192:195], v135 offset:38912
	ds_read_b128 v[200:203], v135 offset:39936
	s_nop 0
	global_load_lds_dwordx4 v133, s[40:41]
	s_mov_b32 m0, s57
	s_nop 0
	global_load_lds_dwordx4 v131, s[40:41]
	s_nop 0
	s_nop 0
	s_nop 0
	s_nop 0
	s_nop 0
	s_nop 0
	s_nop 0
	s_nop 0
	s_nop 0
	s_waitcnt vmcnt(8)
	s_waitcnt lgkmcnt(0)
	s_setprio 1
	s_barrier
	v_mfma_f32_16x16x32_bf16 v[124:127], v[136:139], v[168:171], v[124:127]
	v_mfma_f32_16x16x32_bf16 v[124:127], v[140:143], v[172:175], v[124:127]
	v_mfma_f32_16x16x32_bf16 v[120:123], v[144:147], v[168:171], v[120:123]
	v_mfma_f32_16x16x32_bf16 v[120:123], v[148:151], v[172:175], v[120:123]
	v_mfma_f32_16x16x32_bf16 v[116:119], v[136:139], v[176:179], v[116:119]
	v_mfma_f32_16x16x32_bf16 v[116:119], v[140:143], v[180:183], v[116:119]
	v_mfma_f32_16x16x32_bf16 v[108:111], v[144:147], v[176:179], v[108:111]
	v_mfma_f32_16x16x32_bf16 v[108:111], v[148:151], v[180:183], v[108:111]
	v_mfma_f32_16x16x32_bf16 v[100:103], v[136:139], v[184:187], v[100:103]
	v_mfma_f32_16x16x32_bf16 v[100:103], v[140:143], v[188:191], v[100:103]
	v_mfma_f32_16x16x32_bf16 v[92:95], v[144:147], v[184:187], v[92:95]
	v_mfma_f32_16x16x32_bf16 v[92:95], v[148:151], v[188:191], v[92:95]
	v_mfma_f32_16x16x32_bf16 v[84:87], v[136:139], v[192:195], v[84:87]
	v_mfma_f32_16x16x32_bf16 v[84:87], v[140:143], v[200:203], v[84:87]
	v_mfma_f32_16x16x32_bf16 v[76:79], v[144:147], v[192:195], v[76:79]
	v_mfma_f32_16x16x32_bf16 v[76:79], v[148:151], v[200:203], v[76:79]
	v_mfma_f32_16x16x32_bf16 v[112:115], v[152:155], v[168:171], v[112:115]
	v_mfma_f32_16x16x32_bf16 v[112:115], v[156:159], v[172:175], v[112:115]
	v_mfma_f32_16x16x32_bf16 v[104:107], v[160:163], v[168:171], v[104:107]
	v_mfma_f32_16x16x32_bf16 v[104:107], v[164:167], v[172:175], v[104:107]
	v_mfma_f32_16x16x32_bf16 v[96:99], v[152:155], v[176:179], v[96:99]
	v_mfma_f32_16x16x32_bf16 v[96:99], v[156:159], v[180:183], v[96:99]
	v_mfma_f32_16x16x32_bf16 v[88:91], v[160:163], v[176:179], v[88:91]
	v_mfma_f32_16x16x32_bf16 v[88:91], v[164:167], v[180:183], v[88:91]
	v_mfma_f32_16x16x32_bf16 v[80:83], v[152:155], v[184:187], v[80:83]
	v_mfma_f32_16x16x32_bf16 v[80:83], v[156:159], v[188:191], v[80:83]
	v_mfma_f32_16x16x32_bf16 v[72:75], v[160:163], v[184:187], v[72:75]
	v_mfma_f32_16x16x32_bf16 v[72:75], v[164:167], v[188:191], v[72:75]
	v_mfma_f32_16x16x32_bf16 v[68:71], v[152:155], v[192:195], v[68:71]
	v_mfma_f32_16x16x32_bf16 v[68:71], v[156:159], v[200:203], v[68:71]
	v_mfma_f32_16x16x32_bf16 v[64:67], v[160:163], v[192:195], v[64:67]
	v_mfma_f32_16x16x32_bf16 v[64:67], v[164:167], v[200:203], v[64:67]
	s_barrier
	s_setprio 0
	s_add_u32 s40, s38, 0x80
	s_addc_u32 s41, s39, 0
	s_add_i32 s23, s23, s97
	s_mov_b32 m0, s23
	ds_read_b128 v[168:171], v135 offset:49152
	ds_read_b128 v[172:175], v135 offset:50176
	ds_read_b128 v[176:179], v135 offset:51200
	ds_read_b128 v[180:183], v135 offset:52224
	ds_read_b128 v[184:187], v135 offset:53248
	ds_read_b128 v[188:191], v135 offset:54272
	ds_read_b128 v[192:195], v135 offset:55296
	ds_read_b128 v[200:203], v135 offset:56320
	s_nop 0
	global_load_lds_dwordx4 v132, s[40:41]
	s_add_i32 m0, s23, 0x2000
	s_add_u32 s38, s38, 0x80080
	s_addc_u32 s39, s39, 0
	s_add_i32 s23, s46, s97
	s_nop 0
	global_load_lds_dwordx4 v130, s[40:41]
	s_mov_b32 m0, s23
	s_nop 0
	global_load_lds_dwordx4 v132, s[38:39]
	s_add_i32 m0, s23, 0x2000
	s_nop 0
	global_load_lds_dwordx4 v130, s[38:39]
	s_mov_b32 m0, s70
	s_nop 0
	global_load_lds_dwordx4 v133, s[36:37]
	s_mov_b32 m0, s71
	s_nop 0
	global_load_lds_dwordx4 v131, s[36:37]
	s_nop 0
	s_nop 0
	s_nop 0
	s_nop 0
	s_nop 0
	s_nop 0
	s_nop 0
	s_nop 0
	s_waitcnt vmcnt(8)
	s_waitcnt lgkmcnt(0)
	s_setprio 1
	s_barrier
	v_mfma_f32_16x16x32_bf16 v[60:63], v[136:139], v[168:171], v[60:63]
	v_mfma_f32_16x16x32_bf16 v[60:63], v[140:143], v[172:175], v[60:63]
	v_mfma_f32_16x16x32_bf16 v[56:59], v[144:147], v[168:171], v[56:59]
	v_mfma_f32_16x16x32_bf16 v[56:59], v[148:151], v[172:175], v[56:59]
	v_mfma_f32_16x16x32_bf16 v[52:55], v[136:139], v[176:179], v[52:55]
	v_mfma_f32_16x16x32_bf16 v[52:55], v[140:143], v[180:183], v[52:55]
	v_mfma_f32_16x16x32_bf16 v[44:47], v[144:147], v[176:179], v[44:47]
	v_mfma_f32_16x16x32_bf16 v[44:47], v[148:151], v[180:183], v[44:47]
	v_mfma_f32_16x16x32_bf16 v[36:39], v[136:139], v[184:187], v[36:39]
	v_mfma_f32_16x16x32_bf16 v[36:39], v[140:143], v[188:191], v[36:39]
	v_mfma_f32_16x16x32_bf16 v[28:31], v[144:147], v[184:187], v[28:31]
	v_mfma_f32_16x16x32_bf16 v[28:31], v[148:151], v[188:191], v[28:31]
	v_mfma_f32_16x16x32_bf16 v[20:23], v[136:139], v[192:195], v[20:23]
	v_mfma_f32_16x16x32_bf16 v[20:23], v[140:143], v[200:203], v[20:23]
	v_mfma_f32_16x16x32_bf16 v[12:15], v[144:147], v[192:195], v[12:15]
	v_mfma_f32_16x16x32_bf16 v[12:15], v[148:151], v[200:203], v[12:15]
	v_mfma_f32_16x16x32_bf16 v[48:51], v[152:155], v[168:171], v[48:51]
	v_mfma_f32_16x16x32_bf16 v[48:51], v[156:159], v[172:175], v[48:51]
	v_mfma_f32_16x16x32_bf16 v[40:43], v[160:163], v[168:171], v[40:43]
	v_mfma_f32_16x16x32_bf16 v[40:43], v[164:167], v[172:175], v[40:43]
	v_mfma_f32_16x16x32_bf16 v[32:35], v[152:155], v[176:179], v[32:35]
	v_mfma_f32_16x16x32_bf16 v[32:35], v[156:159], v[180:183], v[32:35]
	v_mfma_f32_16x16x32_bf16 v[24:27], v[160:163], v[176:179], v[24:27]
	v_mfma_f32_16x16x32_bf16 v[24:27], v[164:167], v[180:183], v[24:27]
	v_mfma_f32_16x16x32_bf16 v[16:19], v[152:155], v[184:187], v[16:19]
	v_mfma_f32_16x16x32_bf16 v[16:19], v[156:159], v[188:191], v[16:19]
	v_mfma_f32_16x16x32_bf16 v[8:11], v[160:163], v[184:187], v[8:11]
	v_mfma_f32_16x16x32_bf16 v[8:11], v[164:167], v[188:191], v[8:11]
	v_mfma_f32_16x16x32_bf16 v[4:7], v[152:155], v[192:195], v[4:7]
	v_mfma_f32_16x16x32_bf16 v[4:7], v[156:159], v[200:203], v[4:7]
	v_mfma_f32_16x16x32_bf16 v[0:3], v[160:163], v[192:195], v[0:3]
	v_mfma_f32_16x16x32_bf16 v[0:3], v[164:167], v[200:203], v[0:3]
	s_barrier
	s_setprio 0
	s_add_i32 s21, s21, 2
	s_add_u32 s4, s4, 0x100
	s_addc_u32 s5, s5, 0
	s_add_u32 s15, s15, 0x100
	s_addc_u32 s17, s17, 0
	s_add_u32 s34, s34, 0x100
	s_addc_u32 s35, s35, 0
	s_cmp_gt_u32 s21, 13
	s_cbranch_scc0 .LBB0_1290
	s_and_b64 vcc, exec, s[60:61]
	s_cbranch_vccz .LBB0_1293
	s_barrier

.LBB0_1425:
	s_cmpk_eq_i32 s80, 0x54
	s_cselect_b32 s56, s48, s4
	s_cselect_b32 s57, s49, s5
	s_cselect_b32 s74, s70, s15
	s_cselect_b32 s75, s71, s72
	s_add_u32 s16, s56, 0x80
	s_addc_u32 s17, s57, 0
	s_add_i32 s81, 0, 0x10000
	s_add_i32 vcc_lo, 0, 0x14000
	v_add_u32_e32 v136, s81, v172
	v_add_u32_e32 v156, vcc_lo, v172
	ds_read_b128 v[120:123], v136
	ds_read_b128 v[124:127], v136 offset:1024
	ds_read_b128 v[132:135], v136 offset:2048
	ds_read_b128 v[136:139], v136 offset:3072
	ds_read_b128 v[144:147], v156
	ds_read_b128 v[148:151], v156 offset:1024
	ds_read_b128 v[152:155], v156 offset:2048
	ds_read_b128 v[156:159], v156 offset:3072
	s_mov_b64 s[12:13], s[28:29]
	s_add_i32 m0, s2, 0xc000
	ds_read_b128 v[160:163], v173
	ds_read_b128 v[164:167], v173 offset:1024
	ds_read_b128 v[174:177], v173 offset:2048
	ds_read_b128 v[178:181], v173 offset:3072
	ds_read_b128 v[182:185], v173 offset:4096
	ds_read_b128 v[186:189], v173 offset:5120
	ds_read_b128 v[190:193], v173 offset:6144
	ds_read_b128 v[200:203], v173 offset:7168
	s_nop 0
	global_load_lds_dwordx4 v168, s[12:13]
	s_add_i32 m0, s2, 0xe000
	s_nop 0
	global_load_lds_dwordx4 v170, s[12:13]
	s_nop 0
	s_waitcnt vmcnt(8)
	s_waitcnt lgkmcnt(0)
	s_setprio 1
	s_barrier
	v_mfma_f32_16x16x32_bf16 v[140:143], v[120:123], v[160:163], v[140:143]
	v_mfma_f32_16x16x32_bf16 v[140:143], v[124:127], v[164:167], v[140:143]
	v_mfma_f32_16x16x32_bf16 v[128:131], v[132:135], v[160:163], v[128:131]
	v_mfma_f32_16x16x32_bf16 v[128:131], v[136:139], v[164:167], v[128:131]
	v_mfma_f32_16x16x32_bf16 v[116:119], v[120:123], v[174:177], v[116:119]
	v_mfma_f32_16x16x32_bf16 v[116:119], v[124:127], v[178:181], v[116:119]
	v_mfma_f32_16x16x32_bf16 v[104:107], v[132:135], v[174:177], v[104:107]
	v_mfma_f32_16x16x32_bf16 v[104:107], v[136:139], v[178:181], v[104:107]
	v_mfma_f32_16x16x32_bf16 v[96:99], v[120:123], v[182:185], v[96:99]
	v_mfma_f32_16x16x32_bf16 v[96:99], v[124:127], v[186:189], v[96:99]
	v_mfma_f32_16x16x32_bf16 v[88:91], v[132:135], v[182:185], v[88:91]
	v_mfma_f32_16x16x32_bf16 v[88:91], v[136:139], v[186:189], v[88:91]
	v_mfma_f32_16x16x32_bf16 v[84:87], v[120:123], v[190:193], v[84:87]
	v_mfma_f32_16x16x32_bf16 v[84:87], v[124:127], v[200:203], v[84:87]
	v_mfma_f32_16x16x32_bf16 v[72:75], v[132:135], v[190:193], v[72:75]
	v_mfma_f32_16x16x32_bf16 v[72:75], v[136:139], v[200:203], v[72:75]
	v_mfma_f32_16x16x32_bf16 v[112:115], v[144:147], v[160:163], v[112:115]
	v_mfma_f32_16x16x32_bf16 v[112:115], v[148:151], v[164:167], v[112:115]
	v_mfma_f32_16x16x32_bf16 v[108:111], v[152:155], v[160:163], v[108:111]
	v_mfma_f32_16x16x32_bf16 v[108:111], v[156:159], v[164:167], v[108:111]
	v_mfma_f32_16x16x32_bf16 v[100:103], v[144:147], v[174:177], v[100:103]
	v_mfma_f32_16x16x32_bf16 v[100:103], v[148:151], v[178:181], v[100:103]
	v_mfma_f32_16x16x32_bf16 v[92:95], v[152:155], v[174:177], v[92:95]
	v_mfma_f32_16x16x32_bf16 v[92:95], v[156:159], v[178:181], v[92:95]
	v_mfma_f32_16x16x32_bf16 v[80:83], v[144:147], v[182:185], v[80:83]
	v_mfma_f32_16x16x32_bf16 v[80:83], v[148:151], v[186:189], v[80:83]
	v_mfma_f32_16x16x32_bf16 v[76:79], v[152:155], v[182:185], v[76:79]
	v_mfma_f32_16x16x32_bf16 v[76:79], v[156:159], v[186:189], v[76:79]
	v_mfma_f32_16x16x32_bf16 v[68:71], v[144:147], v[190:193], v[68:71]
	v_mfma_f32_16x16x32_bf16 v[68:71], v[148:151], v[200:203], v[68:71]
	v_mfma_f32_16x16x32_bf16 v[64:67], v[152:155], v[190:193], v[64:67]
	v_mfma_f32_16x16x32_bf16 v[64:67], v[156:159], v[200:203], v[64:67]
	s_barrier
	s_setprio 0
	s_add_i32 s81, s81, s97
	s_mov_b64 s[12:13], s[74:75]
	s_mov_b32 m0, s81
	ds_read_b128 v[160:163], v173 offset:16384
	ds_read_b128 v[164:167], v173 offset:17408
	ds_read_b128 v[174:177], v173 offset:18432
	ds_read_b128 v[178:181], v173 offset:19456
	ds_read_b128 v[182:185], v173 offset:20480
	ds_read_b128 v[186:189], v173 offset:21504
	ds_read_b128 v[190:193], v173 offset:22528
	ds_read_b128 v[200:203], v173 offset:23552
	s_nop 0
	global_load_lds_dwordx4 v169, s[12:13]
	s_add_i32 m0, s81, 0x2000
	s_nop 0
	global_load_lds_dwordx4 v171, s[12:13]
	s_add_u32 s12, s74, 0x160000
	s_addc_u32 s13, s75, 0
	s_add_i32 s81, vcc_lo, s97
	s_mov_b32 m0, s81
	s_nop 0
	global_load_lds_dwordx4 v169, s[12:13]
	s_add_i32 m0, s81, 0x2000
	s_nop 0
	global_load_lds_dwordx4 v171, s[12:13]
	s_mov_b64 s[12:13], s[56:57]
	s_mov_b32 m0, s2
	s_nop 0
	global_load_lds_dwordx4 v168, s[12:13]
	s_mov_b32 m0, s65
	s_nop 0
	global_load_lds_dwordx4 v170, s[12:13]
	s_nop 0
	s_nop 0
	s_nop 0
	s_nop 0
	s_nop 0
	s_nop 0
	s_nop 0
	s_nop 0
	s_nop 0
	s_waitcnt vmcnt(8)
	s_waitcnt lgkmcnt(0)
	s_setprio 1
	s_barrier
	v_mfma_f32_16x16x32_bf16 v[60:63], v[120:123], v[160:163], v[60:63]
	v_mfma_f32_16x16x32_bf16 v[60:63], v[124:127], v[164:167], v[60:63]
	v_mfma_f32_16x16x32_bf16 v[56:59], v[132:135], v[160:163], v[56:59]
	v_mfma_f32_16x16x32_bf16 v[56:59], v[136:139], v[164:167], v[56:59]
	v_mfma_f32_16x16x32_bf16 v[48:51], v[120:123], v[174:177], v[48:51]
	v_mfma_f32_16x16x32_bf16 v[48:51], v[124:127], v[178:181], v[48:51]
	v_mfma_f32_16x16x32_bf16 v[40:43], v[132:135], v[174:177], v[40:43]
	v_mfma_f32_16x16x32_bf16 v[40:43], v[136:139], v[178:181], v[40:43]
	v_mfma_f32_16x16x32_bf16 v[32:35], v[120:123], v[182:185], v[32:35]
	v_mfma_f32_16x16x32_bf16 v[32:35], v[124:127], v[186:189], v[32:35]
	v_mfma_f32_16x16x32_bf16 v[24:27], v[132:135], v[182:185], v[24:27]
	v_mfma_f32_16x16x32_bf16 v[24:27], v[136:139], v[186:189], v[24:27]
	v_mfma_f32_16x16x32_bf16 v[16:19], v[120:123], v[190:193], v[16:19]
	v_mfma_f32_16x16x32_bf16 v[16:19], v[124:127], v[200:203], v[16:19]
	v_mfma_f32_16x16x32_bf16 v[8:11], v[132:135], v[190:193], v[8:11]
	v_mfma_f32_16x16x32_bf16 v[8:11], v[136:139], v[200:203], v[8:11]
	v_mfma_f32_16x16x32_bf16 v[52:55], v[144:147], v[160:163], v[52:55]
	v_mfma_f32_16x16x32_bf16 v[52:55], v[148:151], v[164:167], v[52:55]
	v_mfma_f32_16x16x32_bf16 v[44:47], v[152:155], v[160:163], v[44:47]
	v_mfma_f32_16x16x32_bf16 v[44:47], v[156:159], v[164:167], v[44:47]
	v_mfma_f32_16x16x32_bf16 v[36:39], v[144:147], v[174:177], v[36:39]
	v_mfma_f32_16x16x32_bf16 v[36:39], v[148:151], v[178:181], v[36:39]
	v_mfma_f32_16x16x32_bf16 v[28:31], v[152:155], v[174:177], v[28:31]
	v_mfma_f32_16x16x32_bf16 v[28:31], v[156:159], v[178:181], v[28:31]
	v_mfma_f32_16x16x32_bf16 v[20:23], v[144:147], v[182:185], v[20:23]
	v_mfma_f32_16x16x32_bf16 v[20:23], v[148:151], v[186:189], v[20:23]
	v_mfma_f32_16x16x32_bf16 v[12:15], v[152:155], v[182:185], v[12:15]
	v_mfma_f32_16x16x32_bf16 v[12:15], v[156:159], v[186:189], v[12:15]
	v_mfma_f32_16x16x32_bf16 v[4:7], v[144:147], v[190:193], v[4:7]
	v_mfma_f32_16x16x32_bf16 v[4:7], v[148:151], v[200:203], v[4:7]
	v_mfma_f32_16x16x32_bf16 v[0:3], v[152:155], v[190:193], v[0:3]
	v_mfma_f32_16x16x32_bf16 v[0:3], v[156:159], v[200:203], v[0:3]
	s_barrier
	s_setprio 0
	s_add_i32 s81, 0, 0x18000
	s_add_i32 vcc_lo, 0, 0x1c000
	v_add_u32_e32 v136, s81, v172
	v_add_u32_e32 v156, vcc_lo, v172
	ds_read_b128 v[120:123], v136
	ds_read_b128 v[124:127], v136 offset:1024
	ds_read_b128 v[132:135], v136 offset:2048
	ds_read_b128 v[136:139], v136 offset:3072
	ds_read_b128 v[144:147], v156
	ds_read_b128 v[148:151], v156 offset:1024
	ds_read_b128 v[152:155], v156 offset:2048
	ds_read_b128 v[156:159], v156 offset:3072
	s_add_u32 s12, s56, 0x160000
	s_addc_u32 s13, s57, 0
	s_mov_b32 m0, s93
	ds_read_b128 v[160:163], v173 offset:32768
	ds_read_b128 v[164:167], v173 offset:33792
	ds_read_b128 v[174:177], v173 offset:34816
	ds_read_b128 v[178:181], v173 offset:35840
	ds_read_b128 v[182:185], v173 offset:36864
	ds_read_b128 v[186:189], v173 offset:37888
	ds_read_b128 v[190:193], v173 offset:38912
	ds_read_b128 v[200:203], v173 offset:39936
	s_nop 0
	global_load_lds_dwordx4 v168, s[12:13]
	s_mov_b32 m0, s92
	s_nop 0
	global_load_lds_dwordx4 v170, s[12:13]
	s_nop 0
	s_nop 0
	s_nop 0
	s_nop 0
	s_nop 0
	s_nop 0
	s_nop 0
	s_nop 0
	s_nop 0
	s_waitcnt vmcnt(8)
	s_waitcnt lgkmcnt(0)
	s_setprio 1
	s_barrier
	v_mfma_f32_16x16x32_bf16 v[140:143], v[120:123], v[160:163], v[140:143]
	v_mfma_f32_16x16x32_bf16 v[140:143], v[124:127], v[164:167], v[140:143]
	v_mfma_f32_16x16x32_bf16 v[128:131], v[132:135], v[160:163], v[128:131]
	v_mfma_f32_16x16x32_bf16 v[128:131], v[136:139], v[164:167], v[128:131]
	v_mfma_f32_16x16x32_bf16 v[116:119], v[120:123], v[174:177], v[116:119]
	v_mfma_f32_16x16x32_bf16 v[116:119], v[124:127], v[178:181], v[116:119]
	v_mfma_f32_16x16x32_bf16 v[104:107], v[132:135], v[174:177], v[104:107]
	v_mfma_f32_16x16x32_bf16 v[104:107], v[136:139], v[178:181], v[104:107]
	v_mfma_f32_16x16x32_bf16 v[96:99], v[120:123], v[182:185], v[96:99]
	v_mfma_f32_16x16x32_bf16 v[96:99], v[124:127], v[186:189], v[96:99]
	v_mfma_f32_16x16x32_bf16 v[88:91], v[132:135], v[182:185], v[88:91]
	v_mfma_f32_16x16x32_bf16 v[88:91], v[136:139], v[186:189], v[88:91]
	v_mfma_f32_16x16x32_bf16 v[84:87], v[120:123], v[190:193], v[84:87]
	v_mfma_f32_16x16x32_bf16 v[84:87], v[124:127], v[200:203], v[84:87]
	v_mfma_f32_16x16x32_bf16 v[72:75], v[132:135], v[190:193], v[72:75]
	v_mfma_f32_16x16x32_bf16 v[72:75], v[136:139], v[200:203], v[72:75]
	v_mfma_f32_16x16x32_bf16 v[112:115], v[144:147], v[160:163], v[112:115]
	v_mfma_f32_16x16x32_bf16 v[112:115], v[148:151], v[164:167], v[112:115]
	v_mfma_f32_16x16x32_bf16 v[108:111], v[152:155], v[160:163], v[108:111]
	v_mfma_f32_16x16x32_bf16 v[108:111], v[156:159], v[164:167], v[108:111]
	v_mfma_f32_16x16x32_bf16 v[100:103], v[144:147], v[174:177], v[100:103]
	v_mfma_f32_16x16x32_bf16 v[100:103], v[148:151], v[178:181], v[100:103]
	v_mfma_f32_16x16x32_bf16 v[92:95], v[152:155], v[174:177], v[92:95]
	v_mfma_f32_16x16x32_bf16 v[92:95], v[156:159], v[178:181], v[92:95]
	v_mfma_f32_16x16x32_bf16 v[80:83], v[144:147], v[182:185], v[80:83]
	v_mfma_f32_16x16x32_bf16 v[80:83], v[148:151], v[186:189], v[80:83]
	v_mfma_f32_16x16x32_bf16 v[76:79], v[152:155], v[182:185], v[76:79]
	v_mfma_f32_16x16x32_bf16 v[76:79], v[156:159], v[186:189], v[76:79]
	v_mfma_f32_16x16x32_bf16 v[68:71], v[144:147], v[190:193], v[68:71]
	v_mfma_f32_16x16x32_bf16 v[68:71], v[148:151], v[200:203], v[68:71]
	v_mfma_f32_16x16x32_bf16 v[64:67], v[152:155], v[190:193], v[64:67]
	v_mfma_f32_16x16x32_bf16 v[64:67], v[156:159], v[200:203], v[64:67]
	s_barrier
	s_setprio 0
	s_add_u32 s12, s74, 0x80
	s_addc_u32 s13, s75, 0
	s_add_i32 s56, s81, s97
	s_mov_b32 m0, s56
	ds_read_b128 v[160:163], v173 offset:49152
	ds_read_b128 v[164:167], v173 offset:50176
	ds_read_b128 v[174:177], v173 offset:51200
	ds_read_b128 v[178:181], v173 offset:52224
	ds_read_b128 v[182:185], v173 offset:53248
	ds_read_b128 v[186:189], v173 offset:54272
	ds_read_b128 v[190:193], v173 offset:55296
	ds_read_b128 v[200:203], v173 offset:56320
	s_nop 0
	global_load_lds_dwordx4 v169, s[12:13]
	s_add_i32 m0, s56, 0x2000
	s_nop 0
	global_load_lds_dwordx4 v171, s[12:13]
	s_add_u32 s12, s74, 0x160080
	s_addc_u32 s13, s75, 0
	s_add_i32 s56, vcc_lo, s97
	s_mov_b32 m0, s56
	s_nop 0
	global_load_lds_dwordx4 v169, s[12:13]
	s_add_i32 m0, s56, 0x2000
	s_nop 0
	global_load_lds_dwordx4 v171, s[12:13]
	s_mov_b32 m0, s19
	s_nop 0
	global_load_lds_dwordx4 v168, s[16:17]
	s_mov_b32 m0, s89
	s_nop 0
	global_load_lds_dwordx4 v170, s[16:17]
	s_nop 0
	s_nop 0
	s_nop 0
	s_nop 0
	s_nop 0
	s_nop 0
	s_nop 0
	s_nop 0
	s_waitcnt vmcnt(8)
	s_waitcnt lgkmcnt(0)
	s_setprio 1
	s_barrier
	v_mfma_f32_16x16x32_bf16 v[60:63], v[120:123], v[160:163], v[60:63]
	v_mfma_f32_16x16x32_bf16 v[60:63], v[124:127], v[164:167], v[60:63]
	v_mfma_f32_16x16x32_bf16 v[56:59], v[132:135], v[160:163], v[56:59]
	v_mfma_f32_16x16x32_bf16 v[56:59], v[136:139], v[164:167], v[56:59]
	v_mfma_f32_16x16x32_bf16 v[48:51], v[120:123], v[174:177], v[48:51]
	v_mfma_f32_16x16x32_bf16 v[48:51], v[124:127], v[178:181], v[48:51]
	v_mfma_f32_16x16x32_bf16 v[40:43], v[132:135], v[174:177], v[40:43]
	v_mfma_f32_16x16x32_bf16 v[40:43], v[136:139], v[178:181], v[40:43]
	v_mfma_f32_16x16x32_bf16 v[32:35], v[120:123], v[182:185], v[32:35]
	v_mfma_f32_16x16x32_bf16 v[32:35], v[124:127], v[186:189], v[32:35]
	v_mfma_f32_16x16x32_bf16 v[24:27], v[132:135], v[182:185], v[24:27]
	v_mfma_f32_16x16x32_bf16 v[24:27], v[136:139], v[186:189], v[24:27]
	v_mfma_f32_16x16x32_bf16 v[16:19], v[120:123], v[190:193], v[16:19]
	v_mfma_f32_16x16x32_bf16 v[16:19], v[124:127], v[200:203], v[16:19]
	v_mfma_f32_16x16x32_bf16 v[8:11], v[132:135], v[190:193], v[8:11]
	v_mfma_f32_16x16x32_bf16 v[8:11], v[136:139], v[200:203], v[8:11]
	v_mfma_f32_16x16x32_bf16 v[52:55], v[144:147], v[160:163], v[52:55]
	v_mfma_f32_16x16x32_bf16 v[52:55], v[148:151], v[164:167], v[52:55]
	v_mfma_f32_16x16x32_bf16 v[44:47], v[152:155], v[160:163], v[44:47]
	v_mfma_f32_16x16x32_bf16 v[44:47], v[156:159], v[164:167], v[44:47]
	v_mfma_f32_16x16x32_bf16 v[36:39], v[144:147], v[174:177], v[36:39]
	v_mfma_f32_16x16x32_bf16 v[36:39], v[148:151], v[178:181], v[36:39]
	v_mfma_f32_16x16x32_bf16 v[28:31], v[152:155], v[174:177], v[28:31]
	v_mfma_f32_16x16x32_bf16 v[28:31], v[156:159], v[178:181], v[28:31]
	v_mfma_f32_16x16x32_bf16 v[20:23], v[144:147], v[182:185], v[20:23]
	v_mfma_f32_16x16x32_bf16 v[20:23], v[148:151], v[186:189], v[20:23]
	v_mfma_f32_16x16x32_bf16 v[12:15], v[152:155], v[182:185], v[12:15]
	v_mfma_f32_16x16x32_bf16 v[12:15], v[156:159], v[186:189], v[12:15]
	v_mfma_f32_16x16x32_bf16 v[4:7], v[144:147], v[190:193], v[4:7]
	v_mfma_f32_16x16x32_bf16 v[4:7], v[148:151], v[200:203], v[4:7]
	v_mfma_f32_16x16x32_bf16 v[0:3], v[152:155], v[190:193], v[0:3]
	v_mfma_f32_16x16x32_bf16 v[0:3], v[156:159], v[200:203], v[0:3]
	s_barrier
	s_setprio 0
	s_add_i32 s80, s80, 2
	s_add_u32 s4, s4, 0x100
	s_addc_u32 s5, s5, 0
	s_add_u32 s15, s15, 0x100
	s_addc_u32 s72, s72, 0
	s_add_u32 s28, s28, 0x100
	s_addc_u32 s29, s29, 0
	s_cmpk_gt_u32 s80, 0x55
	s_cbranch_scc0 .LBB0_1425
	s_and_b64 vcc, exec, s[60:61]
	s_cbranch_vccz .LBB0_1428
	s_barrier

.LBB0_1579:
	s_cmp_eq_u32 s49, 4
	s_cselect_b32 s26, s14, s13
	s_cselect_b32 s27, s15, s21
	s_cselect_b32 s24, s16, s47
	s_cselect_b32 s25, s17, s48
	s_add_u32 s22, s26, 0x80
	s_addc_u32 s23, s27, 0
	s_add_i32 s65, 0, 0x10000
	s_add_i32 s69, 0, 0x14000
	v_add_u32_e32 v132, s65, v154
	v_add_u32_e32 v148, s69, v154
	ds_read_b128 v[112:115], v132
	ds_read_b128 v[120:123], v132 offset:1024
	ds_read_b128 v[128:131], v132 offset:2048
	ds_read_b128 v[132:135], v132 offset:3072
	ds_read_b128 v[144:147], v148
	ds_read_b128 v[156:159], v148 offset:1024
	ds_read_b128 v[160:163], v148 offset:2048
	ds_read_b128 v[164:167], v148 offset:3072
	s_add_u32 s56, s13, 0x15ff80
	s_addc_u32 s57, s21, 0
	s_add_i32 m0, s31, 0xc000
	ds_read_b128 v[168:171], v155
	ds_read_b128 v[172:175], v155 offset:1024
	ds_read_b128 v[176:179], v155 offset:2048
	ds_read_b128 v[180:183], v155 offset:3072
	ds_read_b128 v[184:187], v155 offset:4096
	ds_read_b128 v[188:191], v155 offset:5120
	ds_read_b128 v[192:195], v155 offset:6144
	ds_read_b128 v[200:203], v155 offset:7168
	s_nop 0
	global_load_lds_dwordx4 v151, s[56:57]
	s_add_i32 m0, s31, 0xe000
	s_nop 0
	global_load_lds_dwordx4 v150, s[56:57]
	s_nop 0
	s_nop 0
	s_nop 0
	s_nop 0
	s_nop 0
	s_nop 0
	s_nop 0
	s_nop 0
	s_nop 0
	s_nop 0
	s_nop 0
	s_nop 0
	s_nop 0
	s_waitcnt vmcnt(8)
	s_waitcnt lgkmcnt(0)
	s_setprio 1
	s_barrier
	v_mfma_f32_16x16x32_bf16 v[140:143], v[112:115], v[168:171], v[140:143]
	v_mfma_f32_16x16x32_bf16 v[140:143], v[120:123], v[172:175], v[140:143]
	v_mfma_f32_16x16x32_bf16 v[136:139], v[128:131], v[168:171], v[136:139]
	v_mfma_f32_16x16x32_bf16 v[136:139], v[132:135], v[172:175], v[136:139]
	v_mfma_f32_16x16x32_bf16 v[108:111], v[112:115], v[176:179], v[108:111]
	v_mfma_f32_16x16x32_bf16 v[108:111], v[120:123], v[180:183], v[108:111]
	v_mfma_f32_16x16x32_bf16 v[104:107], v[128:131], v[176:179], v[104:107]
	v_mfma_f32_16x16x32_bf16 v[104:107], v[132:135], v[180:183], v[104:107]
	v_mfma_f32_16x16x32_bf16 v[92:95], v[112:115], v[184:187], v[92:95]
	v_mfma_f32_16x16x32_bf16 v[92:95], v[120:123], v[188:191], v[92:95]
	v_mfma_f32_16x16x32_bf16 v[88:91], v[128:131], v[184:187], v[88:91]
	v_mfma_f32_16x16x32_bf16 v[88:91], v[132:135], v[188:191], v[88:91]
	v_mfma_f32_16x16x32_bf16 v[76:79], v[112:115], v[192:195], v[76:79]
	v_mfma_f32_16x16x32_bf16 v[76:79], v[120:123], v[200:203], v[76:79]
	v_mfma_f32_16x16x32_bf16 v[72:75], v[128:131], v[192:195], v[72:75]
	v_mfma_f32_16x16x32_bf16 v[72:75], v[132:135], v[200:203], v[72:75]
	v_mfma_f32_16x16x32_bf16 v[124:127], v[144:147], v[168:171], v[124:127]
	v_mfma_f32_16x16x32_bf16 v[124:127], v[156:159], v[172:175], v[124:127]
	v_mfma_f32_16x16x32_bf16 v[116:119], v[160:163], v[168:171], v[116:119]
	v_mfma_f32_16x16x32_bf16 v[116:119], v[164:167], v[172:175], v[116:119]
	v_mfma_f32_16x16x32_bf16 v[100:103], v[144:147], v[176:179], v[100:103]
	v_mfma_f32_16x16x32_bf16 v[100:103], v[156:159], v[180:183], v[100:103]
	v_mfma_f32_16x16x32_bf16 v[96:99], v[160:163], v[176:179], v[96:99]
	v_mfma_f32_16x16x32_bf16 v[96:99], v[164:167], v[180:183], v[96:99]
	v_mfma_f32_16x16x32_bf16 v[84:87], v[144:147], v[184:187], v[84:87]
	v_mfma_f32_16x16x32_bf16 v[84:87], v[156:159], v[188:191], v[84:87]
	v_mfma_f32_16x16x32_bf16 v[80:83], v[160:163], v[184:187], v[80:83]
	v_mfma_f32_16x16x32_bf16 v[80:83], v[164:167], v[188:191], v[80:83]
	v_mfma_f32_16x16x32_bf16 v[68:71], v[144:147], v[192:195], v[68:71]
	v_mfma_f32_16x16x32_bf16 v[68:71], v[156:159], v[200:203], v[68:71]
	v_mfma_f32_16x16x32_bf16 v[64:67], v[160:163], v[192:195], v[64:67]
	v_mfma_f32_16x16x32_bf16 v[64:67], v[164:167], v[200:203], v[64:67]
	s_barrier
	s_setprio 0
	s_add_i32 s65, s65, s97
	s_mov_b64 s[56:57], s[24:25]
	s_mov_b32 m0, s65
	ds_read_b128 v[168:171], v155 offset:16384
	ds_read_b128 v[172:175], v155 offset:17408
	ds_read_b128 v[176:179], v155 offset:18432
	ds_read_b128 v[180:183], v155 offset:19456
	ds_read_b128 v[184:187], v155 offset:20480
	ds_read_b128 v[188:191], v155 offset:21504
	ds_read_b128 v[192:195], v155 offset:22528
	ds_read_b128 v[200:203], v155 offset:23552
	s_nop 0
	global_load_lds_dwordx4 v152, s[56:57]
	s_add_i32 m0, s65, 0x2000
	s_nop 0
	global_load_lds_dwordx4 v153, s[56:57]
	s_add_u32 s56, s24, 0x160000
	s_addc_u32 s57, s25, 0
	s_add_i32 s65, s69, s97
	s_mov_b32 m0, s65
	s_nop 0
	global_load_lds_dwordx4 v152, s[56:57]
	s_add_i32 m0, s65, 0x2000
	s_nop 0
	global_load_lds_dwordx4 v153, s[56:57]
	s_mov_b64 s[56:57], s[26:27]
	s_mov_b32 m0, s31
	s_nop 0
	global_load_lds_dwordx4 v151, s[56:57]
	s_mov_b32 m0, s34
	s_nop 0
	global_load_lds_dwordx4 v150, s[56:57]
	s_nop 0
	s_nop 0
	s_nop 0
	s_nop 0
	s_nop 0
	s_nop 0
	s_nop 0
	s_nop 0
	s_nop 0
	s_waitcnt vmcnt(8)
	s_waitcnt lgkmcnt(0)
	s_setprio 1
	s_barrier
	v_mfma_f32_16x16x32_bf16 v[60:63], v[112:115], v[168:171], v[60:63]
	v_mfma_f32_16x16x32_bf16 v[60:63], v[120:123], v[172:175], v[60:63]
	v_mfma_f32_16x16x32_bf16 v[56:59], v[128:131], v[168:171], v[56:59]
	v_mfma_f32_16x16x32_bf16 v[56:59], v[132:135], v[172:175], v[56:59]
	v_mfma_f32_16x16x32_bf16 v[52:55], v[112:115], v[176:179], v[52:55]
	v_mfma_f32_16x16x32_bf16 v[52:55], v[120:123], v[180:183], v[52:55]
	v_mfma_f32_16x16x32_bf16 v[44:47], v[128:131], v[176:179], v[44:47]
	v_mfma_f32_16x16x32_bf16 v[44:47], v[132:135], v[180:183], v[44:47]
	v_mfma_f32_16x16x32_bf16 v[36:39], v[112:115], v[184:187], v[36:39]
	v_mfma_f32_16x16x32_bf16 v[36:39], v[120:123], v[188:191], v[36:39]
	v_mfma_f32_16x16x32_bf16 v[28:31], v[128:131], v[184:187], v[28:31]
	v_mfma_f32_16x16x32_bf16 v[28:31], v[132:135], v[188:191], v[28:31]
	v_mfma_f32_16x16x32_bf16 v[20:23], v[112:115], v[192:195], v[20:23]
	v_mfma_f32_16x16x32_bf16 v[20:23], v[120:123], v[200:203], v[20:23]
	v_mfma_f32_16x16x32_bf16 v[8:11], v[128:131], v[192:195], v[8:11]
	v_mfma_f32_16x16x32_bf16 v[8:11], v[132:135], v[200:203], v[8:11]
	v_mfma_f32_16x16x32_bf16 v[48:51], v[144:147], v[168:171], v[48:51]
	v_mfma_f32_16x16x32_bf16 v[48:51], v[156:159], v[172:175], v[48:51]
	v_mfma_f32_16x16x32_bf16 v[40:43], v[160:163], v[168:171], v[40:43]
	v_mfma_f32_16x16x32_bf16 v[40:43], v[164:167], v[172:175], v[40:43]
	v_mfma_f32_16x16x32_bf16 v[32:35], v[144:147], v[176:179], v[32:35]
	v_mfma_f32_16x16x32_bf16 v[32:35], v[156:159], v[180:183], v[32:35]
	v_mfma_f32_16x16x32_bf16 v[24:27], v[160:163], v[176:179], v[24:27]
	v_mfma_f32_16x16x32_bf16 v[24:27], v[164:167], v[180:183], v[24:27]
	v_mfma_f32_16x16x32_bf16 v[16:19], v[144:147], v[184:187], v[16:19]
	v_mfma_f32_16x16x32_bf16 v[16:19], v[156:159], v[188:191], v[16:19]
	v_mfma_f32_16x16x32_bf16 v[12:15], v[160:163], v[184:187], v[12:15]
	v_mfma_f32_16x16x32_bf16 v[12:15], v[164:167], v[188:191], v[12:15]
	v_mfma_f32_16x16x32_bf16 v[4:7], v[144:147], v[192:195], v[4:7]
	v_mfma_f32_16x16x32_bf16 v[4:7], v[156:159], v[200:203], v[4:7]
	v_mfma_f32_16x16x32_bf16 v[0:3], v[160:163], v[192:195], v[0:3]
	v_mfma_f32_16x16x32_bf16 v[0:3], v[164:167], v[200:203], v[0:3]
	s_barrier
	s_setprio 0
	s_add_i32 s56, 0, 0x18000
	s_add_i32 s57, 0, 0x1c000
	v_add_u32_e32 v132, s56, v154
	v_add_u32_e32 v148, s57, v154
	ds_read_b128 v[112:115], v132
	ds_read_b128 v[120:123], v132 offset:1024
	ds_read_b128 v[128:131], v132 offset:2048
	ds_read_b128 v[132:135], v132 offset:3072
	ds_read_b128 v[144:147], v148
	ds_read_b128 v[156:159], v148 offset:1024
	ds_read_b128 v[160:163], v148 offset:2048
	ds_read_b128 v[164:167], v148 offset:3072
	s_add_u32 s26, s26, 0x160000
	s_addc_u32 s27, s27, 0
	s_mov_b32 m0, s35
	ds_read_b128 v[168:171], v155 offset:32768
	ds_read_b128 v[172:175], v155 offset:33792
	ds_read_b128 v[176:179], v155 offset:34816
	ds_read_b128 v[180:183], v155 offset:35840
	ds_read_b128 v[184:187], v155 offset:36864
	ds_read_b128 v[188:191], v155 offset:37888
	ds_read_b128 v[192:195], v155 offset:38912
	ds_read_b128 v[200:203], v155 offset:39936
	s_nop 0
	global_load_lds_dwordx4 v151, s[26:27]
	s_mov_b32 m0, s36
	s_nop 0
	global_load_lds_dwordx4 v150, s[26:27]
	s_nop 0
	s_nop 0
	s_nop 0
	s_nop 0
	s_nop 0
	s_nop 0
	s_nop 0
	s_nop 0
	s_nop 0
	s_waitcnt vmcnt(8)
	s_waitcnt lgkmcnt(0)
	s_setprio 1
	s_barrier
	v_mfma_f32_16x16x32_bf16 v[140:143], v[112:115], v[168:171], v[140:143]
	v_mfma_f32_16x16x32_bf16 v[140:143], v[120:123], v[172:175], v[140:143]
	v_mfma_f32_16x16x32_bf16 v[136:139], v[128:131], v[168:171], v[136:139]
	v_mfma_f32_16x16x32_bf16 v[136:139], v[132:135], v[172:175], v[136:139]
	v_mfma_f32_16x16x32_bf16 v[108:111], v[112:115], v[176:179], v[108:111]
	v_mfma_f32_16x16x32_bf16 v[108:111], v[120:123], v[180:183], v[108:111]
	v_mfma_f32_16x16x32_bf16 v[104:107], v[128:131], v[176:179], v[104:107]
	v_mfma_f32_16x16x32_bf16 v[104:107], v[132:135], v[180:183], v[104:107]
	v_mfma_f32_16x16x32_bf16 v[92:95], v[112:115], v[184:187], v[92:95]
	v_mfma_f32_16x16x32_bf16 v[92:95], v[120:123], v[188:191], v[92:95]
	v_mfma_f32_16x16x32_bf16 v[88:91], v[128:131], v[184:187], v[88:91]
	v_mfma_f32_16x16x32_bf16 v[88:91], v[132:135], v[188:191], v[88:91]
	v_mfma_f32_16x16x32_bf16 v[76:79], v[112:115], v[192:195], v[76:79]
	v_mfma_f32_16x16x32_bf16 v[76:79], v[120:123], v[200:203], v[76:79]
	v_mfma_f32_16x16x32_bf16 v[72:75], v[128:131], v[192:195], v[72:75]
	v_mfma_f32_16x16x32_bf16 v[72:75], v[132:135], v[200:203], v[72:75]
	v_mfma_f32_16x16x32_bf16 v[124:127], v[144:147], v[168:171], v[124:127]
	v_mfma_f32_16x16x32_bf16 v[124:127], v[156:159], v[172:175], v[124:127]
	v_mfma_f32_16x16x32_bf16 v[116:119], v[160:163], v[168:171], v[116:119]
	v_mfma_f32_16x16x32_bf16 v[116:119], v[164:167], v[172:175], v[116:119]
	v_mfma_f32_16x16x32_bf16 v[100:103], v[144:147], v[176:179], v[100:103]
	v_mfma_f32_16x16x32_bf16 v[100:103], v[156:159], v[180:183], v[100:103]
	v_mfma_f32_16x16x32_bf16 v[96:99], v[160:163], v[176:179], v[96:99]
	v_mfma_f32_16x16x32_bf16 v[96:99], v[164:167], v[180:183], v[96:99]
	v_mfma_f32_16x16x32_bf16 v[84:87], v[144:147], v[184:187], v[84:87]
	v_mfma_f32_16x16x32_bf16 v[84:87], v[156:159], v[188:191], v[84:87]
	v_mfma_f32_16x16x32_bf16 v[80:83], v[160:163], v[184:187], v[80:83]
	v_mfma_f32_16x16x32_bf16 v[80:83], v[164:167], v[188:191], v[80:83]
	v_mfma_f32_16x16x32_bf16 v[68:71], v[144:147], v[192:195], v[68:71]
	v_mfma_f32_16x16x32_bf16 v[68:71], v[156:159], v[200:203], v[68:71]
	v_mfma_f32_16x16x32_bf16 v[64:67], v[160:163], v[192:195], v[64:67]
	v_mfma_f32_16x16x32_bf16 v[64:67], v[164:167], v[200:203], v[64:67]
	s_barrier
	s_setprio 0
	s_add_u32 s26, s24, 0x80
	s_addc_u32 s27, s25, 0
	s_add_i32 s56, s56, s97
	s_mov_b32 m0, s56
	ds_read_b128 v[168:171], v155 offset:49152
	ds_read_b128 v[172:175], v155 offset:50176
	ds_read_b128 v[176:179], v155 offset:51200
	ds_read_b128 v[180:183], v155 offset:52224
	ds_read_b128 v[184:187], v155 offset:53248
	ds_read_b128 v[188:191], v155 offset:54272
	ds_read_b128 v[192:195], v155 offset:55296
	ds_read_b128 v[200:203], v155 offset:56320
	s_nop 0
	global_load_lds_dwordx4 v152, s[26:27]
	s_add_i32 m0, s56, 0x2000
	s_add_u32 s24, s24, 0x160080
	s_addc_u32 s25, s25, 0
	global_load_lds_dwordx4 v153, s[26:27]
	s_add_i32 s26, s57, s97
	s_mov_b32 m0, s26
	s_nop 0
	global_load_lds_dwordx4 v152, s[24:25]
	s_add_i32 m0, s26, 0x2000
	s_nop 0
	global_load_lds_dwordx4 v153, s[24:25]
	s_mov_b32 m0, s37
	s_nop 0
	global_load_lds_dwordx4 v151, s[22:23]
	s_mov_b32 m0, s38
	s_nop 0
	global_load_lds_dwordx4 v150, s[22:23]
	s_nop 0
	s_nop 0
	s_nop 0
	s_nop 0
	s_nop 0
	s_nop 0
	s_nop 0
	s_nop 0
	s_nop 0
	s_waitcnt vmcnt(8)
	s_waitcnt lgkmcnt(0)
	s_setprio 1
	s_barrier
	v_mfma_f32_16x16x32_bf16 v[60:63], v[112:115], v[168:171], v[60:63]
	v_mfma_f32_16x16x32_bf16 v[60:63], v[120:123], v[172:175], v[60:63]
	v_mfma_f32_16x16x32_bf16 v[56:59], v[128:131], v[168:171], v[56:59]
	v_mfma_f32_16x16x32_bf16 v[56:59], v[132:135], v[172:175], v[56:59]
	v_mfma_f32_16x16x32_bf16 v[52:55], v[112:115], v[176:179], v[52:55]
	v_mfma_f32_16x16x32_bf16 v[52:55], v[120:123], v[180:183], v[52:55]
	v_mfma_f32_16x16x32_bf16 v[44:47], v[128:131], v[176:179], v[44:47]
	v_mfma_f32_16x16x32_bf16 v[44:47], v[132:135], v[180:183], v[44:47]
	v_mfma_f32_16x16x32_bf16 v[36:39], v[112:115], v[184:187], v[36:39]
	v_mfma_f32_16x16x32_bf16 v[36:39], v[120:123], v[188:191], v[36:39]
	v_mfma_f32_16x16x32_bf16 v[28:31], v[128:131], v[184:187], v[28:31]
	v_mfma_f32_16x16x32_bf16 v[28:31], v[132:135], v[188:191], v[28:31]
	v_mfma_f32_16x16x32_bf16 v[20:23], v[112:115], v[192:195], v[20:23]
	v_mfma_f32_16x16x32_bf16 v[20:23], v[120:123], v[200:203], v[20:23]
	v_mfma_f32_16x16x32_bf16 v[8:11], v[128:131], v[192:195], v[8:11]
	v_mfma_f32_16x16x32_bf16 v[8:11], v[132:135], v[200:203], v[8:11]
	v_mfma_f32_16x16x32_bf16 v[48:51], v[144:147], v[168:171], v[48:51]
	v_mfma_f32_16x16x32_bf16 v[48:51], v[156:159], v[172:175], v[48:51]
	v_mfma_f32_16x16x32_bf16 v[40:43], v[160:163], v[168:171], v[40:43]
	v_mfma_f32_16x16x32_bf16 v[40:43], v[164:167], v[172:175], v[40:43]
	v_mfma_f32_16x16x32_bf16 v[32:35], v[144:147], v[176:179], v[32:35]
	v_mfma_f32_16x16x32_bf16 v[32:35], v[156:159], v[180:183], v[32:35]
	v_mfma_f32_16x16x32_bf16 v[24:27], v[160:163], v[176:179], v[24:27]
	v_mfma_f32_16x16x32_bf16 v[24:27], v[164:167], v[180:183], v[24:27]
	v_mfma_f32_16x16x32_bf16 v[16:19], v[144:147], v[184:187], v[16:19]
	v_mfma_f32_16x16x32_bf16 v[16:19], v[156:159], v[188:191], v[16:19]
	v_mfma_f32_16x16x32_bf16 v[12:15], v[160:163], v[184:187], v[12:15]
	v_mfma_f32_16x16x32_bf16 v[12:15], v[164:167], v[188:191], v[12:15]
	v_mfma_f32_16x16x32_bf16 v[4:7], v[144:147], v[192:195], v[4:7]
	v_mfma_f32_16x16x32_bf16 v[4:7], v[156:159], v[200:203], v[4:7]
	v_mfma_f32_16x16x32_bf16 v[0:3], v[160:163], v[192:195], v[0:3]
	v_mfma_f32_16x16x32_bf16 v[0:3], v[164:167], v[200:203], v[0:3]
	s_barrier
	s_setprio 0
	s_add_i32 s49, s49, 2
	s_add_u32 s13, s13, 0x100
	s_addc_u32 s21, s21, 0
	s_add_u32 s47, s47, 0x100
	s_addc_u32 s48, s48, 0
	s_cmp_gt_u32 s49, 5
	s_cbranch_scc0 .LBB0_1579
	s_and_b64 vcc, exec, s[60:61]
	s_cbranch_vccz .LBB0_1582
	s_barrier
